# v49 + mid-step LDS-DMA (two k-steps in flight) in out and inproj2rest k-loops + merge step epilogues with all gate/partial-sum loads issued together
# speedup vs baseline: 1.0036x; 1.0036x over previous
.LBB0_86:
	s_add_i32 s35, s11, 1
	s_bitcmp1_b32 s35, 0
	s_cselect_b32 s37, 0x9000, 0
	v_add_u32_e32 v110, s37, v81
	v_lshl_add_u64 v[106:107], v[94:95], 0, s[12:13]
	s_mov_b64 s[38:39], 0x6181080
	v_readfirstlane_b32 s37, v110
	v_add_u32_e32 v111, 0x1000, v110
	v_lshl_add_u64 v[108:109], v[106:107], 0, s[38:39]
	s_mov_b32 m0, s37
	s_mov_b64 s[38:39], 0x61e5080
	v_readfirstlane_b32 s37, v111
	v_add_u32_e32 v111, 0x2000, v110
	global_load_lds_dwordx4 v[108:109], off
	v_lshl_add_u64 v[108:109], v[106:107], 0, s[38:39]
	s_mov_b32 m0, s37
	s_mov_b64 s[38:39], 0x6249080
	v_readfirstlane_b32 s37, v111
	v_add_u32_e32 v111, 0x3000, v110
	global_load_lds_dwordx4 v[108:109], off
	v_lshl_add_u64 v[108:109], v[106:107], 0, s[38:39]
	s_mov_b32 m0, s37
	s_mov_b64 s[38:39], 0x62ad080
	v_readfirstlane_b32 s37, v111
	global_load_lds_dwordx4 v[108:109], off
	v_lshl_add_u64 v[108:109], v[106:107], 0, s[38:39]
	s_mov_b32 m0, s37
	s_mov_b64 s[38:39], 0x6311080
	global_load_lds_dwordx4 v[108:109], off
	v_add_u32_e32 v108, 0x4000, v110
	v_lshl_add_u64 v[106:107], v[106:107], 0, s[38:39]
	v_readfirstlane_b32 s37, v108
	s_mov_b32 m0, s37
	v_add_u32_e32 v111, 0x5000, v110
	global_load_lds_dwordx4 v[106:107], off
	v_lshl_add_u64 v[106:107], v[100:101], 0, s[12:13]
	s_mov_b64 s[38:39], 0x14531080
	v_readfirstlane_b32 s37, v111
	v_add_u32_e32 v111, 0x6000, v110
	v_lshl_add_u64 v[108:109], v[106:107], 0, s[38:39]
	s_mov_b32 m0, s37
	s_mov_b64 s[38:39], 0x14541080
	v_readfirstlane_b32 s37, v111
	v_add_u32_e32 v111, 0x7000, v110
	global_load_lds_dwordx4 v[108:109], off
	v_lshl_add_u64 v[108:109], v[106:107], 0, s[38:39]
	s_mov_b32 m0, s37
	s_mov_b64 s[38:39], 0x14551080
	v_readfirstlane_b32 s37, v111
	global_load_lds_dwordx4 v[108:109], off
	v_lshl_add_u64 v[108:109], v[106:107], 0, s[38:39]
	s_mov_b32 m0, s37
	s_mov_b64 s[38:39], 0x14561080
	global_load_lds_dwordx4 v[108:109], off
	v_add_u32_e32 v108, 0x8000, v110
	v_lshl_add_u64 v[106:107], v[106:107], 0, s[38:39]
	v_readfirstlane_b32 s37, v108
	s_mov_b32 m0, s37
	s_bitcmp1_b32 s11, 0
	global_load_lds_dwordx4 v[106:107], off
	s_cselect_b32 s11, 0x9000, 0
	s_add_i32 s11, s11, 0
	v_add_u32_e32 v114, s11, v116
	v_add_u32_e32 v115, v114, v117
	ds_read_b128 v[106:109], v115
	ds_read_b128 v[110:113], v115 offset:2048
	ds_read_b128 v[122:125], v115 offset:4096
	ds_read_b128 v[156:159], v115 offset:6144
	v_add_u32_e32 v114, v114, v118
	ds_read_b128 v[166:169], v115 offset:8192
	ds_read_b128 v[178:181], v114 offset:20480
	ds_read_b128 v[182:185], v114 offset:22528
	ds_read_b128 v[186:189], v114 offset:24576
	ds_read_b128 v[190:193], v114 offset:26624
	v_add_u32_e32 v210, s11, v119
	v_add_u32_e32 v211, v210, v117
	ds_read_b128 v[212:215], v211
	ds_read_b128 v[216:219], v211 offset:2048
	ds_read_b128 v[220:223], v211 offset:4096
	ds_read_b128 v[224:227], v211 offset:6144
	v_add_u32_e32 v228, v210, v118
	ds_read_b128 v[230:233], v211 offset:8192
	ds_read_b128 v[234:237], v228 offset:20480
	ds_read_b128 v[238:241], v228 offset:22528
	ds_read_b128 v[242:245], v228 offset:24576
	ds_read_b128 v[246:249], v228 offset:26624
	s_setprio 1
	s_waitcnt lgkmcnt(9)
	v_mfma_f32_16x16x32_bf16 v[76:79], v[178:181], v[106:109], v[76:79]
	v_mfma_f32_16x16x32_bf16 v[72:75], v[182:185], v[106:109], v[72:75]
	v_mfma_f32_16x16x32_bf16 v[68:71], v[186:189], v[106:109], v[68:71]
	v_mfma_f32_16x16x32_bf16 v[64:67], v[190:193], v[106:109], v[64:67]
	v_mfma_f32_16x16x32_bf16 v[60:63], v[178:181], v[110:113], v[60:63]
	v_mfma_f32_16x16x32_bf16 v[56:59], v[182:185], v[110:113], v[56:59]
	v_mfma_f32_16x16x32_bf16 v[52:55], v[186:189], v[110:113], v[52:55]
	v_mfma_f32_16x16x32_bf16 v[48:51], v[190:193], v[110:113], v[48:51]
	v_mfma_f32_16x16x32_bf16 v[44:47], v[178:181], v[122:125], v[44:47]
	v_mfma_f32_16x16x32_bf16 v[40:43], v[182:185], v[122:125], v[40:43]
	v_mfma_f32_16x16x32_bf16 v[36:39], v[186:189], v[122:125], v[36:39]
	v_mfma_f32_16x16x32_bf16 v[32:35], v[190:193], v[122:125], v[32:35]
	v_mfma_f32_16x16x32_bf16 v[28:31], v[178:181], v[156:159], v[28:31]
	v_mfma_f32_16x16x32_bf16 v[24:27], v[182:185], v[156:159], v[24:27]
	v_mfma_f32_16x16x32_bf16 v[20:23], v[186:189], v[156:159], v[20:23]
	v_mfma_f32_16x16x32_bf16 v[16:19], v[190:193], v[156:159], v[16:19]
	v_mfma_f32_16x16x32_bf16 v[12:15], v[178:181], v[166:169], v[12:15]
	v_mfma_f32_16x16x32_bf16 v[8:11], v[182:185], v[166:169], v[8:11]
	v_mfma_f32_16x16x32_bf16 v[4:7], v[186:189], v[166:169], v[4:7]
	v_mfma_f32_16x16x32_bf16 v[0:3], v[190:193], v[166:169], v[0:3]
	s_setprio 0
	s_setprio 1
	s_waitcnt lgkmcnt(0)
	v_mfma_f32_16x16x32_bf16 v[76:79], v[234:237], v[212:215], v[76:79]
	v_mfma_f32_16x16x32_bf16 v[72:75], v[238:241], v[212:215], v[72:75]
	v_mfma_f32_16x16x32_bf16 v[68:71], v[242:245], v[212:215], v[68:71]
	v_mfma_f32_16x16x32_bf16 v[64:67], v[246:249], v[212:215], v[64:67]
	v_mfma_f32_16x16x32_bf16 v[60:63], v[234:237], v[216:219], v[60:63]
	v_mfma_f32_16x16x32_bf16 v[56:59], v[238:241], v[216:219], v[56:59]
	v_mfma_f32_16x16x32_bf16 v[52:55], v[242:245], v[216:219], v[52:55]
	v_mfma_f32_16x16x32_bf16 v[48:51], v[246:249], v[216:219], v[48:51]
	v_mfma_f32_16x16x32_bf16 v[44:47], v[234:237], v[220:223], v[44:47]
	v_mfma_f32_16x16x32_bf16 v[40:43], v[238:241], v[220:223], v[40:43]
	v_mfma_f32_16x16x32_bf16 v[36:39], v[242:245], v[220:223], v[36:39]
	v_mfma_f32_16x16x32_bf16 v[32:35], v[246:249], v[220:223], v[32:35]
	v_mfma_f32_16x16x32_bf16 v[28:31], v[234:237], v[224:227], v[28:31]
	v_mfma_f32_16x16x32_bf16 v[24:27], v[238:241], v[224:227], v[24:27]
	v_mfma_f32_16x16x32_bf16 v[20:23], v[242:245], v[224:227], v[20:23]
	v_mfma_f32_16x16x32_bf16 v[16:19], v[246:249], v[224:227], v[16:19]
	v_mfma_f32_16x16x32_bf16 v[12:15], v[234:237], v[230:233], v[12:15]
	v_mfma_f32_16x16x32_bf16 v[8:11], v[238:241], v[230:233], v[8:11]
	v_mfma_f32_16x16x32_bf16 v[4:7], v[242:245], v[230:233], v[4:7]
	v_mfma_f32_16x16x32_bf16 v[0:3], v[246:249], v[230:233], v[0:3]
	s_setprio 0
	s_waitcnt vmcnt(0)
	s_add_u32 s12, s12, 0x80
	s_addc_u32 s13, s13, 0
	s_cmpk_lg_i32 s12, 0x780
	s_mov_b32 s11, s35
	s_waitcnt vmcnt(0)
	s_barrier
	s_cbranch_scc1 .LBB0_86
	v_add_u32_e32 v122, v120, v118
	v_add_u32_e32 v123, v120, v117
	ds_read_b128 v[106:109], v122 offset:63488
	ds_read_b128 v[110:113], v122 offset:61440
	ds_read_b128 v[156:159], v122 offset:59392
	ds_read_b128 v[166:169], v122 offset:57344
	ds_read_b128 v[178:181], v123 offset:45056
	ds_read_b128 v[182:185], v123 offset:43008
	ds_read_b128 v[186:189], v123 offset:40960
	ds_read_b128 v[190:193], v123 offset:38912
	ds_read_b128 v[194:197], v123 offset:36864
	s_setprio 1
	s_waitcnt lgkmcnt(0)
	v_mfma_f32_16x16x32_bf16 v[76:79], v[166:169], v[194:197], v[76:79]
	v_mfma_f32_16x16x32_bf16 v[72:75], v[156:159], v[194:197], v[72:75]
	v_mfma_f32_16x16x32_bf16 v[68:71], v[110:113], v[194:197], v[68:71]
	v_mfma_f32_16x16x32_bf16 v[64:67], v[106:109], v[194:197], v[64:67]
	v_mfma_f32_16x16x32_bf16 v[60:63], v[166:169], v[190:193], v[60:63]
	v_mfma_f32_16x16x32_bf16 v[56:59], v[156:159], v[190:193], v[56:59]
	v_mfma_f32_16x16x32_bf16 v[52:55], v[110:113], v[190:193], v[52:55]
	v_mfma_f32_16x16x32_bf16 v[48:51], v[106:109], v[190:193], v[48:51]
	v_mfma_f32_16x16x32_bf16 v[44:47], v[166:169], v[186:189], v[44:47]
	v_mfma_f32_16x16x32_bf16 v[40:43], v[156:159], v[186:189], v[40:43]
	v_mfma_f32_16x16x32_bf16 v[36:39], v[110:113], v[186:189], v[36:39]
	v_mfma_f32_16x16x32_bf16 v[32:35], v[106:109], v[186:189], v[32:35]
	v_mfma_f32_16x16x32_bf16 v[28:31], v[166:169], v[182:185], v[28:31]
	v_mfma_f32_16x16x32_bf16 v[24:27], v[156:159], v[182:185], v[24:27]
	v_mfma_f32_16x16x32_bf16 v[20:23], v[110:113], v[182:185], v[20:23]
	v_mfma_f32_16x16x32_bf16 v[16:19], v[106:109], v[182:185], v[16:19]
	v_mfma_f32_16x16x32_bf16 v[12:15], v[166:169], v[178:181], v[12:15]
	v_mfma_f32_16x16x32_bf16 v[8:11], v[156:159], v[178:181], v[8:11]
	v_mfma_f32_16x16x32_bf16 v[4:7], v[110:113], v[178:181], v[4:7]
	v_mfma_f32_16x16x32_bf16 v[0:3], v[106:109], v[178:181], v[0:3]
	s_setprio 0
	v_add_u32_e32 v124, v121, v117
	ds_read_b128 v[106:109], v124 offset:36864
	ds_read_b128 v[110:113], v124 offset:38912
	ds_read_b128 v[156:159], v124 offset:40960
	ds_read_b128 v[166:169], v124 offset:43008
	v_add_u32_e32 v125, v121, v118
	ds_read_b128 v[178:181], v124 offset:45056
	ds_read_b128 v[182:185], v125 offset:57344
	ds_read_b128 v[186:189], v125 offset:59392
	ds_read_b128 v[190:193], v125 offset:61440
	ds_read_b128 v[194:197], v125 offset:63488
	s_setprio 1
	s_waitcnt lgkmcnt(1)
	v_mfma_f32_16x16x32_bf16 v[68:71], v[190:193], v[106:109], v[68:71]
	s_waitcnt lgkmcnt(0)
	v_mfma_f32_16x16x32_bf16 v[64:67], v[194:197], v[106:109], v[64:67]
	v_mfma_f32_16x16x32_bf16 v[60:63], v[182:185], v[110:113], v[60:63]
	v_mfma_f32_16x16x32_bf16 v[56:59], v[186:189], v[110:113], v[56:59]
	v_mfma_f32_16x16x32_bf16 v[52:55], v[190:193], v[110:113], v[52:55]
	v_mfma_f32_16x16x32_bf16 v[48:51], v[194:197], v[110:113], v[48:51]
	v_mfma_f32_16x16x32_bf16 v[44:47], v[182:185], v[156:159], v[44:47]
	v_mfma_f32_16x16x32_bf16 v[40:43], v[186:189], v[156:159], v[40:43]
	v_mfma_f32_16x16x32_bf16 v[36:39], v[190:193], v[156:159], v[36:39]
	v_mfma_f32_16x16x32_bf16 v[32:35], v[194:197], v[156:159], v[32:35]
	v_mfma_f32_16x16x32_bf16 v[28:31], v[182:185], v[166:169], v[28:31]
	v_mfma_f32_16x16x32_bf16 v[24:27], v[186:189], v[166:169], v[24:27]
	v_mfma_f32_16x16x32_bf16 v[20:23], v[190:193], v[166:169], v[20:23]
	v_mfma_f32_16x16x32_bf16 v[16:19], v[194:197], v[166:169], v[16:19]
	v_mfma_f32_16x16x32_bf16 v[12:15], v[182:185], v[178:181], v[12:15]
	v_mfma_f32_16x16x32_bf16 v[8:11], v[186:189], v[178:181], v[8:11]
	v_mfma_f32_16x16x32_bf16 v[4:7], v[190:193], v[178:181], v[4:7]
	v_mfma_f32_16x16x32_bf16 v[0:3], v[194:197], v[178:181], v[0:3]
	v_mfma_f32_16x16x32_bf16 v[198:201], v[182:185], v[106:109], v[76:79]
	v_mfma_f32_16x16x32_bf16 v[206:209], v[186:189], v[106:109], v[72:75]
	s_setprio 0
	s_nop 1
	v_mov_b32_e32 v72, v97
	s_waitcnt vmcnt(0)
	s_barrier
	s_mul_i32 s12, s36, 0xa0
	s_movk_i32 s11, 0x50
	s_mov_b32 s35, 0
	s_lshl_b32 s13, s10, 7
	s_movk_i32 s36, 0x3200
	s_mov_b64 s[38:39], 0x1800
	s_mov_b64 s[10:11], 0x800
	v_ashrrev_i32_e32 v220, 7, v176
	v_mov_b32_e32 v221, 0x50
	v_and_or_b32 v224, v176, 15, s12
	v_mad_u32_u24 v224, v220, v221, v224
	v_and_b32_e32 v220, 64, v176
	v_lshrrev_b32_e32 v221, 2, v176
	v_and_b32_e32 v221, 12, v221
	v_or3_b32 v225, v220, v221, s13
	v_mul_u32_u24_e32 v214, 0x3200, v224
	v_lshl_add_u32 v214, v225, 1, v214
	v_add_u32_e32 v214, 0x1800, v214
	v_lshlrev_b32_e32 v215, 12, v224
	v_lshl_add_u32 v215, v225, 2, v215
	v_mov_b32_e32 v223, 0
	v_mov_b32_e32 v222, v214
	v_lshl_add_u64 v[224:225], v[222:223], 0, s[0:1]
	global_load_dwordx2 v[72:73], v[224:225], off
	global_load_dwordx2 v[74:75], v[224:225], off offset:32
	global_load_dwordx2 v[76:77], v[224:225], off offset:64
	global_load_dwordx2 v[78:79], v[224:225], off offset:96
	v_add_u32_e32 v222, 0x32000, v214
	v_lshl_add_u64 v[224:225], v[222:223], 0, s[0:1]
	global_load_dwordx2 v[106:107], v[224:225], off
	global_load_dwordx2 v[108:109], v[224:225], off offset:32
	global_load_dwordx2 v[110:111], v[224:225], off offset:64
	global_load_dwordx2 v[112:113], v[224:225], off offset:96
	v_add_u32_e32 v222, 0x64000, v214
	v_lshl_add_u64 v[224:225], v[222:223], 0, s[0:1]
	global_load_dwordx2 v[114:115], v[224:225], off
	global_load_dwordx2 v[226:227], v[224:225], off offset:32
	global_load_dwordx2 v[246:247], v[224:225], off offset:64
	global_load_dwordx2 v[248:249], v[224:225], off offset:96
	v_add_u32_e32 v222, 0x96000, v214
	v_lshl_add_u64 v[224:225], v[222:223], 0, s[0:1]
	global_load_dwordx2 v[242:243], v[224:225], off
	global_load_dwordx2 v[244:245], v[224:225], off offset:32
	global_load_dwordx2 v[238:239], v[224:225], off offset:64
	global_load_dwordx2 v[240:241], v[224:225], off offset:96
	v_add_u32_e32 v222, 0xc8000, v214
	v_lshl_add_u64 v[224:225], v[222:223], 0, s[0:1]
	global_load_dwordx2 v[234:235], v[224:225], off
	global_load_dwordx2 v[236:237], v[224:225], off offset:32
	global_load_dwordx2 v[230:231], v[224:225], off offset:64
	global_load_dwordx2 v[232:233], v[224:225], off offset:96
	v_mov_b32_e32 v222, v215
	v_lshl_add_u64 v[218:219], v[222:223], 0, s[4:5]
	s_waitcnt vmcnt(19)
	v_lshlrev_b32_e32 v220, 16, v72
	v_and_b32_e32 v221, 0xffff0000, v72
	v_pk_mul_f32 v[198:199], v[198:199], v[220:221]
	v_lshlrev_b32_e32 v72, 16, v73
	v_and_b32_e32 v73, 0xffff0000, v73
	v_pk_mul_f32 v[200:201], v[200:201], v[72:73]
	s_nop 0
	global_store_dwordx4 v[218:219], v[198:201], off
	s_waitcnt vmcnt(19)
	v_lshlrev_b32_e32 v220, 16, v74
	v_and_b32_e32 v221, 0xffff0000, v74
	v_pk_mul_f32 v[206:207], v[206:207], v[220:221]
	v_lshlrev_b32_e32 v74, 16, v75
	v_and_b32_e32 v75, 0xffff0000, v75
	v_pk_mul_f32 v[208:209], v[208:209], v[74:75]
	s_nop 0
	global_store_dwordx4 v[218:219], v[206:209], off offset:64
	s_waitcnt vmcnt(19)
	v_lshlrev_b32_e32 v220, 16, v76
	v_and_b32_e32 v221, 0xffff0000, v76
	v_pk_mul_f32 v[68:69], v[68:69], v[220:221]
	v_lshlrev_b32_e32 v76, 16, v77
	v_and_b32_e32 v77, 0xffff0000, v77
	v_pk_mul_f32 v[70:71], v[70:71], v[76:77]
	s_nop 0
	global_store_dwordx4 v[218:219], v[68:71], off offset:128
	s_waitcnt vmcnt(19)
	v_lshlrev_b32_e32 v220, 16, v78
	v_and_b32_e32 v221, 0xffff0000, v78
	v_pk_mul_f32 v[64:65], v[64:65], v[220:221]
	v_lshlrev_b32_e32 v78, 16, v79
	v_and_b32_e32 v79, 0xffff0000, v79
	v_pk_mul_f32 v[66:67], v[66:67], v[78:79]
	s_nop 0
	global_store_dwordx4 v[218:219], v[64:67], off offset:192
	v_add_u32_e32 v222, 0x10000, v215
	v_lshl_add_u64 v[218:219], v[222:223], 0, s[4:5]
	s_waitcnt vmcnt(19)
	v_lshlrev_b32_e32 v220, 16, v106
	v_and_b32_e32 v221, 0xffff0000, v106
	v_pk_mul_f32 v[60:61], v[60:61], v[220:221]
	v_lshlrev_b32_e32 v106, 16, v107
	v_and_b32_e32 v107, 0xffff0000, v107
	v_pk_mul_f32 v[62:63], v[62:63], v[106:107]
	s_nop 0
	global_store_dwordx4 v[218:219], v[60:63], off
	s_waitcnt vmcnt(19)
	v_lshlrev_b32_e32 v220, 16, v108
	v_and_b32_e32 v221, 0xffff0000, v108
	v_pk_mul_f32 v[56:57], v[56:57], v[220:221]
	v_lshlrev_b32_e32 v108, 16, v109
	v_and_b32_e32 v109, 0xffff0000, v109
	v_pk_mul_f32 v[58:59], v[58:59], v[108:109]
	s_nop 0
	global_store_dwordx4 v[218:219], v[56:59], off offset:64
	s_waitcnt vmcnt(19)
	v_lshlrev_b32_e32 v220, 16, v110
	v_and_b32_e32 v221, 0xffff0000, v110
	v_pk_mul_f32 v[52:53], v[52:53], v[220:221]
	v_lshlrev_b32_e32 v110, 16, v111
	v_and_b32_e32 v111, 0xffff0000, v111
	v_pk_mul_f32 v[54:55], v[54:55], v[110:111]
	s_nop 0
	global_store_dwordx4 v[218:219], v[52:55], off offset:128
	s_waitcnt vmcnt(19)
	v_lshlrev_b32_e32 v220, 16, v112
	v_and_b32_e32 v221, 0xffff0000, v112
	v_pk_mul_f32 v[48:49], v[48:49], v[220:221]
	v_lshlrev_b32_e32 v112, 16, v113
	v_and_b32_e32 v113, 0xffff0000, v113
	v_pk_mul_f32 v[50:51], v[50:51], v[112:113]
	s_nop 0
	global_store_dwordx4 v[218:219], v[48:51], off offset:192
	v_add_u32_e32 v222, 0x20000, v215
	v_lshl_add_u64 v[218:219], v[222:223], 0, s[4:5]
	s_waitcnt vmcnt(19)
	v_lshlrev_b32_e32 v220, 16, v114
	v_and_b32_e32 v221, 0xffff0000, v114
	v_pk_mul_f32 v[44:45], v[44:45], v[220:221]
	v_lshlrev_b32_e32 v114, 16, v115
	v_and_b32_e32 v115, 0xffff0000, v115
	v_pk_mul_f32 v[46:47], v[46:47], v[114:115]
	s_nop 0
	global_store_dwordx4 v[218:219], v[44:47], off
	s_waitcnt vmcnt(19)
	v_lshlrev_b32_e32 v220, 16, v226
	v_and_b32_e32 v221, 0xffff0000, v226
	v_pk_mul_f32 v[40:41], v[40:41], v[220:221]
	v_lshlrev_b32_e32 v226, 16, v227
	v_and_b32_e32 v227, 0xffff0000, v227
	v_pk_mul_f32 v[42:43], v[42:43], v[226:227]
	s_nop 0
	global_store_dwordx4 v[218:219], v[40:43], off offset:64
	s_waitcnt vmcnt(19)
	v_lshlrev_b32_e32 v220, 16, v246
	v_and_b32_e32 v221, 0xffff0000, v246
	v_pk_mul_f32 v[36:37], v[36:37], v[220:221]
	v_lshlrev_b32_e32 v246, 16, v247
	v_and_b32_e32 v247, 0xffff0000, v247
	v_pk_mul_f32 v[38:39], v[38:39], v[246:247]
	s_nop 0
	global_store_dwordx4 v[218:219], v[36:39], off offset:128
	s_waitcnt vmcnt(19)
	v_lshlrev_b32_e32 v220, 16, v248
	v_and_b32_e32 v221, 0xffff0000, v248
	v_pk_mul_f32 v[32:33], v[32:33], v[220:221]
	v_lshlrev_b32_e32 v248, 16, v249
	v_and_b32_e32 v249, 0xffff0000, v249
	v_pk_mul_f32 v[34:35], v[34:35], v[248:249]
	s_nop 0
	global_store_dwordx4 v[218:219], v[32:35], off offset:192
	v_add_u32_e32 v222, 0x30000, v215
	v_lshl_add_u64 v[218:219], v[222:223], 0, s[4:5]
	s_waitcnt vmcnt(19)
	v_lshlrev_b32_e32 v220, 16, v242
	v_and_b32_e32 v221, 0xffff0000, v242
	v_pk_mul_f32 v[28:29], v[28:29], v[220:221]
	v_lshlrev_b32_e32 v242, 16, v243
	v_and_b32_e32 v243, 0xffff0000, v243
	v_pk_mul_f32 v[30:31], v[30:31], v[242:243]
	s_nop 0
	global_store_dwordx4 v[218:219], v[28:31], off
	s_waitcnt vmcnt(19)
	v_lshlrev_b32_e32 v220, 16, v244
	v_and_b32_e32 v221, 0xffff0000, v244
	v_pk_mul_f32 v[24:25], v[24:25], v[220:221]
	v_lshlrev_b32_e32 v244, 16, v245
	v_and_b32_e32 v245, 0xffff0000, v245
	v_pk_mul_f32 v[26:27], v[26:27], v[244:245]
	s_nop 0
	global_store_dwordx4 v[218:219], v[24:27], off offset:64
	s_waitcnt vmcnt(19)
	v_lshlrev_b32_e32 v220, 16, v238
	v_and_b32_e32 v221, 0xffff0000, v238
	v_pk_mul_f32 v[20:21], v[20:21], v[220:221]
	v_lshlrev_b32_e32 v238, 16, v239
	v_and_b32_e32 v239, 0xffff0000, v239
	v_pk_mul_f32 v[22:23], v[22:23], v[238:239]
	s_nop 0
	global_store_dwordx4 v[218:219], v[20:23], off offset:128
	s_waitcnt vmcnt(19)
	v_lshlrev_b32_e32 v220, 16, v240
	v_and_b32_e32 v221, 0xffff0000, v240
	v_pk_mul_f32 v[16:17], v[16:17], v[220:221]
	v_lshlrev_b32_e32 v240, 16, v241
	v_and_b32_e32 v241, 0xffff0000, v241
	v_pk_mul_f32 v[18:19], v[18:19], v[240:241]
	s_nop 0
	global_store_dwordx4 v[218:219], v[16:19], off offset:192
	v_add_u32_e32 v222, 0x40000, v215
	v_lshl_add_u64 v[218:219], v[222:223], 0, s[4:5]
	s_waitcnt vmcnt(19)
	v_lshlrev_b32_e32 v220, 16, v234
	v_and_b32_e32 v221, 0xffff0000, v234
	v_pk_mul_f32 v[12:13], v[12:13], v[220:221]
	v_lshlrev_b32_e32 v234, 16, v235
	v_and_b32_e32 v235, 0xffff0000, v235
	v_pk_mul_f32 v[14:15], v[14:15], v[234:235]
	s_nop 0
	global_store_dwordx4 v[218:219], v[12:15], off
	s_waitcnt vmcnt(19)
	v_lshlrev_b32_e32 v220, 16, v236
	v_and_b32_e32 v221, 0xffff0000, v236
	v_pk_mul_f32 v[8:9], v[8:9], v[220:221]
	v_lshlrev_b32_e32 v236, 16, v237
	v_and_b32_e32 v237, 0xffff0000, v237
	v_pk_mul_f32 v[10:11], v[10:11], v[236:237]
	s_nop 0
	global_store_dwordx4 v[218:219], v[8:11], off offset:64
	s_waitcnt vmcnt(19)
	v_lshlrev_b32_e32 v220, 16, v230
	v_and_b32_e32 v221, 0xffff0000, v230
	v_pk_mul_f32 v[4:5], v[4:5], v[220:221]
	v_lshlrev_b32_e32 v230, 16, v231
	v_and_b32_e32 v231, 0xffff0000, v231
	v_pk_mul_f32 v[6:7], v[6:7], v[230:231]
	s_nop 0
	global_store_dwordx4 v[218:219], v[4:7], off offset:128
	s_waitcnt vmcnt(19)
	v_lshlrev_b32_e32 v220, 16, v232
	v_and_b32_e32 v221, 0xffff0000, v232
	v_pk_mul_f32 v[0:1], v[0:1], v[220:221]
	v_lshlrev_b32_e32 v232, 16, v233
	v_and_b32_e32 v233, 0xffff0000, v233
	v_pk_mul_f32 v[2:3], v[2:3], v[232:233]
	s_nop 0
	global_store_dwordx4 v[218:219], v[0:3], off offset:192
	s_nop 1
	v_lshl_add_u64 v[0:1], v[104:105], 0, s[10:11]
	v_readfirstlane_b32 s10, v81
	s_mov_b32 m0, s10
	s_mov_b64 s[10:11], 0x64800
	global_load_lds_dwordx4 v[0:1], off
	v_lshl_add_u64 v[0:1], v[104:105], 0, s[10:11]
	v_readfirstlane_b32 s10, v133
	s_mov_b32 m0, s10
	s_mov_b64 s[10:11], 0xc8800
	global_load_lds_dwordx4 v[0:1], off
	v_lshl_add_u64 v[0:1], v[104:105], 0, s[10:11]
	v_readfirstlane_b32 s10, v132
	s_mov_b32 m0, s10
	s_mov_b64 s[10:11], 0x12c800
	global_load_lds_dwordx4 v[0:1], off
	v_lshl_add_u64 v[0:1], v[104:105], 0, s[10:11]
	v_readfirstlane_b32 s10, v131
	s_mov_b32 m0, s10
	s_mov_b64 s[10:11], 0x190800
	global_load_lds_dwordx4 v[0:1], off
	v_lshl_add_u64 v[0:1], v[104:105], 0, s[10:11]
	v_readfirstlane_b32 s10, v130
	s_mov_b32 m0, s10
	v_readfirstlane_b32 s10, v129
	global_load_lds_dwordx4 v[0:1], off
	v_lshl_add_u64 v[0:1], v[86:87], 0, s[8:9]
	s_mov_b32 m0, s10
	v_readfirstlane_b32 s10, v128
	global_load_lds_dwordx4 v[0:1], off
	v_lshl_add_u64 v[2:3], v[0:1], 0, s[40:41]
	s_mov_b32 m0, s10
	s_mov_b64 s[10:11], 0x20000
	global_load_lds_dwordx4 v[2:3], off
	v_lshl_add_u64 v[2:3], v[0:1], 0, s[10:11]
	v_readfirstlane_b32 s10, v127
	s_mov_b32 m0, s10
	s_mov_b64 s[10:11], 0x30000
	v_lshl_add_u64 v[0:1], v[0:1], 0, s[10:11]
	v_readfirstlane_b32 s10, v126
	global_load_lds_dwordx4 v[2:3], off
	s_mov_b32 m0, s10
	s_mov_b64 s[10:11], 0
	global_load_lds_dwordx4 v[0:1], off
	s_waitcnt vmcnt(0)
	v_mov_b32_e32 v0, 0
	v_mov_b32_e32 v1, v0
	v_mov_b32_e32 v2, v0
	v_mov_b32_e32 v3, v0
	v_mov_b32_e32 v4, v0
	v_mov_b32_e32 v5, v0
	v_mov_b32_e32 v6, v0
	v_mov_b32_e32 v7, v0
	v_mov_b32_e32 v8, v0
	v_mov_b32_e32 v9, v0
	v_mov_b32_e32 v10, v0
	v_mov_b32_e32 v11, v0
	v_mov_b32_e32 v12, v0
	v_mov_b32_e32 v13, v0
	v_mov_b32_e32 v14, v0
	v_mov_b32_e32 v15, v0
	v_mov_b32_e32 v16, v0
	v_mov_b32_e32 v17, v0
	v_mov_b32_e32 v18, v0
	v_mov_b32_e32 v19, v0
	v_mov_b32_e32 v20, v0
	v_mov_b32_e32 v21, v0
	v_mov_b32_e32 v22, v0
	v_mov_b32_e32 v23, v0
	v_mov_b32_e32 v24, v0
	v_mov_b32_e32 v25, v0
	v_mov_b32_e32 v26, v0
	v_mov_b32_e32 v27, v0
	v_mov_b32_e32 v28, v0
	v_mov_b32_e32 v29, v0
	v_mov_b32_e32 v30, v0
	v_mov_b32_e32 v31, v0
	v_mov_b32_e32 v32, v0
	v_mov_b32_e32 v33, v0
	v_mov_b32_e32 v34, v0
	v_mov_b32_e32 v35, v0
	v_mov_b32_e32 v36, v0
	v_mov_b32_e32 v37, v0
	v_mov_b32_e32 v38, v0
	v_mov_b32_e32 v39, v0
	v_mov_b32_e32 v40, v0
	v_mov_b32_e32 v41, v0
	v_mov_b32_e32 v42, v0
	v_mov_b32_e32 v43, v0
	v_mov_b32_e32 v44, v0
	v_mov_b32_e32 v45, v0
	v_mov_b32_e32 v46, v0
	v_mov_b32_e32 v47, v0
	v_mov_b32_e32 v48, v0
	v_mov_b32_e32 v49, v0
	v_mov_b32_e32 v50, v0
	v_mov_b32_e32 v51, v0
	v_mov_b32_e32 v52, v0
	v_mov_b32_e32 v53, v0
	v_mov_b32_e32 v54, v0
	v_mov_b32_e32 v55, v0
	v_mov_b32_e32 v56, v0
	v_mov_b32_e32 v57, v0
	v_mov_b32_e32 v58, v0
	v_mov_b32_e32 v59, v0
	v_mov_b32_e32 v60, v0
	v_mov_b32_e32 v61, v0
	v_mov_b32_e32 v62, v0
	v_mov_b32_e32 v63, v0
	v_mov_b32_e32 v64, v0
	v_mov_b32_e32 v65, v0
	v_mov_b32_e32 v66, v0
	v_mov_b32_e32 v67, v0
	v_mov_b32_e32 v68, v0
	v_mov_b32_e32 v69, v0
	v_mov_b32_e32 v70, v0
	v_mov_b32_e32 v71, v0
	v_mov_b32_e32 v72, v0
	v_mov_b32_e32 v73, v0
	v_mov_b32_e32 v74, v0
	v_mov_b32_e32 v75, v0
	v_mov_b32_e32 v76, v0
	v_mov_b32_e32 v77, v0
	v_mov_b32_e32 v78, v0
	v_mov_b32_e32 v79, v0
	s_waitcnt vmcnt(0) lgkmcnt(0)
	s_barrier
.LBB0_88:
	s_add_i32 s36, s35, 1
	s_bitcmp1_b32 s36, 0
	s_cselect_b32 s37, 0x9000, 0
	v_add_u32_e32 v108, s37, v81
	v_lshl_add_u64 v[104:105], v[94:95], 0, s[10:11]
	s_mov_b64 s[38:39], 0x6181880
	v_readfirstlane_b32 s37, v108
	v_add_u32_e32 v109, 0x1000, v108
	v_lshl_add_u64 v[106:107], v[104:105], 0, s[38:39]
	s_mov_b32 m0, s37
	s_mov_b64 s[38:39], 0x61e5880
	v_readfirstlane_b32 s37, v109
	v_add_u32_e32 v109, 0x2000, v108
	global_load_lds_dwordx4 v[106:107], off
	v_lshl_add_u64 v[106:107], v[104:105], 0, s[38:39]
	s_mov_b32 m0, s37
	s_mov_b64 s[38:39], 0x6249880
	v_readfirstlane_b32 s37, v109
	v_add_u32_e32 v109, 0x3000, v108
	global_load_lds_dwordx4 v[106:107], off
	v_lshl_add_u64 v[106:107], v[104:105], 0, s[38:39]
	s_mov_b32 m0, s37
	s_mov_b64 s[38:39], 0x62ad880
	v_readfirstlane_b32 s37, v109
	global_load_lds_dwordx4 v[106:107], off
	v_lshl_add_u64 v[106:107], v[104:105], 0, s[38:39]
	s_mov_b32 m0, s37
	s_mov_b64 s[38:39], 0x6311880
	global_load_lds_dwordx4 v[106:107], off
	v_add_u32_e32 v106, 0x4000, v108
	v_lshl_add_u64 v[104:105], v[104:105], 0, s[38:39]
	v_readfirstlane_b32 s37, v106
	s_mov_b32 m0, s37
	v_add_u32_e32 v109, 0x5000, v108
	global_load_lds_dwordx4 v[104:105], off
	v_lshl_add_u64 v[104:105], v[100:101], 0, s[10:11]
	s_mov_b64 s[38:39], 0x14731080
	v_readfirstlane_b32 s37, v109
	v_add_u32_e32 v109, 0x6000, v108
	v_lshl_add_u64 v[106:107], v[104:105], 0, s[38:39]
	s_mov_b32 m0, s37
	s_mov_b64 s[38:39], 0x14741080
	v_readfirstlane_b32 s37, v109
	v_add_u32_e32 v109, 0x7000, v108
	global_load_lds_dwordx4 v[106:107], off
	v_lshl_add_u64 v[106:107], v[104:105], 0, s[38:39]
	s_mov_b32 m0, s37
	s_mov_b64 s[38:39], 0x14751080
	v_readfirstlane_b32 s37, v109
	global_load_lds_dwordx4 v[106:107], off
	v_lshl_add_u64 v[106:107], v[104:105], 0, s[38:39]
	s_mov_b32 m0, s37
	s_mov_b64 s[38:39], 0x14761080
	global_load_lds_dwordx4 v[106:107], off
	v_add_u32_e32 v106, 0x8000, v108
	v_lshl_add_u64 v[104:105], v[104:105], 0, s[38:39]
	v_readfirstlane_b32 s37, v106
	s_mov_b32 m0, s37
	s_bitcmp1_b32 s35, 0
	global_load_lds_dwordx4 v[104:105], off
	s_cselect_b32 s35, 0x9000, 0
	s_add_i32 s35, s35, 0
	v_add_u32_e32 v166, s35, v116
	v_add_u32_e32 v167, v166, v117
	ds_read_b128 v[104:107], v167
	ds_read_b128 v[108:111], v167 offset:2048
	ds_read_b128 v[112:115], v167 offset:4096
	ds_read_b128 v[156:159], v167 offset:6144
	v_add_u32_e32 v177, v166, v118
	ds_read_b128 v[166:169], v167 offset:8192
	ds_read_b128 v[178:181], v177 offset:20480
	ds_read_b128 v[182:185], v177 offset:22528
	ds_read_b128 v[186:189], v177 offset:24576
	ds_read_b128 v[190:193], v177 offset:26624
	v_add_u32_e32 v210, s35, v119
	v_add_u32_e32 v211, v210, v117
	ds_read_b128 v[212:215], v211
	ds_read_b128 v[216:219], v211 offset:2048
	ds_read_b128 v[220:223], v211 offset:4096
	ds_read_b128 v[224:227], v211 offset:6144
	v_add_u32_e32 v228, v210, v118
	ds_read_b128 v[230:233], v211 offset:8192
	ds_read_b128 v[234:237], v228 offset:20480
	ds_read_b128 v[238:241], v228 offset:22528
	ds_read_b128 v[242:245], v228 offset:24576
	ds_read_b128 v[246:249], v228 offset:26624
	s_setprio 1
	s_waitcnt lgkmcnt(9)
	v_mfma_f32_16x16x32_bf16 v[76:79], v[178:181], v[104:107], v[76:79]
	v_mfma_f32_16x16x32_bf16 v[72:75], v[182:185], v[104:107], v[72:75]
	v_mfma_f32_16x16x32_bf16 v[68:71], v[186:189], v[104:107], v[68:71]
	v_mfma_f32_16x16x32_bf16 v[64:67], v[190:193], v[104:107], v[64:67]
	v_mfma_f32_16x16x32_bf16 v[60:63], v[178:181], v[108:111], v[60:63]
	v_mfma_f32_16x16x32_bf16 v[56:59], v[182:185], v[108:111], v[56:59]
	v_mfma_f32_16x16x32_bf16 v[52:55], v[186:189], v[108:111], v[52:55]
	v_mfma_f32_16x16x32_bf16 v[48:51], v[190:193], v[108:111], v[48:51]
	v_mfma_f32_16x16x32_bf16 v[44:47], v[178:181], v[112:115], v[44:47]
	v_mfma_f32_16x16x32_bf16 v[40:43], v[182:185], v[112:115], v[40:43]
	v_mfma_f32_16x16x32_bf16 v[36:39], v[186:189], v[112:115], v[36:39]
	v_mfma_f32_16x16x32_bf16 v[32:35], v[190:193], v[112:115], v[32:35]
	v_mfma_f32_16x16x32_bf16 v[28:31], v[178:181], v[156:159], v[28:31]
	v_mfma_f32_16x16x32_bf16 v[24:27], v[182:185], v[156:159], v[24:27]
	v_mfma_f32_16x16x32_bf16 v[20:23], v[186:189], v[156:159], v[20:23]
	v_mfma_f32_16x16x32_bf16 v[16:19], v[190:193], v[156:159], v[16:19]
	v_mfma_f32_16x16x32_bf16 v[12:15], v[178:181], v[166:169], v[12:15]
	v_mfma_f32_16x16x32_bf16 v[8:11], v[182:185], v[166:169], v[8:11]
	v_mfma_f32_16x16x32_bf16 v[4:7], v[186:189], v[166:169], v[4:7]
	v_mfma_f32_16x16x32_bf16 v[0:3], v[190:193], v[166:169], v[0:3]
	s_setprio 0
	s_setprio 1
	s_waitcnt lgkmcnt(0)
	v_mfma_f32_16x16x32_bf16 v[76:79], v[234:237], v[212:215], v[76:79]
	v_mfma_f32_16x16x32_bf16 v[72:75], v[238:241], v[212:215], v[72:75]
	v_mfma_f32_16x16x32_bf16 v[68:71], v[242:245], v[212:215], v[68:71]
	v_mfma_f32_16x16x32_bf16 v[64:67], v[246:249], v[212:215], v[64:67]
	v_mfma_f32_16x16x32_bf16 v[60:63], v[234:237], v[216:219], v[60:63]
	v_mfma_f32_16x16x32_bf16 v[56:59], v[238:241], v[216:219], v[56:59]
	v_mfma_f32_16x16x32_bf16 v[52:55], v[242:245], v[216:219], v[52:55]
	v_mfma_f32_16x16x32_bf16 v[48:51], v[246:249], v[216:219], v[48:51]
	v_mfma_f32_16x16x32_bf16 v[44:47], v[234:237], v[220:223], v[44:47]
	v_mfma_f32_16x16x32_bf16 v[40:43], v[238:241], v[220:223], v[40:43]
	v_mfma_f32_16x16x32_bf16 v[36:39], v[242:245], v[220:223], v[36:39]
	v_mfma_f32_16x16x32_bf16 v[32:35], v[246:249], v[220:223], v[32:35]
	v_mfma_f32_16x16x32_bf16 v[28:31], v[234:237], v[224:227], v[28:31]
	v_mfma_f32_16x16x32_bf16 v[24:27], v[238:241], v[224:227], v[24:27]
	v_mfma_f32_16x16x32_bf16 v[20:23], v[242:245], v[224:227], v[20:23]
	v_mfma_f32_16x16x32_bf16 v[16:19], v[246:249], v[224:227], v[16:19]
	v_mfma_f32_16x16x32_bf16 v[12:15], v[234:237], v[230:233], v[12:15]
	v_mfma_f32_16x16x32_bf16 v[8:11], v[238:241], v[230:233], v[8:11]
	v_mfma_f32_16x16x32_bf16 v[4:7], v[242:245], v[230:233], v[4:7]
	v_mfma_f32_16x16x32_bf16 v[0:3], v[246:249], v[230:233], v[0:3]
	s_setprio 0
	s_waitcnt vmcnt(0)
	s_add_u32 s10, s10, 0x80
	s_addc_u32 s11, s11, 0
	s_cmpk_lg_i32 s10, 0x780
	s_mov_b32 s35, s36
	s_waitcnt vmcnt(0)
	s_barrier
	s_cbranch_scc1 .LBB0_88
	ds_read_b128 v[104:107], v122 offset:63488
	ds_read_b128 v[108:111], v122 offset:61440
	ds_read_b128 v[112:115], v122 offset:59392
	ds_read_b128 v[156:159], v122 offset:57344
	ds_read_b128 v[166:169], v123 offset:45056
	ds_read_b128 v[178:181], v123 offset:43008
	ds_read_b128 v[182:185], v123 offset:40960
	ds_read_b128 v[186:189], v123 offset:38912
	ds_read_b128 v[190:193], v123 offset:36864
	s_setprio 1
	s_waitcnt lgkmcnt(0)
	v_mfma_f32_16x16x32_bf16 v[76:79], v[156:159], v[190:193], v[76:79]
	v_mfma_f32_16x16x32_bf16 v[72:75], v[112:115], v[190:193], v[72:75]
	v_mfma_f32_16x16x32_bf16 v[68:71], v[108:111], v[190:193], v[68:71]
	v_mfma_f32_16x16x32_bf16 v[64:67], v[104:107], v[190:193], v[64:67]
	v_mfma_f32_16x16x32_bf16 v[60:63], v[156:159], v[186:189], v[60:63]
	v_mfma_f32_16x16x32_bf16 v[56:59], v[112:115], v[186:189], v[56:59]
	v_mfma_f32_16x16x32_bf16 v[52:55], v[108:111], v[186:189], v[52:55]
	v_mfma_f32_16x16x32_bf16 v[48:51], v[104:107], v[186:189], v[48:51]
	v_mfma_f32_16x16x32_bf16 v[44:47], v[156:159], v[182:185], v[44:47]
	v_mfma_f32_16x16x32_bf16 v[40:43], v[112:115], v[182:185], v[40:43]
	v_mfma_f32_16x16x32_bf16 v[36:39], v[108:111], v[182:185], v[36:39]
	v_mfma_f32_16x16x32_bf16 v[32:35], v[104:107], v[182:185], v[32:35]
	v_mfma_f32_16x16x32_bf16 v[28:31], v[156:159], v[178:181], v[28:31]
	v_mfma_f32_16x16x32_bf16 v[24:27], v[112:115], v[178:181], v[24:27]
	v_mfma_f32_16x16x32_bf16 v[20:23], v[108:111], v[178:181], v[20:23]
	v_mfma_f32_16x16x32_bf16 v[16:19], v[104:107], v[178:181], v[16:19]
	v_mfma_f32_16x16x32_bf16 v[12:15], v[156:159], v[166:169], v[12:15]
	v_mfma_f32_16x16x32_bf16 v[8:11], v[112:115], v[166:169], v[8:11]
	v_mfma_f32_16x16x32_bf16 v[4:7], v[108:111], v[166:169], v[4:7]
	v_mfma_f32_16x16x32_bf16 v[0:3], v[104:107], v[166:169], v[0:3]
	s_setprio 0
	ds_read_b128 v[104:107], v124 offset:36864
	ds_read_b128 v[108:111], v124 offset:38912
	ds_read_b128 v[112:115], v124 offset:40960
	ds_read_b128 v[156:159], v124 offset:43008
	ds_read_b128 v[166:169], v124 offset:45056
	ds_read_b128 v[178:181], v125 offset:57344
	ds_read_b128 v[182:185], v125 offset:59392
	ds_read_b128 v[186:189], v125 offset:61440
	ds_read_b128 v[190:193], v125 offset:63488
	s_setprio 1
	s_waitcnt lgkmcnt(3)
	v_mfma_f32_16x16x32_bf16 v[76:79], v[178:181], v[104:107], v[76:79]
	s_waitcnt lgkmcnt(0)
	v_mfma_f32_16x16x32_bf16 v[64:67], v[190:193], v[104:107], v[64:67]
	v_mfma_f32_16x16x32_bf16 v[60:63], v[178:181], v[108:111], v[60:63]
	v_mfma_f32_16x16x32_bf16 v[56:59], v[182:185], v[108:111], v[56:59]
	v_mfma_f32_16x16x32_bf16 v[52:55], v[186:189], v[108:111], v[52:55]
	v_mfma_f32_16x16x32_bf16 v[48:51], v[190:193], v[108:111], v[48:51]
	v_mfma_f32_16x16x32_bf16 v[44:47], v[178:181], v[112:115], v[44:47]
	v_mfma_f32_16x16x32_bf16 v[40:43], v[182:185], v[112:115], v[40:43]
	v_mfma_f32_16x16x32_bf16 v[36:39], v[186:189], v[112:115], v[36:39]
	v_mfma_f32_16x16x32_bf16 v[32:35], v[190:193], v[112:115], v[32:35]
	v_mfma_f32_16x16x32_bf16 v[28:31], v[178:181], v[156:159], v[28:31]
	v_mfma_f32_16x16x32_bf16 v[24:27], v[182:185], v[156:159], v[24:27]
	v_mfma_f32_16x16x32_bf16 v[20:23], v[186:189], v[156:159], v[20:23]
	v_mfma_f32_16x16x32_bf16 v[16:19], v[190:193], v[156:159], v[16:19]
	v_mfma_f32_16x16x32_bf16 v[12:15], v[178:181], v[166:169], v[12:15]
	v_mfma_f32_16x16x32_bf16 v[8:11], v[182:185], v[166:169], v[8:11]
	v_mfma_f32_16x16x32_bf16 v[4:7], v[186:189], v[166:169], v[4:7]
	v_mfma_f32_16x16x32_bf16 v[0:3], v[190:193], v[166:169], v[0:3]
	v_mfma_f32_16x16x32_bf16 v[194:197], v[182:185], v[104:107], v[72:75]
	v_mfma_f32_16x16x32_bf16 v[198:201], v[186:189], v[104:107], v[68:71]
	s_setprio 0
	s_nop 1
	v_mov_b32_e32 v68, v97
	s_waitcnt vmcnt(0)
	s_barrier
	s_movk_i32 s11, 0x50
	s_mov_b32 s10, 0
	s_movk_i32 s11, 0x3200
	s_mov_b64 s[38:39], 0x2000
	s_mov_b64 s[36:37], 0x1000
	v_readfirstlane_b32 s11, v81
	s_mov_b32 m0, s11
	v_readfirstlane_b32 s11, v133
	v_ashrrev_i32_e32 v218, 7, v176
	v_mov_b32_e32 v219, 0x50
	v_and_or_b32 v222, v176, 15, s12
	v_mad_u32_u24 v222, v218, v219, v222
	v_and_b32_e32 v218, 64, v176
	v_lshrrev_b32_e32 v219, 2, v176
	v_and_b32_e32 v219, 12, v219
	v_or3_b32 v223, v218, v219, s13
	v_mul_u32_u24_e32 v204, 0x3200, v222
	v_lshl_add_u32 v204, v223, 1, v204
	v_add_u32_e32 v204, 0x2000, v204
	v_lshlrev_b32_e32 v228, 12, v222
	v_lshl_add_u32 v228, v223, 2, v228
	v_mov_b32_e32 v233, 0
	v_mov_b32_e32 v232, v204
	v_lshl_add_u64 v[222:223], v[232:233], 0, s[0:1]
	global_load_dwordx2 v[68:69], v[222:223], off
	global_load_dwordx2 v[70:71], v[222:223], off offset:32
	global_load_dwordx2 v[72:73], v[222:223], off offset:64
	global_load_dwordx2 v[74:75], v[222:223], off offset:96
	v_add_u32_e32 v232, 0x32000, v204
	v_lshl_add_u64 v[222:223], v[232:233], 0, s[0:1]
	global_load_dwordx2 v[106:107], v[222:223], off
	global_load_dwordx2 v[108:109], v[222:223], off offset:32
	global_load_dwordx2 v[110:111], v[222:223], off offset:64
	global_load_dwordx2 v[112:113], v[222:223], off offset:96
	v_add_u32_e32 v232, 0x64000, v204
	v_lshl_add_u64 v[222:223], v[232:233], 0, s[0:1]
	global_load_dwordx2 v[114:115], v[222:223], off
	global_load_dwordx2 v[202:203], v[222:223], off offset:32
	global_load_dwordx2 v[226:227], v[222:223], off offset:64
	global_load_dwordx2 v[246:247], v[222:223], off offset:96
	v_add_u32_e32 v232, 0x96000, v204
	v_lshl_add_u64 v[222:223], v[232:233], 0, s[0:1]
	global_load_dwordx2 v[248:249], v[222:223], off
	global_load_dwordx2 v[242:243], v[222:223], off offset:32
	global_load_dwordx2 v[244:245], v[222:223], off offset:64
	global_load_dwordx2 v[238:239], v[222:223], off offset:96
	v_add_u32_e32 v232, 0xc8000, v204
	v_lshl_add_u64 v[222:223], v[232:233], 0, s[0:1]
	global_load_dwordx2 v[240:241], v[222:223], off
	global_load_dwordx2 v[234:235], v[222:223], off offset:32
	global_load_dwordx2 v[236:237], v[222:223], off offset:64
	global_load_dwordx2 v[230:231], v[222:223], off offset:96
	v_mov_b32_e32 v232, v228
	v_lshl_add_u64 v[222:223], v[232:233], 0, s[4:5]
	global_load_dwordx4 v[156:159], v[222:223], off
	global_load_dwordx4 v[166:169], v[222:223], off offset:64
	global_load_dwordx4 v[178:181], v[222:223], off offset:128
	global_load_dwordx4 v[182:185], v[222:223], off offset:192
	v_add_u32_e32 v232, 0x10000, v228
	v_lshl_add_u64 v[222:223], v[232:233], 0, s[4:5]
	global_load_dwordx4 v[186:189], v[222:223], off
	global_load_dwordx4 v[190:193], v[222:223], off offset:64
	global_load_dwordx4 v[210:213], v[222:223], off offset:128
	global_load_dwordx4 v[214:217], v[222:223], off offset:192
	v_mov_b32_e32 v232, v228
	v_lshl_add_u64 v[224:225], v[232:233], 0, s[4:5]
	s_waitcnt vmcnt(7)
	v_lshlrev_b32_e32 v218, 16, v68
	v_and_b32_e32 v219, 0xffff0000, v68
	v_pk_fma_f32 v[76:77], v[76:77], v[218:219], v[156:157]
	v_lshlrev_b32_e32 v68, 16, v69
	v_and_b32_e32 v69, 0xffff0000, v69
	v_pk_fma_f32 v[78:79], v[78:79], v[68:69], v[158:159]
	s_nop 0
	global_store_dwordx4 v[224:225], v[76:79], off
	s_waitcnt vmcnt(7)
	v_lshlrev_b32_e32 v218, 16, v70
	v_and_b32_e32 v219, 0xffff0000, v70
	v_pk_fma_f32 v[194:195], v[194:195], v[218:219], v[166:167]
	v_lshlrev_b32_e32 v70, 16, v71
	v_and_b32_e32 v71, 0xffff0000, v71
	v_pk_fma_f32 v[196:197], v[196:197], v[70:71], v[168:169]
	s_nop 0
	global_store_dwordx4 v[224:225], v[194:197], off offset:64
	s_waitcnt vmcnt(7)
	v_lshlrev_b32_e32 v218, 16, v72
	v_and_b32_e32 v219, 0xffff0000, v72
	v_pk_fma_f32 v[198:199], v[198:199], v[218:219], v[178:179]
	v_lshlrev_b32_e32 v72, 16, v73
	v_and_b32_e32 v73, 0xffff0000, v73
	v_pk_fma_f32 v[200:201], v[200:201], v[72:73], v[180:181]
	s_nop 0
	global_store_dwordx4 v[224:225], v[198:201], off offset:128
	s_waitcnt vmcnt(7)
	v_lshlrev_b32_e32 v218, 16, v74
	v_and_b32_e32 v219, 0xffff0000, v74
	v_pk_fma_f32 v[64:65], v[64:65], v[218:219], v[182:183]
	v_lshlrev_b32_e32 v74, 16, v75
	v_and_b32_e32 v75, 0xffff0000, v75
	v_pk_fma_f32 v[66:67], v[66:67], v[74:75], v[184:185]
	s_nop 0
	global_store_dwordx4 v[224:225], v[64:67], off offset:192
	v_add_u32_e32 v232, 0x20000, v228
	v_lshl_add_u64 v[222:223], v[232:233], 0, s[4:5]
	global_load_dwordx4 v[156:159], v[222:223], off
	global_load_dwordx4 v[166:169], v[222:223], off offset:64
	global_load_dwordx4 v[178:181], v[222:223], off offset:128
	global_load_dwordx4 v[182:185], v[222:223], off offset:192
	v_add_u32_e32 v232, 0x10000, v228
	v_lshl_add_u64 v[224:225], v[232:233], 0, s[4:5]
	s_waitcnt vmcnt(11)
	v_lshlrev_b32_e32 v218, 16, v106
	v_and_b32_e32 v219, 0xffff0000, v106
	v_pk_fma_f32 v[60:61], v[60:61], v[218:219], v[186:187]
	v_lshlrev_b32_e32 v106, 16, v107
	v_and_b32_e32 v107, 0xffff0000, v107
	v_pk_fma_f32 v[62:63], v[62:63], v[106:107], v[188:189]
	s_nop 0
	global_store_dwordx4 v[224:225], v[60:63], off
	s_waitcnt vmcnt(11)
	v_lshlrev_b32_e32 v218, 16, v108
	v_and_b32_e32 v219, 0xffff0000, v108
	v_pk_fma_f32 v[56:57], v[56:57], v[218:219], v[190:191]
	v_lshlrev_b32_e32 v108, 16, v109
	v_and_b32_e32 v109, 0xffff0000, v109
	v_pk_fma_f32 v[58:59], v[58:59], v[108:109], v[192:193]
	s_nop 0
	global_store_dwordx4 v[224:225], v[56:59], off offset:64
	s_waitcnt vmcnt(11)
	v_lshlrev_b32_e32 v218, 16, v110
	v_and_b32_e32 v219, 0xffff0000, v110
	v_pk_fma_f32 v[52:53], v[52:53], v[218:219], v[210:211]
	v_lshlrev_b32_e32 v110, 16, v111
	v_and_b32_e32 v111, 0xffff0000, v111
	v_pk_fma_f32 v[54:55], v[54:55], v[110:111], v[212:213]
	s_nop 0
	global_store_dwordx4 v[224:225], v[52:55], off offset:128
	s_waitcnt vmcnt(11)
	v_lshlrev_b32_e32 v218, 16, v112
	v_and_b32_e32 v219, 0xffff0000, v112
	v_pk_fma_f32 v[48:49], v[48:49], v[218:219], v[214:215]
	v_lshlrev_b32_e32 v112, 16, v113
	v_and_b32_e32 v113, 0xffff0000, v113
	v_pk_fma_f32 v[50:51], v[50:51], v[112:113], v[216:217]
	s_nop 0
	global_store_dwordx4 v[224:225], v[48:51], off offset:192
	v_add_u32_e32 v232, 0x30000, v228
	v_lshl_add_u64 v[222:223], v[232:233], 0, s[4:5]
	global_load_dwordx4 v[186:189], v[222:223], off
	global_load_dwordx4 v[190:193], v[222:223], off offset:64
	global_load_dwordx4 v[210:213], v[222:223], off offset:128
	global_load_dwordx4 v[214:217], v[222:223], off offset:192
	v_add_u32_e32 v232, 0x40000, v228
	v_lshl_add_u64 v[222:223], v[232:233], 0, s[4:5]
	global_load_dwordx4 v[68:71], v[222:223], off
	global_load_dwordx4 v[72:75], v[222:223], off offset:64
	global_load_dwordx4 v[106:109], v[222:223], off offset:128
	global_load_dwordx4 v[110:113], v[222:223], off offset:192
	v_add_u32_e32 v232, 0x20000, v228
	v_lshl_add_u64 v[224:225], v[232:233], 0, s[4:5]
	s_waitcnt vmcnt(15)
	v_lshlrev_b32_e32 v218, 16, v114
	v_and_b32_e32 v219, 0xffff0000, v114
	v_pk_fma_f32 v[44:45], v[44:45], v[218:219], v[156:157]
	v_lshlrev_b32_e32 v114, 16, v115
	v_and_b32_e32 v115, 0xffff0000, v115
	v_pk_fma_f32 v[46:47], v[46:47], v[114:115], v[158:159]
	s_nop 0
	global_store_dwordx4 v[224:225], v[44:47], off
	s_waitcnt vmcnt(15)
	v_lshlrev_b32_e32 v218, 16, v202
	v_and_b32_e32 v219, 0xffff0000, v202
	v_pk_fma_f32 v[40:41], v[40:41], v[218:219], v[166:167]
	v_lshlrev_b32_e32 v202, 16, v203
	v_and_b32_e32 v203, 0xffff0000, v203
	v_pk_fma_f32 v[42:43], v[42:43], v[202:203], v[168:169]
	s_nop 0
	global_store_dwordx4 v[224:225], v[40:43], off offset:64
	s_waitcnt vmcnt(15)
	v_lshlrev_b32_e32 v218, 16, v226
	v_and_b32_e32 v219, 0xffff0000, v226
	v_pk_fma_f32 v[36:37], v[36:37], v[218:219], v[178:179]
	v_lshlrev_b32_e32 v226, 16, v227
	v_and_b32_e32 v227, 0xffff0000, v227
	v_pk_fma_f32 v[38:39], v[38:39], v[226:227], v[180:181]
	s_nop 0
	global_store_dwordx4 v[224:225], v[36:39], off offset:128
	s_waitcnt vmcnt(15)
	v_lshlrev_b32_e32 v218, 16, v246
	v_and_b32_e32 v219, 0xffff0000, v246
	v_pk_fma_f32 v[32:33], v[32:33], v[218:219], v[182:183]
	v_lshlrev_b32_e32 v246, 16, v247
	v_and_b32_e32 v247, 0xffff0000, v247
	v_pk_fma_f32 v[34:35], v[34:35], v[246:247], v[184:185]
	s_nop 0
	global_store_dwordx4 v[224:225], v[32:35], off offset:192
	v_add_u32_e32 v232, 0x30000, v228
	v_lshl_add_u64 v[224:225], v[232:233], 0, s[4:5]
	s_waitcnt vmcnt(11)
	v_lshlrev_b32_e32 v218, 16, v248
	v_and_b32_e32 v219, 0xffff0000, v248
	v_pk_fma_f32 v[28:29], v[28:29], v[218:219], v[186:187]
	v_lshlrev_b32_e32 v248, 16, v249
	v_and_b32_e32 v249, 0xffff0000, v249
	v_pk_fma_f32 v[30:31], v[30:31], v[248:249], v[188:189]
	s_nop 0
	global_store_dwordx4 v[224:225], v[28:31], off
	s_waitcnt vmcnt(11)
	v_lshlrev_b32_e32 v218, 16, v242
	v_and_b32_e32 v219, 0xffff0000, v242
	v_pk_fma_f32 v[24:25], v[24:25], v[218:219], v[190:191]
	v_lshlrev_b32_e32 v242, 16, v243
	v_and_b32_e32 v243, 0xffff0000, v243
	v_pk_fma_f32 v[26:27], v[26:27], v[242:243], v[192:193]
	s_nop 0
	global_store_dwordx4 v[224:225], v[24:27], off offset:64
	s_waitcnt vmcnt(11)
	v_lshlrev_b32_e32 v218, 16, v244
	v_and_b32_e32 v219, 0xffff0000, v244
	v_pk_fma_f32 v[20:21], v[20:21], v[218:219], v[210:211]
	v_lshlrev_b32_e32 v244, 16, v245
	v_and_b32_e32 v245, 0xffff0000, v245
	v_pk_fma_f32 v[22:23], v[22:23], v[244:245], v[212:213]
	s_nop 0
	global_store_dwordx4 v[224:225], v[20:23], off offset:128
	s_waitcnt vmcnt(11)
	v_lshlrev_b32_e32 v218, 16, v238
	v_and_b32_e32 v219, 0xffff0000, v238
	v_pk_fma_f32 v[16:17], v[16:17], v[218:219], v[214:215]
	v_lshlrev_b32_e32 v238, 16, v239
	v_and_b32_e32 v239, 0xffff0000, v239
	v_pk_fma_f32 v[18:19], v[18:19], v[238:239], v[216:217]
	s_nop 0
	global_store_dwordx4 v[224:225], v[16:19], off offset:192
	v_add_u32_e32 v232, 0x40000, v228
	v_lshl_add_u64 v[224:225], v[232:233], 0, s[4:5]
	s_waitcnt vmcnt(11)
	v_lshlrev_b32_e32 v218, 16, v240
	v_and_b32_e32 v219, 0xffff0000, v240
	v_pk_fma_f32 v[12:13], v[12:13], v[218:219], v[68:69]
	v_lshlrev_b32_e32 v240, 16, v241
	v_and_b32_e32 v241, 0xffff0000, v241
	v_pk_fma_f32 v[14:15], v[14:15], v[240:241], v[70:71]
	s_nop 0
	global_store_dwordx4 v[224:225], v[12:15], off
	s_waitcnt vmcnt(11)
	v_lshlrev_b32_e32 v218, 16, v234
	v_and_b32_e32 v219, 0xffff0000, v234
	v_pk_fma_f32 v[8:9], v[8:9], v[218:219], v[72:73]
	v_lshlrev_b32_e32 v234, 16, v235
	v_and_b32_e32 v235, 0xffff0000, v235
	v_pk_fma_f32 v[10:11], v[10:11], v[234:235], v[74:75]
	s_nop 0
	global_store_dwordx4 v[224:225], v[8:11], off offset:64
	s_waitcnt vmcnt(11)
	v_lshlrev_b32_e32 v218, 16, v236
	v_and_b32_e32 v219, 0xffff0000, v236
	v_pk_fma_f32 v[4:5], v[4:5], v[218:219], v[106:107]
	v_lshlrev_b32_e32 v236, 16, v237
	v_and_b32_e32 v237, 0xffff0000, v237
	v_pk_fma_f32 v[6:7], v[6:7], v[236:237], v[108:109]
	s_nop 0
	global_store_dwordx4 v[224:225], v[4:7], off offset:128
	s_waitcnt vmcnt(11)
	v_lshlrev_b32_e32 v218, 16, v230
	v_and_b32_e32 v219, 0xffff0000, v230
	v_pk_fma_f32 v[0:1], v[0:1], v[218:219], v[110:111]
	v_lshlrev_b32_e32 v230, 16, v231
	v_and_b32_e32 v231, 0xffff0000, v231
	v_pk_fma_f32 v[2:3], v[2:3], v[230:231], v[112:113]
	s_nop 0
	global_store_dwordx4 v[224:225], v[0:3], off offset:192
	s_nop 1
	v_lshl_add_u64 v[0:1], v[102:103], 0, v[96:97]
	v_lshl_add_u64 v[2:3], v[0:1], 0, s[36:37]
	s_mov_b64 s[36:37], 0x65000
	global_load_lds_dwordx4 v[2:3], off
	v_lshl_add_u64 v[2:3], v[0:1], 0, s[36:37]
	s_mov_b32 m0, s11
	s_mov_b64 s[36:37], 0xc9000
	v_readfirstlane_b32 s11, v132
	global_load_lds_dwordx4 v[2:3], off
	v_lshl_add_u64 v[2:3], v[0:1], 0, s[36:37]
	s_mov_b32 m0, s11
	s_mov_b64 s[36:37], 0x12d000
	v_readfirstlane_b32 s11, v131
	global_load_lds_dwordx4 v[2:3], off
	v_lshl_add_u64 v[2:3], v[0:1], 0, s[36:37]
	s_mov_b32 m0, s11
	s_mov_b64 s[36:37], 0x191000
	v_readfirstlane_b32 s11, v130
	global_load_lds_dwordx4 v[2:3], off
	v_lshl_add_u64 v[0:1], v[0:1], 0, s[36:37]
	s_mov_b32 m0, s11
	s_nop 0
	global_load_lds_dwordx4 v[0:1], off
	v_lshl_add_u64 v[0:1], v[88:89], 0, s[8:9]
	v_readfirstlane_b32 s8, v129
	s_mov_b32 m0, s8
	v_readfirstlane_b32 s8, v128
	global_load_lds_dwordx4 v[0:1], off
	v_lshl_add_u64 v[2:3], v[0:1], 0, s[40:41]
	s_mov_b32 m0, s8
	s_mov_b64 s[8:9], 0x20000
	global_load_lds_dwordx4 v[2:3], off
	v_lshl_add_u64 v[2:3], v[0:1], 0, s[8:9]
	v_readfirstlane_b32 s8, v127
	s_mov_b32 m0, s8
	s_mov_b64 s[8:9], 0x30000
	v_lshl_add_u64 v[0:1], v[0:1], 0, s[8:9]
	v_readfirstlane_b32 s8, v126
	global_load_lds_dwordx4 v[2:3], off
	s_mov_b32 m0, s8
	s_mov_b64 s[8:9], 0
	global_load_lds_dwordx4 v[0:1], off
	s_waitcnt vmcnt(0)
	v_mov_b32_e32 v0, 0
	v_mov_b32_e32 v1, v0
	v_mov_b32_e32 v2, v0
	v_mov_b32_e32 v3, v0
	v_mov_b32_e32 v4, v0
	v_mov_b32_e32 v5, v0
	v_mov_b32_e32 v6, v0
	v_mov_b32_e32 v7, v0
	v_mov_b32_e32 v8, v0
	v_mov_b32_e32 v9, v0
	v_mov_b32_e32 v10, v0
	v_mov_b32_e32 v11, v0
	v_mov_b32_e32 v12, v0
	v_mov_b32_e32 v13, v0
	v_mov_b32_e32 v14, v0
	v_mov_b32_e32 v15, v0
	v_mov_b32_e32 v16, v0
	v_mov_b32_e32 v17, v0
	v_mov_b32_e32 v18, v0
	v_mov_b32_e32 v19, v0
	v_mov_b32_e32 v20, v0
	v_mov_b32_e32 v21, v0
	v_mov_b32_e32 v22, v0
	v_mov_b32_e32 v23, v0
	v_mov_b32_e32 v24, v0
	v_mov_b32_e32 v25, v0
	v_mov_b32_e32 v26, v0
	v_mov_b32_e32 v27, v0
	v_mov_b32_e32 v28, v0
	v_mov_b32_e32 v29, v0
	v_mov_b32_e32 v30, v0
	v_mov_b32_e32 v31, v0
	v_mov_b32_e32 v32, v0
	v_mov_b32_e32 v33, v0
	v_mov_b32_e32 v34, v0
	v_mov_b32_e32 v35, v0
	v_mov_b32_e32 v36, v0
	v_mov_b32_e32 v37, v0
	v_mov_b32_e32 v38, v0
	v_mov_b32_e32 v39, v0
	v_mov_b32_e32 v40, v0
	v_mov_b32_e32 v41, v0
	v_mov_b32_e32 v42, v0
	v_mov_b32_e32 v43, v0
	v_mov_b32_e32 v44, v0
	v_mov_b32_e32 v45, v0
	v_mov_b32_e32 v46, v0
	v_mov_b32_e32 v47, v0
	v_mov_b32_e32 v48, v0
	v_mov_b32_e32 v49, v0
	v_mov_b32_e32 v50, v0
	v_mov_b32_e32 v51, v0
	v_mov_b32_e32 v52, v0
	v_mov_b32_e32 v53, v0
	v_mov_b32_e32 v54, v0
	v_mov_b32_e32 v55, v0
	v_mov_b32_e32 v56, v0
	v_mov_b32_e32 v57, v0
	v_mov_b32_e32 v58, v0
	v_mov_b32_e32 v59, v0
	v_mov_b32_e32 v60, v0
	v_mov_b32_e32 v61, v0
	v_mov_b32_e32 v62, v0
	v_mov_b32_e32 v63, v0
	v_mov_b32_e32 v64, v0
	v_mov_b32_e32 v65, v0
	v_mov_b32_e32 v66, v0
	v_mov_b32_e32 v67, v0
	v_mov_b32_e32 v68, v0
	v_mov_b32_e32 v69, v0
	v_mov_b32_e32 v70, v0
	v_mov_b32_e32 v71, v0
	v_mov_b32_e32 v72, v0
	v_mov_b32_e32 v73, v0
	v_mov_b32_e32 v74, v0
	v_mov_b32_e32 v75, v0
	v_mov_b32_e32 v76, v0
	v_mov_b32_e32 v77, v0
	v_mov_b32_e32 v78, v0
	v_mov_b32_e32 v79, v0
	s_waitcnt vmcnt(0) lgkmcnt(0)
	s_barrier
.LBB0_90:
	s_add_i32 s11, s10, 1
	s_bitcmp1_b32 s11, 0
	s_cselect_b32 s35, 0x9000, 0
	v_add_u32_e32 v96, s35, v81
	v_lshl_add_u64 v[102:103], v[94:95], 0, s[8:9]
	s_mov_b64 s[36:37], 0x6182080
	v_readfirstlane_b32 s35, v96
	v_add_u32_e32 v106, 0x1000, v96
	v_lshl_add_u64 v[104:105], v[102:103], 0, s[36:37]
	s_mov_b32 m0, s35
	s_mov_b64 s[36:37], 0x61e6080
	v_readfirstlane_b32 s35, v106
	v_add_u32_e32 v106, 0x2000, v96
	global_load_lds_dwordx4 v[104:105], off
	v_lshl_add_u64 v[104:105], v[102:103], 0, s[36:37]
	s_mov_b32 m0, s35
	s_mov_b64 s[36:37], 0x624a080
	v_readfirstlane_b32 s35, v106
	v_add_u32_e32 v106, 0x3000, v96
	global_load_lds_dwordx4 v[104:105], off
	v_lshl_add_u64 v[104:105], v[102:103], 0, s[36:37]
	s_mov_b32 m0, s35
	s_mov_b64 s[36:37], 0x62ae080
	v_readfirstlane_b32 s35, v106
	global_load_lds_dwordx4 v[104:105], off
	v_lshl_add_u64 v[104:105], v[102:103], 0, s[36:37]
	s_mov_b32 m0, s35
	s_mov_b64 s[36:37], 0x6312080
	global_load_lds_dwordx4 v[104:105], off
	v_add_u32_e32 v104, 0x4000, v96
	v_lshl_add_u64 v[102:103], v[102:103], 0, s[36:37]
	v_readfirstlane_b32 s35, v104
	s_mov_b32 m0, s35
	v_add_u32_e32 v106, 0x5000, v96
	global_load_lds_dwordx4 v[102:103], off
	v_lshl_add_u64 v[102:103], v[100:101], 0, s[8:9]
	s_mov_b64 s[36:37], 0x14931080
	v_readfirstlane_b32 s35, v106
	v_add_u32_e32 v106, 0x6000, v96
	v_lshl_add_u64 v[104:105], v[102:103], 0, s[36:37]
	s_mov_b32 m0, s35
	s_mov_b64 s[36:37], 0x14941080
	v_readfirstlane_b32 s35, v106
	v_add_u32_e32 v106, 0x7000, v96
	global_load_lds_dwordx4 v[104:105], off
	v_lshl_add_u64 v[104:105], v[102:103], 0, s[36:37]
	s_mov_b32 m0, s35
	s_mov_b64 s[36:37], 0x14951080
	v_readfirstlane_b32 s35, v106
	v_add_u32_e32 v96, 0x8000, v96
	global_load_lds_dwordx4 v[104:105], off
	v_lshl_add_u64 v[104:105], v[102:103], 0, s[36:37]
	s_mov_b32 m0, s35
	s_mov_b64 s[36:37], 0x14961080
	v_readfirstlane_b32 s35, v96
	global_load_lds_dwordx4 v[104:105], off
	v_lshl_add_u64 v[102:103], v[102:103], 0, s[36:37]
	s_mov_b32 m0, s35
	s_bitcmp1_b32 s10, 0
	global_load_lds_dwordx4 v[102:103], off
	s_cselect_b32 s10, 0x9000, 0
	s_add_i32 s10, s10, 0
	v_add_u32_e32 v96, s10, v116
	v_add_u32_e32 v114, v96, v117
	ds_read_b128 v[102:105], v114
	ds_read_b128 v[106:109], v114 offset:2048
	ds_read_b128 v[110:113], v114 offset:4096
	ds_read_b128 v[126:129], v114 offset:6144
	v_add_u32_e32 v96, v96, v118
	ds_read_b128 v[130:133], v114 offset:8192
	ds_read_b128 v[156:159], v96 offset:20480
	ds_read_b128 v[166:169], v96 offset:22528
	ds_read_b128 v[178:181], v96 offset:24576
	ds_read_b128 v[182:185], v96 offset:26624
	v_add_u32_e32 v210, s10, v119
	v_add_u32_e32 v211, v210, v117
	ds_read_b128 v[212:215], v211
	ds_read_b128 v[216:219], v211 offset:2048
	ds_read_b128 v[220:223], v211 offset:4096
	ds_read_b128 v[224:227], v211 offset:6144
	v_add_u32_e32 v228, v210, v118
	ds_read_b128 v[230:233], v211 offset:8192
	ds_read_b128 v[234:237], v228 offset:20480
	ds_read_b128 v[238:241], v228 offset:22528
	ds_read_b128 v[242:245], v228 offset:24576
	ds_read_b128 v[246:249], v228 offset:26624
	s_setprio 1
	s_waitcnt lgkmcnt(9)
	v_mfma_f32_16x16x32_bf16 v[76:79], v[156:159], v[102:105], v[76:79]
	v_mfma_f32_16x16x32_bf16 v[72:75], v[166:169], v[102:105], v[72:75]
	v_mfma_f32_16x16x32_bf16 v[68:71], v[178:181], v[102:105], v[68:71]
	v_mfma_f32_16x16x32_bf16 v[64:67], v[182:185], v[102:105], v[64:67]
	v_mfma_f32_16x16x32_bf16 v[60:63], v[156:159], v[106:109], v[60:63]
	v_mfma_f32_16x16x32_bf16 v[56:59], v[166:169], v[106:109], v[56:59]
	v_mfma_f32_16x16x32_bf16 v[52:55], v[178:181], v[106:109], v[52:55]
	v_mfma_f32_16x16x32_bf16 v[48:51], v[182:185], v[106:109], v[48:51]
	v_mfma_f32_16x16x32_bf16 v[44:47], v[156:159], v[110:113], v[44:47]
	v_mfma_f32_16x16x32_bf16 v[40:43], v[166:169], v[110:113], v[40:43]
	v_mfma_f32_16x16x32_bf16 v[36:39], v[178:181], v[110:113], v[36:39]
	v_mfma_f32_16x16x32_bf16 v[32:35], v[182:185], v[110:113], v[32:35]
	v_mfma_f32_16x16x32_bf16 v[28:31], v[156:159], v[126:129], v[28:31]
	v_mfma_f32_16x16x32_bf16 v[24:27], v[166:169], v[126:129], v[24:27]
	v_mfma_f32_16x16x32_bf16 v[20:23], v[178:181], v[126:129], v[20:23]
	v_mfma_f32_16x16x32_bf16 v[16:19], v[182:185], v[126:129], v[16:19]
	v_mfma_f32_16x16x32_bf16 v[12:15], v[156:159], v[130:133], v[12:15]
	v_mfma_f32_16x16x32_bf16 v[8:11], v[166:169], v[130:133], v[8:11]
	v_mfma_f32_16x16x32_bf16 v[4:7], v[178:181], v[130:133], v[4:7]
	v_mfma_f32_16x16x32_bf16 v[0:3], v[182:185], v[130:133], v[0:3]
	s_setprio 0
	s_setprio 1
	s_waitcnt lgkmcnt(0)
	v_mfma_f32_16x16x32_bf16 v[76:79], v[234:237], v[212:215], v[76:79]
	v_mfma_f32_16x16x32_bf16 v[72:75], v[238:241], v[212:215], v[72:75]
	v_mfma_f32_16x16x32_bf16 v[68:71], v[242:245], v[212:215], v[68:71]
	v_mfma_f32_16x16x32_bf16 v[64:67], v[246:249], v[212:215], v[64:67]
	v_mfma_f32_16x16x32_bf16 v[60:63], v[234:237], v[216:219], v[60:63]
	v_mfma_f32_16x16x32_bf16 v[56:59], v[238:241], v[216:219], v[56:59]
	v_mfma_f32_16x16x32_bf16 v[52:55], v[242:245], v[216:219], v[52:55]
	v_mfma_f32_16x16x32_bf16 v[48:51], v[246:249], v[216:219], v[48:51]
	v_mfma_f32_16x16x32_bf16 v[44:47], v[234:237], v[220:223], v[44:47]
	v_mfma_f32_16x16x32_bf16 v[40:43], v[238:241], v[220:223], v[40:43]
	v_mfma_f32_16x16x32_bf16 v[36:39], v[242:245], v[220:223], v[36:39]
	v_mfma_f32_16x16x32_bf16 v[32:35], v[246:249], v[220:223], v[32:35]
	v_mfma_f32_16x16x32_bf16 v[28:31], v[234:237], v[224:227], v[28:31]
	v_mfma_f32_16x16x32_bf16 v[24:27], v[238:241], v[224:227], v[24:27]
	v_mfma_f32_16x16x32_bf16 v[20:23], v[242:245], v[224:227], v[20:23]
	v_mfma_f32_16x16x32_bf16 v[16:19], v[246:249], v[224:227], v[16:19]
	v_mfma_f32_16x16x32_bf16 v[12:15], v[234:237], v[230:233], v[12:15]
	v_mfma_f32_16x16x32_bf16 v[8:11], v[238:241], v[230:233], v[8:11]
	v_mfma_f32_16x16x32_bf16 v[4:7], v[242:245], v[230:233], v[4:7]
	v_mfma_f32_16x16x32_bf16 v[0:3], v[246:249], v[230:233], v[0:3]
	s_setprio 0
	s_waitcnt vmcnt(0)
	s_add_u32 s8, s8, 0x80
	s_addc_u32 s9, s9, 0
	s_cmpk_lg_i32 s8, 0x780
	s_mov_b32 s10, s11
	s_waitcnt vmcnt(0)
	s_barrier
	s_cbranch_scc1 .LBB0_90
	ds_read_b128 v[100:103], v122 offset:63488
	ds_read_b128 v[104:107], v122 offset:61440
	ds_read_b128 v[108:111], v122 offset:59392
	ds_read_b128 v[112:115], v122 offset:57344
	ds_read_b128 v[126:129], v123 offset:45056
	ds_read_b128 v[130:133], v123 offset:43008
	ds_read_b128 v[156:159], v123 offset:40960
	ds_read_b128 v[166:169], v123 offset:38912
	ds_read_b128 v[178:181], v123 offset:36864
	s_setprio 1
	s_waitcnt lgkmcnt(0)
	v_mfma_f32_16x16x32_bf16 v[76:79], v[112:115], v[178:181], v[76:79]
	v_mfma_f32_16x16x32_bf16 v[72:75], v[108:111], v[178:181], v[72:75]
	v_mfma_f32_16x16x32_bf16 v[68:71], v[104:107], v[178:181], v[68:71]
	v_mfma_f32_16x16x32_bf16 v[64:67], v[100:103], v[178:181], v[64:67]
	v_mfma_f32_16x16x32_bf16 v[60:63], v[112:115], v[166:169], v[60:63]
	v_mfma_f32_16x16x32_bf16 v[56:59], v[108:111], v[166:169], v[56:59]
	v_mfma_f32_16x16x32_bf16 v[52:55], v[104:107], v[166:169], v[52:55]
	v_mfma_f32_16x16x32_bf16 v[48:51], v[100:103], v[166:169], v[48:51]
	v_mfma_f32_16x16x32_bf16 v[44:47], v[112:115], v[156:159], v[44:47]
	v_mfma_f32_16x16x32_bf16 v[40:43], v[108:111], v[156:159], v[40:43]
	v_mfma_f32_16x16x32_bf16 v[36:39], v[104:107], v[156:159], v[36:39]
	v_mfma_f32_16x16x32_bf16 v[32:35], v[100:103], v[156:159], v[32:35]
	v_mfma_f32_16x16x32_bf16 v[28:31], v[112:115], v[130:133], v[28:31]
	v_mfma_f32_16x16x32_bf16 v[24:27], v[108:111], v[130:133], v[24:27]
	v_mfma_f32_16x16x32_bf16 v[20:23], v[104:107], v[130:133], v[20:23]
	v_mfma_f32_16x16x32_bf16 v[16:19], v[100:103], v[130:133], v[16:19]
	v_mfma_f32_16x16x32_bf16 v[12:15], v[112:115], v[126:129], v[12:15]
	v_mfma_f32_16x16x32_bf16 v[8:11], v[108:111], v[126:129], v[8:11]
	v_mfma_f32_16x16x32_bf16 v[4:7], v[104:107], v[126:129], v[4:7]
	v_mfma_f32_16x16x32_bf16 v[0:3], v[100:103], v[126:129], v[0:3]
	s_setprio 0
	ds_read_b128 v[100:103], v124 offset:36864
	ds_read_b128 v[104:107], v124 offset:38912
	ds_read_b128 v[108:111], v124 offset:40960
	ds_read_b128 v[112:115], v124 offset:43008
	ds_read_b128 v[126:129], v124 offset:45056
	ds_read_b128 v[130:133], v125 offset:57344
	ds_read_b128 v[156:159], v125 offset:59392
	ds_read_b128 v[166:169], v125 offset:61440
	ds_read_b128 v[122:125], v125 offset:63488
	s_setprio 1
	s_waitcnt lgkmcnt(3)
	v_mfma_f32_16x16x32_bf16 v[178:181], v[130:133], v[100:103], v[76:79]
	s_waitcnt lgkmcnt(2)
	v_mfma_f32_16x16x32_bf16 v[72:75], v[156:159], v[100:103], v[72:75]
	s_waitcnt lgkmcnt(1)
	v_mfma_f32_16x16x32_bf16 v[68:71], v[166:169], v[100:103], v[68:71]
	s_waitcnt lgkmcnt(0)
	v_mfma_f32_16x16x32_bf16 v[64:67], v[122:125], v[100:103], v[64:67]
	v_mfma_f32_16x16x32_bf16 v[60:63], v[130:133], v[104:107], v[60:63]
	v_mfma_f32_16x16x32_bf16 v[56:59], v[156:159], v[104:107], v[56:59]
	v_mfma_f32_16x16x32_bf16 v[52:55], v[166:169], v[104:107], v[52:55]
	v_mfma_f32_16x16x32_bf16 v[48:51], v[122:125], v[104:107], v[48:51]
	v_mfma_f32_16x16x32_bf16 v[44:47], v[130:133], v[108:111], v[44:47]
	v_mfma_f32_16x16x32_bf16 v[40:43], v[156:159], v[108:111], v[40:43]
	v_mfma_f32_16x16x32_bf16 v[36:39], v[166:169], v[108:111], v[36:39]
	v_mfma_f32_16x16x32_bf16 v[32:35], v[122:125], v[108:111], v[32:35]
	v_mfma_f32_16x16x32_bf16 v[28:31], v[130:133], v[112:115], v[28:31]
	v_mfma_f32_16x16x32_bf16 v[24:27], v[156:159], v[112:115], v[24:27]
	v_mfma_f32_16x16x32_bf16 v[20:23], v[166:169], v[112:115], v[20:23]
	v_mfma_f32_16x16x32_bf16 v[16:19], v[122:125], v[112:115], v[16:19]
	v_mfma_f32_16x16x32_bf16 v[12:15], v[130:133], v[126:129], v[12:15]
	v_mfma_f32_16x16x32_bf16 v[8:11], v[156:159], v[126:129], v[8:11]
	v_mfma_f32_16x16x32_bf16 v[4:7], v[166:169], v[126:129], v[4:7]
	v_mfma_f32_16x16x32_bf16 v[0:3], v[122:125], v[126:129], v[0:3]
	s_setprio 0
	v_mov_b32_e32 v76, v97
	s_waitcnt vmcnt(0)
	s_barrier
	v_ashrrev_i32_e32 v220, 7, v176
	v_mov_b32_e32 v221, 0x50
	v_and_or_b32 v224, v176, 15, s12
	v_mad_u32_u24 v224, v220, v221, v224
	v_and_b32_e32 v220, 64, v176
	v_lshrrev_b32_e32 v221, 2, v176
	v_and_b32_e32 v221, 12, v221
	v_or3_b32 v225, v220, v221, s13
	v_mul_u32_u24_e32 v216, 0x3200, v224
	v_lshl_add_u32 v216, v225, 1, v216
	v_add_u32_e32 v216, 0x2800, v216
	v_lshlrev_b32_e32 v217, 12, v224
	v_lshl_add_u32 v217, v225, 2, v217
	v_lshlrev_b32_e32 v210, 11, v224
	v_lshl_add_u32 v210, v225, 1, v210
	v_mov_b32_e32 v223, 0
	v_mov_b32_e32 v222, v216
	v_lshl_add_u64 v[224:225], v[222:223], 0, s[0:1]
	global_load_dwordx2 v[76:77], v[224:225], off
	global_load_dwordx2 v[78:79], v[224:225], off offset:32
	global_load_dwordx2 v[106:107], v[224:225], off offset:64
	global_load_dwordx2 v[108:109], v[224:225], off offset:96
	v_add_u32_e32 v222, 0x32000, v216
	v_lshl_add_u64 v[224:225], v[222:223], 0, s[0:1]
	global_load_dwordx2 v[110:111], v[224:225], off
	global_load_dwordx2 v[112:113], v[224:225], off offset:32
	global_load_dwordx2 v[122:123], v[224:225], off offset:64
	global_load_dwordx2 v[124:125], v[224:225], off offset:96
	v_add_u32_e32 v222, 0x64000, v216
	v_lshl_add_u64 v[224:225], v[222:223], 0, s[0:1]
	global_load_dwordx2 v[114:115], v[224:225], off
	global_load_dwordx2 v[226:227], v[224:225], off offset:32
	global_load_dwordx2 v[246:247], v[224:225], off offset:64
	global_load_dwordx2 v[248:249], v[224:225], off offset:96
	v_add_u32_e32 v222, 0x96000, v216
	v_lshl_add_u64 v[224:225], v[222:223], 0, s[0:1]
	global_load_dwordx2 v[242:243], v[224:225], off
	global_load_dwordx2 v[244:245], v[224:225], off offset:32
	global_load_dwordx2 v[238:239], v[224:225], off offset:64
	global_load_dwordx2 v[240:241], v[224:225], off offset:96
	v_add_u32_e32 v222, 0xc8000, v216
	v_lshl_add_u64 v[224:225], v[222:223], 0, s[0:1]
	global_load_dwordx2 v[234:235], v[224:225], off
	global_load_dwordx2 v[236:237], v[224:225], off offset:32
	global_load_dwordx2 v[230:231], v[224:225], off offset:64
	global_load_dwordx2 v[232:233], v[224:225], off offset:96
	v_mov_b32_e32 v222, v217
	v_lshl_add_u64 v[224:225], v[222:223], 0, s[4:5]
	global_load_dwordx4 v[126:129], v[224:225], off
	global_load_dwordx4 v[130:133], v[224:225], off offset:64
	global_load_dwordx4 v[156:159], v[224:225], off offset:128
	global_load_dwordx4 v[166:169], v[224:225], off offset:192
	v_add_u32_e32 v222, 0x10000, v217
	v_lshl_add_u64 v[224:225], v[222:223], 0, s[4:5]
	global_load_dwordx4 v[182:185], v[224:225], off
	global_load_dwordx4 v[186:189], v[224:225], off offset:64
	global_load_dwordx4 v[190:193], v[224:225], off offset:128
	global_load_dwordx4 v[194:197], v[224:225], off offset:192
	v_mov_b32_e32 v222, v210
	v_lshl_add_u64 v[214:215], v[222:223], 0, s[6:7]
	s_waitcnt vmcnt(7)
	v_lshlrev_b32_e32 v220, 16, v76
	v_and_b32_e32 v221, 0xffff0000, v76
	v_pk_fma_f32 v[178:179], v[178:179], v[220:221], v[126:127]
	v_lshlrev_b32_e32 v76, 16, v77
	v_and_b32_e32 v77, 0xffff0000, v77
	v_pk_fma_f32 v[180:181], v[180:181], v[76:77], v[128:129]
	s_nop 0
	v_bfe_u32 v220, v178, 16, 1
	v_add3_u32 v178, v178, v220, s33
	v_bfe_u32 v220, v179, 16, 1
	v_add3_u32 v179, v179, v220, s33
	v_bfe_u32 v220, v180, 16, 1
	v_add3_u32 v180, v180, v220, s33
	v_bfe_u32 v220, v181, 16, 1
	v_add3_u32 v181, v181, v220, s33
	v_perm_b32 v178, v179, v178, s96
	v_perm_b32 v179, v181, v180, s96
	global_store_dwordx2 v[214:215], v[178:179], off
	s_waitcnt vmcnt(7)
	v_lshlrev_b32_e32 v220, 16, v78
	v_and_b32_e32 v221, 0xffff0000, v78
	v_pk_fma_f32 v[72:73], v[72:73], v[220:221], v[130:131]
	v_lshlrev_b32_e32 v78, 16, v79
	v_and_b32_e32 v79, 0xffff0000, v79
	v_pk_fma_f32 v[74:75], v[74:75], v[78:79], v[132:133]
	s_nop 0
	v_bfe_u32 v220, v72, 16, 1
	v_add3_u32 v72, v72, v220, s33
	v_bfe_u32 v220, v73, 16, 1
	v_add3_u32 v73, v73, v220, s33
	v_bfe_u32 v220, v74, 16, 1
	v_add3_u32 v74, v74, v220, s33
	v_bfe_u32 v220, v75, 16, 1
	v_add3_u32 v75, v75, v220, s33
	v_perm_b32 v72, v73, v72, s96
	v_perm_b32 v73, v75, v74, s96
	global_store_dwordx2 v[214:215], v[72:73], off offset:32
	s_waitcnt vmcnt(7)
	v_lshlrev_b32_e32 v220, 16, v106
	v_and_b32_e32 v221, 0xffff0000, v106
	v_pk_fma_f32 v[68:69], v[68:69], v[220:221], v[156:157]
	v_lshlrev_b32_e32 v106, 16, v107
	v_and_b32_e32 v107, 0xffff0000, v107
	v_pk_fma_f32 v[70:71], v[70:71], v[106:107], v[158:159]
	s_nop 0
	v_bfe_u32 v220, v68, 16, 1
	v_add3_u32 v68, v68, v220, s33
	v_bfe_u32 v220, v69, 16, 1
	v_add3_u32 v69, v69, v220, s33
	v_bfe_u32 v220, v70, 16, 1
	v_add3_u32 v70, v70, v220, s33
	v_bfe_u32 v220, v71, 16, 1
	v_add3_u32 v71, v71, v220, s33
	v_perm_b32 v68, v69, v68, s96
	v_perm_b32 v69, v71, v70, s96
	global_store_dwordx2 v[214:215], v[68:69], off offset:64
	s_waitcnt vmcnt(7)
	v_lshlrev_b32_e32 v220, 16, v108
	v_and_b32_e32 v221, 0xffff0000, v108
	v_pk_fma_f32 v[64:65], v[64:65], v[220:221], v[166:167]
	v_lshlrev_b32_e32 v108, 16, v109
	v_and_b32_e32 v109, 0xffff0000, v109
	v_pk_fma_f32 v[66:67], v[66:67], v[108:109], v[168:169]
	s_nop 0
	v_bfe_u32 v220, v64, 16, 1
	v_add3_u32 v64, v64, v220, s33
	v_bfe_u32 v220, v65, 16, 1
	v_add3_u32 v65, v65, v220, s33
	v_bfe_u32 v220, v66, 16, 1
	v_add3_u32 v66, v66, v220, s33
	v_bfe_u32 v220, v67, 16, 1
	v_add3_u32 v67, v67, v220, s33
	v_perm_b32 v64, v65, v64, s96
	v_perm_b32 v65, v67, v66, s96
	global_store_dwordx2 v[214:215], v[64:65], off offset:96
	v_add_u32_e32 v222, 0x20000, v217
	v_lshl_add_u64 v[224:225], v[222:223], 0, s[4:5]
	global_load_dwordx4 v[126:129], v[224:225], off
	global_load_dwordx4 v[130:133], v[224:225], off offset:64
	global_load_dwordx4 v[156:159], v[224:225], off offset:128
	global_load_dwordx4 v[166:169], v[224:225], off offset:192
	v_add_u32_e32 v222, 0x8000, v210
	v_lshl_add_u64 v[214:215], v[222:223], 0, s[6:7]
	s_waitcnt vmcnt(11)
	v_lshlrev_b32_e32 v220, 16, v110
	v_and_b32_e32 v221, 0xffff0000, v110
	v_pk_fma_f32 v[60:61], v[60:61], v[220:221], v[182:183]
	v_lshlrev_b32_e32 v110, 16, v111
	v_and_b32_e32 v111, 0xffff0000, v111
	v_pk_fma_f32 v[62:63], v[62:63], v[110:111], v[184:185]
	s_nop 0
	v_bfe_u32 v220, v60, 16, 1
	v_add3_u32 v60, v60, v220, s33
	v_bfe_u32 v220, v61, 16, 1
	v_add3_u32 v61, v61, v220, s33
	v_bfe_u32 v220, v62, 16, 1
	v_add3_u32 v62, v62, v220, s33
	v_bfe_u32 v220, v63, 16, 1
	v_add3_u32 v63, v63, v220, s33
	v_perm_b32 v60, v61, v60, s96
	v_perm_b32 v61, v63, v62, s96
	global_store_dwordx2 v[214:215], v[60:61], off
	s_waitcnt vmcnt(11)
	v_lshlrev_b32_e32 v220, 16, v112
	v_and_b32_e32 v221, 0xffff0000, v112
	v_pk_fma_f32 v[56:57], v[56:57], v[220:221], v[186:187]
	v_lshlrev_b32_e32 v112, 16, v113
	v_and_b32_e32 v113, 0xffff0000, v113
	v_pk_fma_f32 v[58:59], v[58:59], v[112:113], v[188:189]
	s_nop 0
	v_bfe_u32 v220, v56, 16, 1
	v_add3_u32 v56, v56, v220, s33
	v_bfe_u32 v220, v57, 16, 1
	v_add3_u32 v57, v57, v220, s33
	v_bfe_u32 v220, v58, 16, 1
	v_add3_u32 v58, v58, v220, s33
	v_bfe_u32 v220, v59, 16, 1
	v_add3_u32 v59, v59, v220, s33
	v_perm_b32 v56, v57, v56, s96
	v_perm_b32 v57, v59, v58, s96
	global_store_dwordx2 v[214:215], v[56:57], off offset:32
	s_waitcnt vmcnt(11)
	v_lshlrev_b32_e32 v220, 16, v122
	v_and_b32_e32 v221, 0xffff0000, v122
	v_pk_fma_f32 v[52:53], v[52:53], v[220:221], v[190:191]
	v_lshlrev_b32_e32 v122, 16, v123
	v_and_b32_e32 v123, 0xffff0000, v123
	v_pk_fma_f32 v[54:55], v[54:55], v[122:123], v[192:193]
	s_nop 0
	v_bfe_u32 v220, v52, 16, 1
	v_add3_u32 v52, v52, v220, s33
	v_bfe_u32 v220, v53, 16, 1
	v_add3_u32 v53, v53, v220, s33
	v_bfe_u32 v220, v54, 16, 1
	v_add3_u32 v54, v54, v220, s33
	v_bfe_u32 v220, v55, 16, 1
	v_add3_u32 v55, v55, v220, s33
	v_perm_b32 v52, v53, v52, s96
	v_perm_b32 v53, v55, v54, s96
	global_store_dwordx2 v[214:215], v[52:53], off offset:64
	s_waitcnt vmcnt(11)
	v_lshlrev_b32_e32 v220, 16, v124
	v_and_b32_e32 v221, 0xffff0000, v124
	v_pk_fma_f32 v[48:49], v[48:49], v[220:221], v[194:195]
	v_lshlrev_b32_e32 v124, 16, v125
	v_and_b32_e32 v125, 0xffff0000, v125
	v_pk_fma_f32 v[50:51], v[50:51], v[124:125], v[196:197]
	s_nop 0
	v_bfe_u32 v220, v48, 16, 1
	v_add3_u32 v48, v48, v220, s33
	v_bfe_u32 v220, v49, 16, 1
	v_add3_u32 v49, v49, v220, s33
	v_bfe_u32 v220, v50, 16, 1
	v_add3_u32 v50, v50, v220, s33
	v_bfe_u32 v220, v51, 16, 1
	v_add3_u32 v51, v51, v220, s33
	v_perm_b32 v48, v49, v48, s96
	v_perm_b32 v49, v51, v50, s96
	global_store_dwordx2 v[214:215], v[48:49], off offset:96
	v_add_u32_e32 v222, 0x30000, v217
	v_lshl_add_u64 v[224:225], v[222:223], 0, s[4:5]
	global_load_dwordx4 v[182:185], v[224:225], off
	global_load_dwordx4 v[186:189], v[224:225], off offset:64
	global_load_dwordx4 v[190:193], v[224:225], off offset:128
	global_load_dwordx4 v[194:197], v[224:225], off offset:192
	v_add_u32_e32 v222, 0x40000, v217
	v_lshl_add_u64 v[224:225], v[222:223], 0, s[4:5]
	global_load_dwordx4 v[76:79], v[224:225], off
	global_load_dwordx4 v[106:109], v[224:225], off offset:64
	global_load_dwordx4 v[110:113], v[224:225], off offset:128
	global_load_dwordx4 v[122:125], v[224:225], off offset:192
	v_add_u32_e32 v222, 0x10000, v210
	v_lshl_add_u64 v[214:215], v[222:223], 0, s[6:7]
	s_waitcnt vmcnt(15)
	v_lshlrev_b32_e32 v220, 16, v114
	v_and_b32_e32 v221, 0xffff0000, v114
	v_pk_fma_f32 v[44:45], v[44:45], v[220:221], v[126:127]
	v_lshlrev_b32_e32 v114, 16, v115
	v_and_b32_e32 v115, 0xffff0000, v115
	v_pk_fma_f32 v[46:47], v[46:47], v[114:115], v[128:129]
	s_nop 0
	v_bfe_u32 v220, v44, 16, 1
	v_add3_u32 v44, v44, v220, s33
	v_bfe_u32 v220, v45, 16, 1
	v_add3_u32 v45, v45, v220, s33
	v_bfe_u32 v220, v46, 16, 1
	v_add3_u32 v46, v46, v220, s33
	v_bfe_u32 v220, v47, 16, 1
	v_add3_u32 v47, v47, v220, s33
	v_perm_b32 v44, v45, v44, s96
	v_perm_b32 v45, v47, v46, s96
	global_store_dwordx2 v[214:215], v[44:45], off
	s_waitcnt vmcnt(15)
	v_lshlrev_b32_e32 v220, 16, v226
	v_and_b32_e32 v221, 0xffff0000, v226
	v_pk_fma_f32 v[40:41], v[40:41], v[220:221], v[130:131]
	v_lshlrev_b32_e32 v226, 16, v227
	v_and_b32_e32 v227, 0xffff0000, v227
	v_pk_fma_f32 v[42:43], v[42:43], v[226:227], v[132:133]
	s_nop 0
	v_bfe_u32 v220, v40, 16, 1
	v_add3_u32 v40, v40, v220, s33
	v_bfe_u32 v220, v41, 16, 1
	v_add3_u32 v41, v41, v220, s33
	v_bfe_u32 v220, v42, 16, 1
	v_add3_u32 v42, v42, v220, s33
	v_bfe_u32 v220, v43, 16, 1
	v_add3_u32 v43, v43, v220, s33
	v_perm_b32 v40, v41, v40, s96
	v_perm_b32 v41, v43, v42, s96
	global_store_dwordx2 v[214:215], v[40:41], off offset:32
	s_waitcnt vmcnt(15)
	v_lshlrev_b32_e32 v220, 16, v246
	v_and_b32_e32 v221, 0xffff0000, v246
	v_pk_fma_f32 v[36:37], v[36:37], v[220:221], v[156:157]
	v_lshlrev_b32_e32 v246, 16, v247
	v_and_b32_e32 v247, 0xffff0000, v247
	v_pk_fma_f32 v[38:39], v[38:39], v[246:247], v[158:159]
	s_nop 0
	v_bfe_u32 v220, v36, 16, 1
	v_add3_u32 v36, v36, v220, s33
	v_bfe_u32 v220, v37, 16, 1
	v_add3_u32 v37, v37, v220, s33
	v_bfe_u32 v220, v38, 16, 1
	v_add3_u32 v38, v38, v220, s33
	v_bfe_u32 v220, v39, 16, 1
	v_add3_u32 v39, v39, v220, s33
	v_perm_b32 v36, v37, v36, s96
	v_perm_b32 v37, v39, v38, s96
	global_store_dwordx2 v[214:215], v[36:37], off offset:64
	s_waitcnt vmcnt(15)
	v_lshlrev_b32_e32 v220, 16, v248
	v_and_b32_e32 v221, 0xffff0000, v248
	v_pk_fma_f32 v[32:33], v[32:33], v[220:221], v[166:167]
	v_lshlrev_b32_e32 v248, 16, v249
	v_and_b32_e32 v249, 0xffff0000, v249
	v_pk_fma_f32 v[34:35], v[34:35], v[248:249], v[168:169]
	s_nop 0
	v_bfe_u32 v220, v32, 16, 1
	v_add3_u32 v32, v32, v220, s33
	v_bfe_u32 v220, v33, 16, 1
	v_add3_u32 v33, v33, v220, s33
	v_bfe_u32 v220, v34, 16, 1
	v_add3_u32 v34, v34, v220, s33
	v_bfe_u32 v220, v35, 16, 1
	v_add3_u32 v35, v35, v220, s33
	v_perm_b32 v32, v33, v32, s96
	v_perm_b32 v33, v35, v34, s96
	global_store_dwordx2 v[214:215], v[32:33], off offset:96
	v_add_u32_e32 v222, 0x18000, v210
	v_lshl_add_u64 v[214:215], v[222:223], 0, s[6:7]
	s_waitcnt vmcnt(11)
	v_lshlrev_b32_e32 v220, 16, v242
	v_and_b32_e32 v221, 0xffff0000, v242
	v_pk_fma_f32 v[28:29], v[28:29], v[220:221], v[182:183]
	v_lshlrev_b32_e32 v242, 16, v243
	v_and_b32_e32 v243, 0xffff0000, v243
	v_pk_fma_f32 v[30:31], v[30:31], v[242:243], v[184:185]
	s_nop 0
	v_bfe_u32 v220, v28, 16, 1
	v_add3_u32 v28, v28, v220, s33
	v_bfe_u32 v220, v29, 16, 1
	v_add3_u32 v29, v29, v220, s33
	v_bfe_u32 v220, v30, 16, 1
	v_add3_u32 v30, v30, v220, s33
	v_bfe_u32 v220, v31, 16, 1
	v_add3_u32 v31, v31, v220, s33
	v_perm_b32 v28, v29, v28, s96
	v_perm_b32 v29, v31, v30, s96
	global_store_dwordx2 v[214:215], v[28:29], off
	s_waitcnt vmcnt(11)
	v_lshlrev_b32_e32 v220, 16, v244
	v_and_b32_e32 v221, 0xffff0000, v244
	v_pk_fma_f32 v[24:25], v[24:25], v[220:221], v[186:187]
	v_lshlrev_b32_e32 v244, 16, v245
	v_and_b32_e32 v245, 0xffff0000, v245
	v_pk_fma_f32 v[26:27], v[26:27], v[244:245], v[188:189]
	s_nop 0
	v_bfe_u32 v220, v24, 16, 1
	v_add3_u32 v24, v24, v220, s33
	v_bfe_u32 v220, v25, 16, 1
	v_add3_u32 v25, v25, v220, s33
	v_bfe_u32 v220, v26, 16, 1
	v_add3_u32 v26, v26, v220, s33
	v_bfe_u32 v220, v27, 16, 1
	v_add3_u32 v27, v27, v220, s33
	v_perm_b32 v24, v25, v24, s96
	v_perm_b32 v25, v27, v26, s96
	global_store_dwordx2 v[214:215], v[24:25], off offset:32
	s_waitcnt vmcnt(11)
	v_lshlrev_b32_e32 v220, 16, v238
	v_and_b32_e32 v221, 0xffff0000, v238
	v_pk_fma_f32 v[20:21], v[20:21], v[220:221], v[190:191]
	v_lshlrev_b32_e32 v238, 16, v239
	v_and_b32_e32 v239, 0xffff0000, v239
	v_pk_fma_f32 v[22:23], v[22:23], v[238:239], v[192:193]
	s_nop 0
	v_bfe_u32 v220, v20, 16, 1
	v_add3_u32 v20, v20, v220, s33
	v_bfe_u32 v220, v21, 16, 1
	v_add3_u32 v21, v21, v220, s33
	v_bfe_u32 v220, v22, 16, 1
	v_add3_u32 v22, v22, v220, s33
	v_bfe_u32 v220, v23, 16, 1
	v_add3_u32 v23, v23, v220, s33
	v_perm_b32 v20, v21, v20, s96
	v_perm_b32 v21, v23, v22, s96
	global_store_dwordx2 v[214:215], v[20:21], off offset:64
	s_waitcnt vmcnt(11)
	v_lshlrev_b32_e32 v220, 16, v240
	v_and_b32_e32 v221, 0xffff0000, v240
	v_pk_fma_f32 v[16:17], v[16:17], v[220:221], v[194:195]
	v_lshlrev_b32_e32 v240, 16, v241
	v_and_b32_e32 v241, 0xffff0000, v241
	v_pk_fma_f32 v[18:19], v[18:19], v[240:241], v[196:197]
	s_nop 0
	v_bfe_u32 v220, v16, 16, 1
	v_add3_u32 v16, v16, v220, s33
	v_bfe_u32 v220, v17, 16, 1
	v_add3_u32 v17, v17, v220, s33
	v_bfe_u32 v220, v18, 16, 1
	v_add3_u32 v18, v18, v220, s33
	v_bfe_u32 v220, v19, 16, 1
	v_add3_u32 v19, v19, v220, s33
	v_perm_b32 v16, v17, v16, s96
	v_perm_b32 v17, v19, v18, s96
	global_store_dwordx2 v[214:215], v[16:17], off offset:96
	v_add_u32_e32 v222, 0x20000, v210
	v_lshl_add_u64 v[214:215], v[222:223], 0, s[6:7]
	s_waitcnt vmcnt(11)
	v_lshlrev_b32_e32 v220, 16, v234
	v_and_b32_e32 v221, 0xffff0000, v234
	v_pk_fma_f32 v[12:13], v[12:13], v[220:221], v[76:77]
	v_lshlrev_b32_e32 v234, 16, v235
	v_and_b32_e32 v235, 0xffff0000, v235
	v_pk_fma_f32 v[14:15], v[14:15], v[234:235], v[78:79]
	s_nop 0
	v_bfe_u32 v220, v12, 16, 1
	v_add3_u32 v12, v12, v220, s33
	v_bfe_u32 v220, v13, 16, 1
	v_add3_u32 v13, v13, v220, s33
	v_bfe_u32 v220, v14, 16, 1
	v_add3_u32 v14, v14, v220, s33
	v_bfe_u32 v220, v15, 16, 1
	v_add3_u32 v15, v15, v220, s33
	v_perm_b32 v12, v13, v12, s96
	v_perm_b32 v13, v15, v14, s96
	global_store_dwordx2 v[214:215], v[12:13], off
	s_waitcnt vmcnt(11)
	v_lshlrev_b32_e32 v220, 16, v236
	v_and_b32_e32 v221, 0xffff0000, v236
	v_pk_fma_f32 v[8:9], v[8:9], v[220:221], v[106:107]
	v_lshlrev_b32_e32 v236, 16, v237
	v_and_b32_e32 v237, 0xffff0000, v237
	v_pk_fma_f32 v[10:11], v[10:11], v[236:237], v[108:109]
	s_nop 0
	v_bfe_u32 v220, v8, 16, 1
	v_add3_u32 v8, v8, v220, s33
	v_bfe_u32 v220, v9, 16, 1
	v_add3_u32 v9, v9, v220, s33
	v_bfe_u32 v220, v10, 16, 1
	v_add3_u32 v10, v10, v220, s33
	v_bfe_u32 v220, v11, 16, 1
	v_add3_u32 v11, v11, v220, s33
	v_perm_b32 v8, v9, v8, s96
	v_perm_b32 v9, v11, v10, s96
	global_store_dwordx2 v[214:215], v[8:9], off offset:32
	s_waitcnt vmcnt(11)
	v_lshlrev_b32_e32 v220, 16, v230
	v_and_b32_e32 v221, 0xffff0000, v230
	v_pk_fma_f32 v[4:5], v[4:5], v[220:221], v[110:111]
	v_lshlrev_b32_e32 v230, 16, v231
	v_and_b32_e32 v231, 0xffff0000, v231
	v_pk_fma_f32 v[6:7], v[6:7], v[230:231], v[112:113]
	s_nop 0
	v_bfe_u32 v220, v4, 16, 1
	v_add3_u32 v4, v4, v220, s33
	v_bfe_u32 v220, v5, 16, 1
	v_add3_u32 v5, v5, v220, s33
	v_bfe_u32 v220, v6, 16, 1
	v_add3_u32 v6, v6, v220, s33
	v_bfe_u32 v220, v7, 16, 1
	v_add3_u32 v7, v7, v220, s33
	v_perm_b32 v4, v5, v4, s96
	v_perm_b32 v5, v7, v6, s96
	global_store_dwordx2 v[214:215], v[4:5], off offset:64
	s_waitcnt vmcnt(11)
	v_lshlrev_b32_e32 v220, 16, v232
	v_and_b32_e32 v221, 0xffff0000, v232
	v_pk_fma_f32 v[0:1], v[0:1], v[220:221], v[122:123]
	v_lshlrev_b32_e32 v232, 16, v233
	v_and_b32_e32 v233, 0xffff0000, v233
	v_pk_fma_f32 v[2:3], v[2:3], v[232:233], v[124:125]
	s_nop 0
	v_bfe_u32 v220, v0, 16, 1
	v_add3_u32 v0, v0, v220, s33
	v_bfe_u32 v220, v1, 16, 1
	v_add3_u32 v1, v1, v220, s33
	v_bfe_u32 v220, v2, 16, 1
	v_add3_u32 v2, v2, v220, s33
	v_bfe_u32 v220, v3, 16, 1
	v_add3_u32 v3, v3, v220, s33
	v_perm_b32 v0, v1, v0, s96
	v_perm_b32 v1, v3, v2, s96
	global_store_dwordx2 v[214:215], v[0:1], off offset:96
	s_mov_b32 s35, 0
	s_movk_i32 s8, 0x50
	s_movk_i32 s10, 0x3200
	s_mov_b64 s[12:13], 0x2800

.LBB0_134:
	s_lshl_b32 s10, s36, 3
	s_mul_i32 s11, s10, s2
	s_cmpk_gt_i32 s11, 0x33f
	s_mov_b32 s37, 2
	s_mov_b64 s[44:45], 0x10000
	s_cbranch_scc1 .LBB0_139
	s_or_b32 s10, s10, s14
	s_mul_i32 s10, s10, s2
	s_add_i32 s10, s10, s15
	s_cmpk_gt_i32 s10, 0x33f
	s_mov_b32 s37, 4
	s_cbranch_scc1 .LBB0_139
	s_mul_hi_i32 s11, s10, 0x4ec4ec4f
	s_lshr_b32 s12, s11, 31
	s_ashr_i32 s11, s11, 8
	s_add_i32 s11, s11, s12
	s_lshl_b32 s12, s11, 3
	s_mulk_i32 s11, 0x340
	s_sub_i32 s10, s10, s11
	s_and_b32 s11, s10, 7
	s_ashr_i32 s38, s10, 3
	s_or_b32 s10, s12, s11
	s_mul_i32 s12, s38, 0x50000
	s_ashr_i32 s13, s12, 31
	v_readfirstlane_b32 s11, v177
	v_add_u32_e32 v4, 0x1000, v177
	v_lshl_add_u64 v[0:1], v[80:81], 0, s[12:13]
	s_mov_b32 m0, s11
	v_readfirstlane_b32 s11, v4
	v_add_u32_e32 v4, 0x2000, v177
	global_load_lds_dwordx4 v[0:1], off
	v_lshl_add_u64 v[2:3], v[0:1], 0, s[44:45]
	s_mov_b32 m0, s11
	s_mov_b64 s[46:47], 0x20000
	v_readfirstlane_b32 s11, v4
	v_add_u32_e32 v4, 0x3000, v177
	global_load_lds_dwordx4 v[2:3], off
	v_lshl_add_u64 v[2:3], v[0:1], 0, s[46:47]
	s_mov_b32 m0, s11
	s_mov_b64 s[48:49], 0x30000
	v_readfirstlane_b32 s11, v4
	global_load_lds_dwordx4 v[2:3], off
	v_lshl_add_u64 v[2:3], v[0:1], 0, s[48:49]
	s_mov_b32 m0, s11
	s_add_i32 s10, s10, 16
	global_load_lds_dwordx4 v[2:3], off
	v_add_u32_e32 v2, 0x4000, v177
	s_mov_b64 s[40:41], 0x40000
	v_readfirstlane_b32 s11, v2
	s_mov_b32 m0, s11
	s_ashr_i32 s11, s10, 31
	v_add_u32_e32 v2, 0x5000, v177
	v_lshl_add_u64 v[0:1], v[0:1], 0, s[40:41]
	s_lshl_b64 s[40:41], s[10:11], 18
	v_readfirstlane_b32 s11, v2
	v_add_u32_e32 v4, 0x6000, v177
	global_load_lds_dwordx4 v[0:1], off
	v_lshl_add_u64 v[0:1], v[82:83], 0, s[40:41]
	s_mov_b32 m0, s11
	v_readfirstlane_b32 s11, v4
	v_add_u32_e32 v4, 0x7000, v177
	global_load_lds_dwordx4 v[0:1], off
	v_lshl_add_u64 v[2:3], v[0:1], 0, s[44:45]
	s_mov_b32 m0, s11
	v_readfirstlane_b32 s11, v4
	global_load_lds_dwordx4 v[2:3], off
	v_lshl_add_u64 v[2:3], v[0:1], 0, s[46:47]
	s_mov_b32 m0, s11
	v_lshl_add_u64 v[0:1], v[0:1], 0, s[48:49]
	global_load_lds_dwordx4 v[2:3], off
	v_add_u32_e32 v2, 0x8000, v177
	v_lshl_add_u64 v[86:87], v[84:85], 0, s[12:13]
	v_readfirstlane_b32 s11, v2
	s_mov_b32 m0, s11
	v_lshl_add_u64 v[88:89], v[84:85], 0, s[40:41]
	global_load_lds_dwordx4 v[0:1], off
	s_nop 0
	v_mov_b32_e32 v0, 0
	s_nop 0
	s_nop 0
	s_mov_b32 s11, 0
	s_mov_b64 s[12:13], 0
	v_mov_b32_e32 v1, v0
	v_mov_b32_e32 v2, v0
	v_mov_b32_e32 v3, v0
	v_mov_b32_e32 v4, v0
	v_mov_b32_e32 v5, v0
	v_mov_b32_e32 v6, v0
	v_mov_b32_e32 v7, v0
	v_mov_b32_e32 v8, v0
	v_mov_b32_e32 v9, v0
	v_mov_b32_e32 v10, v0
	v_mov_b32_e32 v11, v0
	v_mov_b32_e32 v12, v0
	v_mov_b32_e32 v13, v0
	v_mov_b32_e32 v14, v0
	v_mov_b32_e32 v15, v0
	v_mov_b32_e32 v16, v0
	v_mov_b32_e32 v17, v0
	v_mov_b32_e32 v18, v0
	v_mov_b32_e32 v19, v0
	v_mov_b32_e32 v20, v0
	v_mov_b32_e32 v21, v0
	v_mov_b32_e32 v22, v0
	v_mov_b32_e32 v23, v0
	v_mov_b32_e32 v24, v0
	v_mov_b32_e32 v25, v0
	v_mov_b32_e32 v26, v0
	v_mov_b32_e32 v27, v0
	v_mov_b32_e32 v28, v0
	v_mov_b32_e32 v29, v0
	v_mov_b32_e32 v30, v0
	v_mov_b32_e32 v31, v0
	v_mov_b32_e32 v32, v0
	v_mov_b32_e32 v33, v0
	v_mov_b32_e32 v34, v0
	v_mov_b32_e32 v35, v0
	v_mov_b32_e32 v36, v0
	v_mov_b32_e32 v37, v0
	v_mov_b32_e32 v38, v0
	v_mov_b32_e32 v39, v0
	v_mov_b32_e32 v40, v0
	v_mov_b32_e32 v41, v0
	v_mov_b32_e32 v42, v0
	v_mov_b32_e32 v43, v0
	v_mov_b32_e32 v44, v0
	v_mov_b32_e32 v45, v0
	v_mov_b32_e32 v46, v0
	v_mov_b32_e32 v47, v0
	v_mov_b32_e32 v48, v0
	v_mov_b32_e32 v49, v0
	v_mov_b32_e32 v50, v0
	v_mov_b32_e32 v51, v0
	v_mov_b32_e32 v52, v0
	v_mov_b32_e32 v53, v0
	v_mov_b32_e32 v54, v0
	v_mov_b32_e32 v55, v0
	v_mov_b32_e32 v56, v0
	v_mov_b32_e32 v57, v0
	v_mov_b32_e32 v58, v0
	v_mov_b32_e32 v59, v0
	v_mov_b32_e32 v60, v0
	v_mov_b32_e32 v61, v0
	v_mov_b32_e32 v62, v0
	v_mov_b32_e32 v63, v0
	v_mov_b32_e32 v64, v0
	v_mov_b32_e32 v65, v0
	v_mov_b32_e32 v66, v0
	v_mov_b32_e32 v67, v0
	v_mov_b32_e32 v68, v0
	v_mov_b32_e32 v69, v0
	v_mov_b32_e32 v70, v0
	v_mov_b32_e32 v71, v0
	v_mov_b32_e32 v72, v0
	v_mov_b32_e32 v73, v0
	v_mov_b32_e32 v74, v0
	v_mov_b32_e32 v75, v0
	v_mov_b32_e32 v76, v0
	v_mov_b32_e32 v77, v0
	v_mov_b32_e32 v78, v0
	v_mov_b32_e32 v79, v0
	s_mov_b64 s[44:45], 0x4101080
	s_mov_b64 s[46:47], 0x4111080
	s_mov_b64 s[48:49], 0x4121080
	s_mov_b64 s[52:53], 0x4131080
	s_mov_b64 s[54:55], 0x13931080
	s_mov_b64 s[56:57], 0x13941080
	s_mov_b64 s[58:59], 0x13951080
	s_mov_b64 s[60:61], 0x13961080
	s_mov_b32 s39, 0x9000
	v_add_u32_e32 v196, s39, v177
	v_lshl_add_u64 v[192:193], v[86:87], 0, s[12:13]
	v_readfirstlane_b32 s39, v196
	v_add_u32_e32 v197, 0x1000, v196
	v_lshl_add_u64 v[194:195], v[192:193], 0, s[44:45]
	s_mov_b32 m0, s39
	v_readfirstlane_b32 s39, v197
	v_add_u32_e32 v197, 0x2000, v196
	global_load_lds_dwordx4 v[194:195], off
	v_lshl_add_u64 v[194:195], v[192:193], 0, s[46:47]
	s_mov_b32 m0, s39
	v_readfirstlane_b32 s39, v197
	v_add_u32_e32 v197, 0x3000, v196
	global_load_lds_dwordx4 v[194:195], off
	v_lshl_add_u64 v[194:195], v[192:193], 0, s[48:49]
	s_mov_b32 m0, s39
	v_readfirstlane_b32 s39, v197
	global_load_lds_dwordx4 v[194:195], off
	v_lshl_add_u64 v[194:195], v[192:193], 0, s[52:53]
	s_mov_b32 m0, s39
	s_mov_b64 s[40:41], 0x4141080
	global_load_lds_dwordx4 v[194:195], off
	v_add_u32_e32 v194, 0x4000, v196
	v_lshl_add_u64 v[192:193], v[192:193], 0, s[40:41]
	v_readfirstlane_b32 s39, v194
	s_mov_b32 m0, s39
	v_add_u32_e32 v197, 0x5000, v196
	global_load_lds_dwordx4 v[192:193], off
	v_lshl_add_u64 v[192:193], v[88:89], 0, s[12:13]
	v_readfirstlane_b32 s39, v197
	v_add_u32_e32 v197, 0x6000, v196
	v_lshl_add_u64 v[194:195], v[192:193], 0, s[54:55]
	s_mov_b32 m0, s39
	v_readfirstlane_b32 s39, v197
	v_add_u32_e32 v197, 0x7000, v196
	global_load_lds_dwordx4 v[194:195], off
	v_lshl_add_u64 v[194:195], v[192:193], 0, s[56:57]
	s_mov_b32 m0, s39
	v_readfirstlane_b32 s39, v197
	global_load_lds_dwordx4 v[194:195], off
	v_lshl_add_u64 v[194:195], v[192:193], 0, s[58:59]
	s_mov_b32 m0, s39
	v_lshl_add_u64 v[192:193], v[192:193], 0, s[60:61]
	global_load_lds_dwordx4 v[194:195], off
	v_add_u32_e32 v194, 0x8000, v196
	s_nop 0
	v_readfirstlane_b32 s39, v194
	s_mov_b32 m0, s39
	s_nop 0
	global_load_lds_dwordx4 v[192:193], off
	s_waitcnt vmcnt(9) lgkmcnt(0)
	s_barrier
.LBB0_137:
	s_add_i32 s37, s11, 1
	s_bitcmp1_b32 s11, 0
	s_cselect_b32 s11, 0x9000, 0
	s_add_i32 s11, s11, 0
	v_add_u32_e32 v94, s11, v178
	v_add_u32_e32 v95, v94, v179
	ds_read_b128 v[90:93], v95
	ds_read_b128 v[100:103], v95 offset:2048
	ds_read_b128 v[104:107], v95 offset:4096
	ds_read_b128 v[108:111], v95 offset:6144
	v_add_u32_e32 v94, v94, v180
	ds_read_b128 v[112:115], v95 offset:8192
	ds_read_b128 v[116:119], v94 offset:20480
	ds_read_b128 v[120:123], v94 offset:22528
	ds_read_b128 v[124:127], v94 offset:24576
	ds_read_b128 v[128:131], v94 offset:26624
	v_add_u32_e32 v206, s11, v181
	v_add_u32_e32 v207, v206, v179
	ds_read_b128 v[208:211], v207
	ds_read_b128 v[212:215], v207 offset:2048
	ds_read_b128 v[216:219], v207 offset:4096
	ds_read_b128 v[220:223], v207 offset:6144
	v_add_u32_e32 v224, v206, v180
	ds_read_b128 v[226:229], v207 offset:8192
	ds_read_b128 v[230:233], v224 offset:20480
	ds_read_b128 v[234:237], v224 offset:22528
	ds_read_b128 v[238:241], v224 offset:24576
	ds_read_b128 v[242:245], v224 offset:26624
	s_setprio 1
	s_waitcnt lgkmcnt(9)
	v_mfma_f32_16x16x32_bf16 v[76:79], v[116:119], v[90:93], v[76:79]
	v_mfma_f32_16x16x32_bf16 v[72:75], v[120:123], v[90:93], v[72:75]
	v_mfma_f32_16x16x32_bf16 v[68:71], v[124:127], v[90:93], v[68:71]
	v_mfma_f32_16x16x32_bf16 v[64:67], v[128:131], v[90:93], v[64:67]
	v_mfma_f32_16x16x32_bf16 v[60:63], v[116:119], v[100:103], v[60:63]
	v_mfma_f32_16x16x32_bf16 v[56:59], v[120:123], v[100:103], v[56:59]
	v_mfma_f32_16x16x32_bf16 v[52:55], v[124:127], v[100:103], v[52:55]
	v_mfma_f32_16x16x32_bf16 v[48:51], v[128:131], v[100:103], v[48:51]
	v_mfma_f32_16x16x32_bf16 v[44:47], v[116:119], v[104:107], v[44:47]
	v_mfma_f32_16x16x32_bf16 v[40:43], v[120:123], v[104:107], v[40:43]
	v_mfma_f32_16x16x32_bf16 v[36:39], v[124:127], v[104:107], v[36:39]
	v_mfma_f32_16x16x32_bf16 v[32:35], v[128:131], v[104:107], v[32:35]
	v_mfma_f32_16x16x32_bf16 v[28:31], v[116:119], v[108:111], v[28:31]
	v_mfma_f32_16x16x32_bf16 v[24:27], v[120:123], v[108:111], v[24:27]
	v_mfma_f32_16x16x32_bf16 v[20:23], v[124:127], v[108:111], v[20:23]
	v_mfma_f32_16x16x32_bf16 v[16:19], v[128:131], v[108:111], v[16:19]
	v_mfma_f32_16x16x32_bf16 v[12:15], v[116:119], v[112:115], v[12:15]
	v_mfma_f32_16x16x32_bf16 v[8:11], v[120:123], v[112:115], v[8:11]
	v_mfma_f32_16x16x32_bf16 v[4:7], v[124:127], v[112:115], v[4:7]
	v_mfma_f32_16x16x32_bf16 v[0:3], v[128:131], v[112:115], v[0:3]
	s_setprio 0
	s_setprio 1
	s_waitcnt lgkmcnt(0)
	s_setprio 0
	s_barrier
	s_add_u32 s12, s12, 0x80
	s_addc_u32 s13, s13, 0
	s_mov_b32 s39, s11
	v_add_u32_e32 v196, s39, v177
	v_lshl_add_u64 v[192:193], v[86:87], 0, s[12:13]
	v_readfirstlane_b32 s39, v196
	v_add_u32_e32 v197, 0x1000, v196
	v_lshl_add_u64 v[194:195], v[192:193], 0, s[44:45]
	s_mov_b32 m0, s39
	v_readfirstlane_b32 s39, v197
	v_add_u32_e32 v197, 0x2000, v196
	global_load_lds_dwordx4 v[194:195], off
	v_lshl_add_u64 v[194:195], v[192:193], 0, s[46:47]
	s_mov_b32 m0, s39
	v_readfirstlane_b32 s39, v197
	v_add_u32_e32 v197, 0x3000, v196
	global_load_lds_dwordx4 v[194:195], off
	v_lshl_add_u64 v[194:195], v[192:193], 0, s[48:49]
	s_mov_b32 m0, s39
	v_readfirstlane_b32 s39, v197
	global_load_lds_dwordx4 v[194:195], off
	v_lshl_add_u64 v[194:195], v[192:193], 0, s[52:53]
	s_mov_b32 m0, s39
	s_mov_b64 s[40:41], 0x4141080
	global_load_lds_dwordx4 v[194:195], off
	v_add_u32_e32 v194, 0x4000, v196
	v_lshl_add_u64 v[192:193], v[192:193], 0, s[40:41]
	v_readfirstlane_b32 s39, v194
	s_mov_b32 m0, s39
	v_add_u32_e32 v197, 0x5000, v196
	global_load_lds_dwordx4 v[192:193], off
	v_lshl_add_u64 v[192:193], v[88:89], 0, s[12:13]
	v_readfirstlane_b32 s39, v197
	v_add_u32_e32 v197, 0x6000, v196
	v_lshl_add_u64 v[194:195], v[192:193], 0, s[54:55]
	s_mov_b32 m0, s39
	v_readfirstlane_b32 s39, v197
	v_add_u32_e32 v197, 0x7000, v196
	global_load_lds_dwordx4 v[194:195], off
	v_lshl_add_u64 v[194:195], v[192:193], 0, s[56:57]
	s_mov_b32 m0, s39
	v_readfirstlane_b32 s39, v197
	global_load_lds_dwordx4 v[194:195], off
	v_lshl_add_u64 v[194:195], v[192:193], 0, s[58:59]
	s_mov_b32 m0, s39
	v_lshl_add_u64 v[192:193], v[192:193], 0, s[60:61]
	global_load_lds_dwordx4 v[194:195], off
	v_add_u32_e32 v194, 0x8000, v196
	s_nop 0
	v_readfirstlane_b32 s39, v194
	s_mov_b32 m0, s39
	s_nop 0
	global_load_lds_dwordx4 v[192:193], off
	s_setprio 1
	v_mfma_f32_16x16x32_bf16 v[76:79], v[230:233], v[208:211], v[76:79]
	v_mfma_f32_16x16x32_bf16 v[72:75], v[234:237], v[208:211], v[72:75]
	v_mfma_f32_16x16x32_bf16 v[68:71], v[238:241], v[208:211], v[68:71]
	v_mfma_f32_16x16x32_bf16 v[64:67], v[242:245], v[208:211], v[64:67]
	v_mfma_f32_16x16x32_bf16 v[60:63], v[230:233], v[212:215], v[60:63]
	v_mfma_f32_16x16x32_bf16 v[56:59], v[234:237], v[212:215], v[56:59]
	v_mfma_f32_16x16x32_bf16 v[52:55], v[238:241], v[212:215], v[52:55]
	v_mfma_f32_16x16x32_bf16 v[48:51], v[242:245], v[212:215], v[48:51]
	v_mfma_f32_16x16x32_bf16 v[44:47], v[230:233], v[216:219], v[44:47]
	v_mfma_f32_16x16x32_bf16 v[40:43], v[234:237], v[216:219], v[40:43]
	v_mfma_f32_16x16x32_bf16 v[36:39], v[238:241], v[216:219], v[36:39]
	v_mfma_f32_16x16x32_bf16 v[32:35], v[242:245], v[216:219], v[32:35]
	v_mfma_f32_16x16x32_bf16 v[28:31], v[230:233], v[220:223], v[28:31]
	v_mfma_f32_16x16x32_bf16 v[24:27], v[234:237], v[220:223], v[24:27]
	v_mfma_f32_16x16x32_bf16 v[20:23], v[238:241], v[220:223], v[20:23]
	v_mfma_f32_16x16x32_bf16 v[16:19], v[242:245], v[220:223], v[16:19]
	v_mfma_f32_16x16x32_bf16 v[12:15], v[230:233], v[226:229], v[12:15]
	v_mfma_f32_16x16x32_bf16 v[8:11], v[234:237], v[226:229], v[8:11]
	v_mfma_f32_16x16x32_bf16 v[4:7], v[238:241], v[226:229], v[4:7]
	v_mfma_f32_16x16x32_bf16 v[0:3], v[242:245], v[226:229], v[0:3]
	s_setprio 0
	s_cmpk_lg_i32 s12, 0x700
	s_mov_b32 s11, s37
	s_waitcnt vmcnt(9)
	s_barrier
	s_cbranch_scc1 .LBB0_137
	s_add_i32 s37, s11, 1
	s_bitcmp1_b32 s11, 0
	s_cselect_b32 s11, 0x9000, 0
	s_add_i32 s11, s11, 0
	v_add_u32_e32 v94, s11, v178
	v_add_u32_e32 v95, v94, v179
	ds_read_b128 v[90:93], v95
	ds_read_b128 v[100:103], v95 offset:2048
	ds_read_b128 v[104:107], v95 offset:4096
	ds_read_b128 v[108:111], v95 offset:6144
	v_add_u32_e32 v94, v94, v180
	ds_read_b128 v[112:115], v95 offset:8192
	ds_read_b128 v[116:119], v94 offset:20480
	ds_read_b128 v[120:123], v94 offset:22528
	ds_read_b128 v[124:127], v94 offset:24576
	ds_read_b128 v[128:131], v94 offset:26624
	v_add_u32_e32 v206, s11, v181
	v_add_u32_e32 v207, v206, v179
	ds_read_b128 v[208:211], v207
	ds_read_b128 v[212:215], v207 offset:2048
	ds_read_b128 v[216:219], v207 offset:4096
	ds_read_b128 v[220:223], v207 offset:6144
	v_add_u32_e32 v224, v206, v180
	ds_read_b128 v[226:229], v207 offset:8192
	ds_read_b128 v[230:233], v224 offset:20480
	ds_read_b128 v[234:237], v224 offset:22528
	ds_read_b128 v[238:241], v224 offset:24576
	ds_read_b128 v[242:245], v224 offset:26624
	s_setprio 1
	s_waitcnt lgkmcnt(9)
	v_mfma_f32_16x16x32_bf16 v[76:79], v[116:119], v[90:93], v[76:79]
	v_mfma_f32_16x16x32_bf16 v[72:75], v[120:123], v[90:93], v[72:75]
	v_mfma_f32_16x16x32_bf16 v[68:71], v[124:127], v[90:93], v[68:71]
	v_mfma_f32_16x16x32_bf16 v[64:67], v[128:131], v[90:93], v[64:67]
	v_mfma_f32_16x16x32_bf16 v[60:63], v[116:119], v[100:103], v[60:63]
	v_mfma_f32_16x16x32_bf16 v[56:59], v[120:123], v[100:103], v[56:59]
	v_mfma_f32_16x16x32_bf16 v[52:55], v[124:127], v[100:103], v[52:55]
	v_mfma_f32_16x16x32_bf16 v[48:51], v[128:131], v[100:103], v[48:51]
	v_mfma_f32_16x16x32_bf16 v[44:47], v[116:119], v[104:107], v[44:47]
	v_mfma_f32_16x16x32_bf16 v[40:43], v[120:123], v[104:107], v[40:43]
	v_mfma_f32_16x16x32_bf16 v[36:39], v[124:127], v[104:107], v[36:39]
	v_mfma_f32_16x16x32_bf16 v[32:35], v[128:131], v[104:107], v[32:35]
	v_mfma_f32_16x16x32_bf16 v[28:31], v[116:119], v[108:111], v[28:31]
	v_mfma_f32_16x16x32_bf16 v[24:27], v[120:123], v[108:111], v[24:27]
	v_mfma_f32_16x16x32_bf16 v[20:23], v[124:127], v[108:111], v[20:23]
	v_mfma_f32_16x16x32_bf16 v[16:19], v[128:131], v[108:111], v[16:19]
	v_mfma_f32_16x16x32_bf16 v[12:15], v[116:119], v[112:115], v[12:15]
	v_mfma_f32_16x16x32_bf16 v[8:11], v[120:123], v[112:115], v[8:11]
	v_mfma_f32_16x16x32_bf16 v[4:7], v[124:127], v[112:115], v[4:7]
	v_mfma_f32_16x16x32_bf16 v[0:3], v[128:131], v[112:115], v[0:3]
	s_setprio 0
	s_setprio 1
	s_waitcnt lgkmcnt(0)
	v_mfma_f32_16x16x32_bf16 v[76:79], v[230:233], v[208:211], v[76:79]
	v_mfma_f32_16x16x32_bf16 v[72:75], v[234:237], v[208:211], v[72:75]
	v_mfma_f32_16x16x32_bf16 v[68:71], v[238:241], v[208:211], v[68:71]
	v_mfma_f32_16x16x32_bf16 v[64:67], v[242:245], v[208:211], v[64:67]
	v_mfma_f32_16x16x32_bf16 v[60:63], v[230:233], v[212:215], v[60:63]
	v_mfma_f32_16x16x32_bf16 v[56:59], v[234:237], v[212:215], v[56:59]
	v_mfma_f32_16x16x32_bf16 v[52:55], v[238:241], v[212:215], v[52:55]
	v_mfma_f32_16x16x32_bf16 v[48:51], v[242:245], v[212:215], v[48:51]
	v_mfma_f32_16x16x32_bf16 v[44:47], v[230:233], v[216:219], v[44:47]
	v_mfma_f32_16x16x32_bf16 v[40:43], v[234:237], v[216:219], v[40:43]
	v_mfma_f32_16x16x32_bf16 v[36:39], v[238:241], v[216:219], v[36:39]
	v_mfma_f32_16x16x32_bf16 v[32:35], v[242:245], v[216:219], v[32:35]
	v_mfma_f32_16x16x32_bf16 v[28:31], v[230:233], v[220:223], v[28:31]
	v_mfma_f32_16x16x32_bf16 v[24:27], v[234:237], v[220:223], v[24:27]
	v_mfma_f32_16x16x32_bf16 v[20:23], v[238:241], v[220:223], v[20:23]
	v_mfma_f32_16x16x32_bf16 v[16:19], v[242:245], v[220:223], v[16:19]
	v_mfma_f32_16x16x32_bf16 v[12:15], v[230:233], v[226:229], v[12:15]
	v_mfma_f32_16x16x32_bf16 v[8:11], v[234:237], v[226:229], v[8:11]
	v_mfma_f32_16x16x32_bf16 v[4:7], v[238:241], v[226:229], v[4:7]
	v_mfma_f32_16x16x32_bf16 v[0:3], v[242:245], v[226:229], v[0:3]
	s_setprio 0
	s_add_u32 s12, s12, 0x80
	s_addc_u32 s13, s13, 0
	s_mov_b32 s11, s37
	s_waitcnt vmcnt(0)
	s_barrier
	v_add_u32_e32 v94, v182, v180
	ds_read_b128 v[86:89], v94 offset:63488
	ds_read_b128 v[90:93], v94 offset:61440
	ds_read_b128 v[100:103], v94 offset:59392
	ds_read_b128 v[104:107], v94 offset:57344
	v_add_u32_e32 v94, v182, v179
	ds_read_b128 v[108:111], v94 offset:45056
	ds_read_b128 v[112:115], v94 offset:43008
	ds_read_b128 v[116:119], v94 offset:40960
	ds_read_b128 v[120:123], v94 offset:38912
	ds_read_b128 v[124:127], v94 offset:36864
	s_setprio 1
	s_waitcnt lgkmcnt(0)
	v_mfma_f32_16x16x32_bf16 v[76:79], v[104:107], v[124:127], v[76:79]
	v_mfma_f32_16x16x32_bf16 v[72:75], v[100:103], v[124:127], v[72:75]
	v_mfma_f32_16x16x32_bf16 v[68:71], v[90:93], v[124:127], v[68:71]
	v_mfma_f32_16x16x32_bf16 v[64:67], v[86:89], v[124:127], v[64:67]
	v_mfma_f32_16x16x32_bf16 v[60:63], v[104:107], v[120:123], v[60:63]
	v_mfma_f32_16x16x32_bf16 v[56:59], v[100:103], v[120:123], v[56:59]
	v_mfma_f32_16x16x32_bf16 v[52:55], v[90:93], v[120:123], v[52:55]
	v_mfma_f32_16x16x32_bf16 v[48:51], v[86:89], v[120:123], v[48:51]
	v_mfma_f32_16x16x32_bf16 v[44:47], v[104:107], v[116:119], v[44:47]
	v_mfma_f32_16x16x32_bf16 v[40:43], v[100:103], v[116:119], v[40:43]
	v_mfma_f32_16x16x32_bf16 v[36:39], v[90:93], v[116:119], v[36:39]
	v_mfma_f32_16x16x32_bf16 v[32:35], v[86:89], v[116:119], v[32:35]
	v_mfma_f32_16x16x32_bf16 v[28:31], v[104:107], v[112:115], v[28:31]
	v_mfma_f32_16x16x32_bf16 v[24:27], v[100:103], v[112:115], v[24:27]
	v_mfma_f32_16x16x32_bf16 v[20:23], v[90:93], v[112:115], v[20:23]
	v_mfma_f32_16x16x32_bf16 v[16:19], v[86:89], v[112:115], v[16:19]
	v_mfma_f32_16x16x32_bf16 v[12:15], v[104:107], v[108:111], v[12:15]
	v_mfma_f32_16x16x32_bf16 v[8:11], v[100:103], v[108:111], v[8:11]
	v_mfma_f32_16x16x32_bf16 v[4:7], v[90:93], v[108:111], v[4:7]
	v_mfma_f32_16x16x32_bf16 v[0:3], v[86:89], v[108:111], v[0:3]
	s_setprio 0
	v_add_u32_e32 v94, v183, v179
	ds_read_b128 v[86:89], v94 offset:36864
	ds_read_b128 v[90:93], v94 offset:38912
	ds_read_b128 v[100:103], v94 offset:40960
	ds_read_b128 v[104:107], v94 offset:43008
	v_add_u32_e32 v95, v183, v180
	ds_read_b128 v[108:111], v94 offset:45056
	ds_read_b128 v[112:115], v95 offset:57344
	ds_read_b128 v[116:119], v95 offset:59392
	ds_read_b128 v[120:123], v95 offset:61440
	ds_read_b128 v[124:127], v95 offset:63488
	s_setprio 1
	s_waitcnt lgkmcnt(3)
	v_mfma_f32_16x16x32_bf16 v[76:79], v[112:115], v[86:89], v[76:79]
	s_waitcnt lgkmcnt(2)
	v_mfma_f32_16x16x32_bf16 v[72:75], v[116:119], v[86:89], v[72:75]
	s_waitcnt lgkmcnt(1)
	v_mfma_f32_16x16x32_bf16 v[68:71], v[120:123], v[86:89], v[68:71]
	s_waitcnt lgkmcnt(0)
	v_mfma_f32_16x16x32_bf16 v[64:67], v[124:127], v[86:89], v[64:67]
	v_mfma_f32_16x16x32_bf16 v[60:63], v[112:115], v[90:93], v[60:63]
	v_mfma_f32_16x16x32_bf16 v[56:59], v[116:119], v[90:93], v[56:59]
	v_mfma_f32_16x16x32_bf16 v[52:55], v[120:123], v[90:93], v[52:55]
	v_mfma_f32_16x16x32_bf16 v[48:51], v[124:127], v[90:93], v[48:51]
	v_mfma_f32_16x16x32_bf16 v[44:47], v[112:115], v[100:103], v[44:47]
	v_mfma_f32_16x16x32_bf16 v[40:43], v[116:119], v[100:103], v[40:43]
	v_mfma_f32_16x16x32_bf16 v[36:39], v[120:123], v[100:103], v[36:39]
	v_mfma_f32_16x16x32_bf16 v[32:35], v[124:127], v[100:103], v[32:35]
	v_mfma_f32_16x16x32_bf16 v[28:31], v[112:115], v[104:107], v[28:31]
	v_mfma_f32_16x16x32_bf16 v[24:27], v[116:119], v[104:107], v[24:27]
	v_mfma_f32_16x16x32_bf16 v[20:23], v[120:123], v[104:107], v[20:23]
	v_mfma_f32_16x16x32_bf16 v[16:19], v[124:127], v[104:107], v[16:19]
	v_mfma_f32_16x16x32_bf16 v[12:15], v[112:115], v[108:111], v[12:15]
	v_mfma_f32_16x16x32_bf16 v[8:11], v[116:119], v[108:111], v[8:11]
	v_mfma_f32_16x16x32_bf16 v[4:7], v[120:123], v[108:111], v[4:7]
	v_mfma_f32_16x16x32_bf16 v[0:3], v[124:127], v[108:111], v[0:3]
	s_setprio 0
	v_mov_b32_e32 v86, v97
	s_waitcnt vmcnt(0)
	s_barrier
	s_mulk_i32 s38, 0xa0
	v_add_u32_e32 v87, v86, v176
	v_ashrrev_i32_e32 v88, 7, v87
	v_and_or_b32 v86, v87, 15, s38
	s_movk_i32 s11, 0x50
	v_mad_u64_u32 v[88:89], s[12:13], v88, s11, v[86:87]
	s_lshl_b32 s10, s10, 7
	v_lshrrev_b32_e32 v86, 2, v87
	v_and_b32_e32 v92, 64, v87
	s_and_b32 s11, s10, 0x380
	v_and_b32_e32 v89, 12, v86
	v_or3_b32 v158, v92, s11, v89
	v_cmp_lt_i32_e32 vcc, v140, v138
	s_ashr_i32 s11, s10, 31
	s_lshl_b64 s[10:11], s[10:11], 1
	v_cndmask_b32_e32 v86, v137, v140, vcc
	v_cmp_lt_i32_e32 vcc, v139, v138
	v_lshlrev_b32_e32 v184, 2, v86
	s_add_u32 s10, s34, s10
	v_cndmask_b32_e32 v86, v137, v139, vcc
	v_lshlrev_b32_e32 v185, 2, v86
	s_addc_u32 s11, s35, s11
	v_lshlrev_b32_e32 v86, 1, v92
	v_mov_b32_e32 v87, v97
	s_mov_b32 s37, 0
	v_lshlrev_b32_e32 v96, 1, v158
	v_lshl_add_u64 v[86:87], s[10:11], 0, v[86:87]
	v_lshlrev_b32_e32 v92, 1, v89
	v_mov_b32_e32 v93, v97
	v_lshl_add_u64 v[90:91], s[6:7], 0, v[96:97]
	v_lshl_add_u64 v[86:87], v[86:87], 0, v[92:93]
	v_ashrrev_i32_e32 v89, 31, v88
	v_lshlrev_b64 v[92:93], 11, v[88:89]
	v_lshl_add_u64 v[94:95], v[90:91], 0, v[92:93]
	global_load_dwordx2 v[102:103], v[94:95], off
	global_load_dwordx2 v[100:101], v[94:95], off offset:32
	s_mov_b32 s38, 0x3c800000
	s_mov_b32 s12, 0x800000
	s_movk_i32 s13, 0x3200
	s_waitcnt vmcnt(1)
	v_lshlrev_b32_e32 v132, 16, v102
	s_waitcnt vmcnt(0)
	v_lshlrev_b32_e32 v123, 16, v100
	v_and_b32_e32 v119, 0xffff0000, v100
	v_alignbit_b32 v89, v101, v100, 16
	v_and_b32_e32 v121, 0xffff0000, v101
	global_load_dwordx2 v[100:101], v[94:95], off offset:64
	v_and_b32_e32 v125, 0xffff0000, v89
	v_and_b32_e32 v129, 0xffff0000, v103
	v_and_b32_e32 v130, 0xffff0000, v102
	v_mov_b32_e32 v128, v132
	v_mov_b32_e32 v131, v132
	v_mul_f32_e32 v108, v132, v132
	v_mul_f32_e32 v122, v123, v123
	v_mul_f32_e32 v118, v119, v119
	v_mul_f32_e32 v124, v125, v125
	v_mul_f32_e32 v120, v121, v121
	s_waitcnt vmcnt(0)
	v_lshlrev_b32_e32 v115, 16, v100
	v_and_b32_e32 v111, 0xffff0000, v100
	v_alignbit_b32 v89, v101, v100, 16
	v_and_b32_e32 v113, 0xffff0000, v101
	global_load_dwordx2 v[100:101], v[94:95], off offset:96
	v_and_b32_e32 v117, 0xffff0000, v89
	v_mul_f32_e32 v114, v115, v115
	v_mul_f32_e32 v110, v111, v111
	v_mul_f32_e32 v116, v117, v117
	v_mul_f32_e32 v112, v113, v113
	s_waitcnt vmcnt(0)
	v_alignbit_b32 v89, v101, v100, 16
	v_and_b32_e32 v107, 0xffff0000, v89
	v_alignbit_b32 v89, v103, v102, 16
	v_and_b32_e32 v103, 0xffff0000, v89
	v_and_b32_e32 v102, 16, v102
	v_mov_b32_e32 v89, v132
	v_pk_add_f32 v[126:127], v[102:103], v[128:129]
	v_pk_add_f32 v[156:157], v[130:131], v[88:89] op_sel_hi:[0,1]
	v_mov_b32_e32 v109, v127
	v_pk_mul_f32 v[126:127], v[130:131], v[130:131]
	v_mov_b32_e32 v128, v103
	v_mul_f32_e32 v102, v129, v129
	v_mov_b32_e32 v133, v103
	v_mov_b32_e32 v127, v157
	v_pk_fma_f32 v[102:103], v[128:129], v[128:129], v[102:103] op_sel_hi:[1,1,0]
	v_pk_add_f32 v[108:109], v[108:109], v[126:127]
	v_mov_b32_e32 v103, v97
	v_pk_add_f32 v[102:103], v[108:109], v[102:103]
	v_pk_add_f32 v[108:109], v[122:123], v[118:119]
	v_pk_add_f32 v[126:127], v[124:125], v[120:121]
	v_lshlrev_b32_e32 v105, 16, v100
	v_pk_add_f32 v[108:109], v[108:109], v[126:127]
	v_and_b32_e32 v95, 0xffff0000, v100
	v_and_b32_e32 v101, 0xffff0000, v101
	v_pk_add_f32 v[102:103], v[102:103], v[108:109]
	v_pk_add_f32 v[108:109], v[114:115], v[110:111]
	v_pk_add_f32 v[126:127], v[116:117], v[112:113]
	v_mul_f32_e32 v104, v105, v105
	v_mul_f32_e32 v94, v95, v95
	v_mul_f32_e32 v106, v107, v107
	v_mul_f32_e32 v100, v101, v101
	v_pk_add_f32 v[108:109], v[108:109], v[126:127]
	v_pk_add_f32 v[126:127], v[106:107], v[100:101]
	v_pk_add_f32 v[102:103], v[102:103], v[108:109]
	v_pk_add_f32 v[108:109], v[104:105], v[94:95]
	v_mul_f32_e32 v100, 0xbfb8aa3b, v76
	v_pk_add_f32 v[108:109], v[108:109], v[126:127]
	v_exp_f32_e32 v186, v100
	v_pk_add_f32 v[102:103], v[102:103], v[108:109]
	s_nop 0
	ds_bpermute_b32 v109, v184, v103
	ds_bpermute_b32 v108, v184, v102
	v_mul_f32_e32 v100, 0xbfb8aa3b, v77
	v_exp_f32_e32 v126, v100
	v_mul_f32_e32 v100, 0xbfb8aa3b, v78
	v_exp_f32_e32 v187, v100
	s_waitcnt lgkmcnt(0)
	v_pk_add_f32 v[102:103], v[102:103], v[108:109]
	s_nop 0
	ds_bpermute_b32 v109, v185, v103
	ds_bpermute_b32 v108, v185, v102
	v_mov_b32_e32 v131, v129
	v_mul_f32_e32 v100, 0xbfb8aa3b, v79
	v_exp_f32_e32 v127, v100
	v_mov_b32_e32 v124, v123
	s_waitcnt lgkmcnt(0)
	v_pk_add_f32 v[102:103], v[102:103], v[108:109]
	v_lshl_add_u64 v[108:109], s[8:9], 0, v[92:93]
	v_pk_mul_f32 v[102:103], v[102:103], s[38:39] op_sel_hi:[1,0]
	v_lshl_add_u64 v[108:109], v[108:109], 0, v[96:97]
	v_fma_f32 v89, -v103, v103, v102
	v_max_f32_e32 v89, 0, v89
	v_add_f32_e32 v89, 0x3a27c5ac, v89
	v_cmp_gt_f32_e32 vcc, s12, v89
	v_mul_f32_e32 v94, 0x4b800000, v89
	v_pk_add_f32 v[132:133], v[132:133], v[102:103] op_sel:[0,1] neg_lo:[0,1] neg_hi:[0,1]
	v_cndmask_b32_e32 v89, v89, v94, vcc
	v_rsq_f32_e32 v89, v89
	v_pk_add_f32 v[128:129], v[130:131], v[102:103] op_sel:[0,1] neg_lo:[0,1] neg_hi:[0,1]
	v_pk_add_f32 v[126:127], v[126:127], 1.0 op_sel_hi:[1,0]
	v_mad_i64_i32 v[92:93], s[10:11], v88, s13, v[86:87]
	v_mul_f32_e32 v94, 0x45800000, v89
	v_cndmask_b32_e32 v94, v89, v94, vcc
	v_lshlrev_b32_e32 v89, 2, v158
	global_load_dwordx4 v[156:159], v89, s[0:1]
	global_load_dwordx4 v[166:169], v89, s[4:5]
	v_pk_mul_f32 v[132:133], v[132:133], v[94:95] op_sel_hi:[1,0]
	v_pk_mul_f32 v[128:129], v[128:129], v[94:95] op_sel_hi:[1,0]
	v_pk_add_f32 v[122:123], v[124:125], v[102:103] op_sel:[0,1] neg_lo:[0,1] neg_hi:[0,1]
	v_mov_b32_e32 v120, v119
	v_pk_mul_f32 v[122:123], v[122:123], v[94:95] op_sel_hi:[1,0]
	v_pk_add_f32 v[118:119], v[120:121], v[102:103] op_sel:[0,1] neg_lo:[0,1] neg_hi:[0,1]
	v_mov_b32_e32 v116, v115
	v_pk_mul_f32 v[118:119], v[118:119], v[94:95] op_sel_hi:[1,0]
	v_pk_add_f32 v[114:115], v[116:117], v[102:103] op_sel:[0,1] neg_lo:[0,1] neg_hi:[0,1]
	s_waitcnt vmcnt(1)
	v_mov_b32_e32 v188, v156
	v_mov_b32_e32 v189, v158
	s_waitcnt vmcnt(0)
	v_mov_b32_e32 v190, v166
	v_mov_b32_e32 v191, v168
	v_pk_fma_f32 v[132:133], v[188:189], v[132:133], v[190:191]
	global_load_dwordx2 v[188:189], v[108:109], off
	v_mov_b32_e32 v158, v157
	v_mov_b32_e32 v168, v167
	v_pk_fma_f32 v[128:129], v[158:159], v[128:129], v[168:169]
	v_pk_mul_f32 v[114:115], v[114:115], v[94:95] op_sel_hi:[1,0]
	s_waitcnt vmcnt(0)
	v_and_b32_e32 v131, 0xffff0000, v189
	v_and_b32_e32 v130, 0xffff0000, v188
	v_pk_add_f32 v[128:129], v[128:129], v[130:131]
	v_pk_add_f32 v[130:131], v[186:187], 1.0 op_sel_hi:[1,0]
	v_lshlrev_b32_e32 v191, 16, v189
	v_lshlrev_b32_e32 v190, 16, v188
	v_pk_add_f32 v[132:133], v[132:133], v[190:191]
	v_rcp_f32_e32 v100, v131
	s_nop 0
	v_mul_f32_e32 v131, v78, v100
	s_nop 0
	v_rcp_f32_e32 v78, v130
	s_nop 0
	v_mul_f32_e32 v130, v76, v78
	v_pk_mul_f32 v[130:131], v[130:131], v[132:133]
	v_rcp_f32_e32 v76, v127
	s_nop 0
	v_mul_f32_e32 v79, v79, v76
	s_nop 0
	v_rcp_f32_e32 v76, v126
	s_nop 0
	v_mul_f32_e32 v78, v77, v76
	v_pk_mul_f32 v[76:77], v[78:79], v[128:129]
	v_and_b32_sdwa v78, v131, v154 dst_sel:DWORD dst_unused:UNUSED_PAD src0_sel:WORD_1 src1_sel:DWORD
	v_and_b32_sdwa v100, v77, v154 dst_sel:DWORD dst_unused:UNUSED_PAD src0_sel:WORD_1 src1_sel:DWORD
	v_and_b32_sdwa v104, v76, v154 dst_sel:DWORD dst_unused:UNUSED_PAD src0_sel:WORD_1 src1_sel:DWORD
	v_and_b32_sdwa v79, v130, v154 dst_sel:DWORD dst_unused:UNUSED_PAD src0_sel:WORD_1 src1_sel:DWORD
	v_add3_u32 v77, v77, v100, s33
	v_add3_u32 v76, v76, v104, s33
	v_add3_u32 v79, v130, v79, s33
	v_add3_u32 v78, v131, v78, s33
	v_and_b32_e32 v77, 0xffff0000, v77
	v_and_b32_e32 v76, 0xffff0000, v76
	v_or_b32_sdwa v77, v77, v78 dst_sel:DWORD dst_unused:UNUSED_PAD src0_sel:DWORD src1_sel:WORD_1
	v_or_b32_sdwa v76, v76, v79 dst_sel:DWORD dst_unused:UNUSED_PAD src0_sel:DWORD src1_sel:WORD_1
	global_store_dwordx2 v[92:93], v[76:77], off
	global_load_dwordx4 v[126:129], v89, s[0:1] offset:64
	global_load_dwordx4 v[130:133], v89, s[4:5] offset:64
	v_mul_f32_e32 v76, 0xbfb8aa3b, v72
	v_mul_f32_e32 v77, 0xbfb8aa3b, v74
	v_exp_f32_e32 v78, v76
	v_exp_f32_e32 v79, v77
	v_mul_f32_e32 v76, 0xbfb8aa3b, v73
	v_mul_f32_e32 v77, 0xbfb8aa3b, v75
	v_exp_f32_e32 v76, v76
	v_pk_add_f32 v[78:79], v[78:79], 1.0 op_sel_hi:[1,0]
	v_exp_f32_e32 v77, v77
	s_nop 0
	v_pk_add_f32 v[76:77], v[76:77], 1.0 op_sel_hi:[1,0]
	v_rcp_f32_e32 v100, v79
	s_nop 0
	v_mul_f32_e32 v79, v74, v100
	v_mov_b32_e32 v112, v111
	v_rcp_f32_e32 v74, v78
	s_nop 0
	v_mul_f32_e32 v78, v72, v74
	v_pk_add_f32 v[110:111], v[112:113], v[102:103] op_sel:[0,1] neg_lo:[0,1] neg_hi:[0,1]
	v_rcp_f32_e32 v72, v77
	s_nop 0
	v_mul_f32_e32 v75, v75, v72
	v_pk_mul_f32 v[110:111], v[110:111], v[94:95] op_sel_hi:[1,0]
	v_rcp_f32_e32 v72, v76
	s_nop 0
	v_mul_f32_e32 v74, v73, v72
	s_waitcnt vmcnt(1)
	v_mov_b32_e32 v124, v126
	v_mov_b32_e32 v125, v128
	s_waitcnt vmcnt(0)
	v_mov_b32_e32 v156, v130
	v_mov_b32_e32 v157, v132
	v_pk_fma_f32 v[122:123], v[122:123], v[124:125], v[156:157]
	global_load_dwordx2 v[124:125], v[108:109], off offset:32
	v_mov_b32_e32 v128, v127
	v_mov_b32_e32 v132, v131
	v_pk_fma_f32 v[118:119], v[118:119], v[128:129], v[132:133]
	s_waitcnt vmcnt(0)
	v_and_b32_e32 v121, 0xffff0000, v125
	v_and_b32_e32 v120, 0xffff0000, v124
	v_lshlrev_b32_e32 v157, 16, v125
	v_lshlrev_b32_e32 v156, 16, v124
	v_pk_add_f32 v[118:119], v[118:119], v[120:121]
	v_pk_add_f32 v[122:123], v[122:123], v[156:157]
	v_pk_mul_f32 v[72:73], v[74:75], v[118:119]
	v_pk_mul_f32 v[78:79], v[78:79], v[122:123]
	v_and_b32_sdwa v76, v73, v154 dst_sel:DWORD dst_unused:UNUSED_PAD src0_sel:WORD_1 src1_sel:DWORD
	v_and_b32_sdwa v77, v72, v154 dst_sel:DWORD dst_unused:UNUSED_PAD src0_sel:WORD_1 src1_sel:DWORD
	v_and_b32_sdwa v74, v79, v154 dst_sel:DWORD dst_unused:UNUSED_PAD src0_sel:WORD_1 src1_sel:DWORD
	v_and_b32_sdwa v75, v78, v154 dst_sel:DWORD dst_unused:UNUSED_PAD src0_sel:WORD_1 src1_sel:DWORD
	v_add3_u32 v73, v73, v76, s33
	v_add3_u32 v72, v72, v77, s33
	v_add3_u32 v75, v78, v75, s33
	v_add3_u32 v74, v79, v74, s33
	v_and_b32_e32 v73, 0xffff0000, v73
	v_and_b32_e32 v72, 0xffff0000, v72
	v_or_b32_sdwa v73, v73, v74 dst_sel:DWORD dst_unused:UNUSED_PAD src0_sel:DWORD src1_sel:WORD_1
	v_or_b32_sdwa v72, v72, v75 dst_sel:DWORD dst_unused:UNUSED_PAD src0_sel:DWORD src1_sel:WORD_1
	global_store_dwordx2 v[92:93], v[72:73], off offset:32
	global_load_dwordx4 v[74:77], v89, s[0:1] offset:128
	global_load_dwordx4 v[118:121], v89, s[4:5] offset:128
	v_mul_f32_e32 v72, 0xbfb8aa3b, v68
	v_mul_f32_e32 v73, 0xbfb8aa3b, v70
	v_exp_f32_e32 v78, v72
	v_exp_f32_e32 v79, v73
	v_mul_f32_e32 v72, 0xbfb8aa3b, v69
	v_mul_f32_e32 v73, 0xbfb8aa3b, v71
	v_exp_f32_e32 v72, v72
	v_exp_f32_e32 v73, v73
	s_waitcnt vmcnt(1)
	v_mov_b32_e32 v116, v74
	v_mov_b32_e32 v117, v76
	s_waitcnt vmcnt(0)
	v_mov_b32_e32 v122, v118
	v_mov_b32_e32 v123, v120
	v_pk_fma_f32 v[114:115], v[114:115], v[116:117], v[122:123]
	global_load_dwordx2 v[116:117], v[108:109], off offset:64
	v_mov_b32_e32 v76, v75
	v_mov_b32_e32 v120, v119
	v_pk_fma_f32 v[74:75], v[110:111], v[76:77], v[120:121]
	v_pk_add_f32 v[72:73], v[72:73], 1.0 op_sel_hi:[1,0]
	s_waitcnt vmcnt(0)
	v_and_b32_e32 v77, 0xffff0000, v117
	v_and_b32_e32 v76, 0xffff0000, v116
	v_pk_add_f32 v[74:75], v[74:75], v[76:77]
	v_pk_add_f32 v[76:77], v[78:79], 1.0 op_sel_hi:[1,0]
	v_lshlrev_b32_e32 v123, 16, v117
	v_lshlrev_b32_e32 v122, 16, v116
	v_pk_add_f32 v[114:115], v[114:115], v[122:123]
	v_rcp_f32_e32 v78, v77
	s_nop 0
	v_mul_f32_e32 v77, v70, v78
	v_mov_b32_e32 v106, v105
	v_rcp_f32_e32 v70, v76
	s_nop 0
	v_mul_f32_e32 v76, v68, v70
	v_pk_mul_f32 v[76:77], v[76:77], v[114:115]
	v_pk_add_f32 v[104:105], v[106:107], v[102:103] op_sel:[0,1] neg_lo:[0,1] neg_hi:[0,1]
	v_rcp_f32_e32 v68, v73
	s_nop 0
	v_mul_f32_e32 v71, v71, v68
	v_pk_mul_f32 v[104:105], v[104:105], v[94:95] op_sel_hi:[1,0]
	v_mov_b32_e32 v100, v95
	v_pk_add_f32 v[100:101], v[100:101], v[102:103] op_sel:[0,1] neg_lo:[0,1] neg_hi:[0,1]
	v_rcp_f32_e32 v68, v72
	s_nop 0
	v_mul_f32_e32 v70, v69, v68
	v_pk_mul_f32 v[68:69], v[70:71], v[74:75]
	v_and_b32_sdwa v70, v77, v154 dst_sel:DWORD dst_unused:UNUSED_PAD src0_sel:WORD_1 src1_sel:DWORD
	v_and_b32_sdwa v72, v69, v154 dst_sel:DWORD dst_unused:UNUSED_PAD src0_sel:WORD_1 src1_sel:DWORD
	v_and_b32_sdwa v73, v68, v154 dst_sel:DWORD dst_unused:UNUSED_PAD src0_sel:WORD_1 src1_sel:DWORD
	v_and_b32_sdwa v71, v76, v154 dst_sel:DWORD dst_unused:UNUSED_PAD src0_sel:WORD_1 src1_sel:DWORD
	v_add3_u32 v69, v69, v72, s33
	v_add3_u32 v68, v68, v73, s33
	v_add3_u32 v71, v76, v71, s33
	v_add3_u32 v70, v77, v70, s33
	v_and_b32_e32 v69, 0xffff0000, v69
	v_and_b32_e32 v68, 0xffff0000, v68
	v_or_b32_sdwa v69, v69, v70 dst_sel:DWORD dst_unused:UNUSED_PAD src0_sel:DWORD src1_sel:WORD_1
	v_or_b32_sdwa v68, v68, v71 dst_sel:DWORD dst_unused:UNUSED_PAD src0_sel:DWORD src1_sel:WORD_1
	global_store_dwordx2 v[92:93], v[68:69], off offset:64
	global_load_dwordx4 v[70:73], v89, s[0:1] offset:192
	global_load_dwordx4 v[74:77], v89, s[4:5] offset:192
	v_mul_f32_e32 v68, 0xbfb8aa3b, v64
	v_mul_f32_e32 v69, 0xbfb8aa3b, v66
	v_exp_f32_e32 v78, v68
	v_exp_f32_e32 v79, v69
	v_pk_mul_f32 v[94:95], v[100:101], v[94:95] op_sel_hi:[1,0]
	v_mul_f32_e32 v68, 0xbfb8aa3b, v65
	v_mul_f32_e32 v69, 0xbfb8aa3b, v67
	v_exp_f32_e32 v68, v68
	v_exp_f32_e32 v69, v69
	s_waitcnt vmcnt(1)
	v_mov_b32_e32 v106, v70
	v_mov_b32_e32 v107, v72
	s_waitcnt vmcnt(0)
	v_mov_b32_e32 v110, v74
	v_mov_b32_e32 v111, v76
	v_pk_fma_f32 v[104:105], v[104:105], v[106:107], v[110:111]
	global_load_dwordx2 v[106:107], v[108:109], off offset:96
	v_mov_b32_e32 v72, v71
	v_mov_b32_e32 v76, v75
	v_pk_fma_f32 v[70:71], v[94:95], v[72:73], v[76:77]
	v_pk_add_f32 v[68:69], v[68:69], 1.0 op_sel_hi:[1,0]
	s_waitcnt vmcnt(0)
	v_and_b32_e32 v73, 0xffff0000, v107
	v_and_b32_e32 v72, 0xffff0000, v106
	v_pk_add_f32 v[70:71], v[70:71], v[72:73]
	v_pk_add_f32 v[72:73], v[78:79], 1.0 op_sel_hi:[1,0]
	v_lshlrev_b32_e32 v109, 16, v107
	v_lshlrev_b32_e32 v108, 16, v106
	v_pk_add_f32 v[104:105], v[104:105], v[108:109]
	v_rcp_f32_e32 v74, v73
	s_nop 0
	v_mul_f32_e32 v73, v66, v74
	s_nop 0
	v_rcp_f32_e32 v66, v72
	s_nop 0
	v_mul_f32_e32 v72, v64, v66
	v_pk_mul_f32 v[72:73], v[72:73], v[104:105]
	v_rcp_f32_e32 v64, v69
	s_nop 0
	v_mul_f32_e32 v67, v67, v64
	s_nop 0
	v_rcp_f32_e32 v64, v68
	s_nop 0
	v_mul_f32_e32 v66, v65, v64
	v_pk_mul_f32 v[64:65], v[66:67], v[70:71]
	v_and_b32_sdwa v66, v73, v154 dst_sel:DWORD dst_unused:UNUSED_PAD src0_sel:WORD_1 src1_sel:DWORD
	v_and_b32_sdwa v68, v65, v154 dst_sel:DWORD dst_unused:UNUSED_PAD src0_sel:WORD_1 src1_sel:DWORD
	v_and_b32_sdwa v69, v64, v154 dst_sel:DWORD dst_unused:UNUSED_PAD src0_sel:WORD_1 src1_sel:DWORD
	v_and_b32_sdwa v67, v72, v154 dst_sel:DWORD dst_unused:UNUSED_PAD src0_sel:WORD_1 src1_sel:DWORD
	v_add3_u32 v65, v65, v68, s33
	v_add3_u32 v64, v64, v69, s33
	v_add3_u32 v67, v72, v67, s33
	v_add3_u32 v66, v73, v66, s33
	v_and_b32_e32 v65, 0xffff0000, v65
	v_and_b32_e32 v64, 0xffff0000, v64
	v_or_b32_sdwa v65, v65, v66 dst_sel:DWORD dst_unused:UNUSED_PAD src0_sel:DWORD src1_sel:WORD_1
	v_or_b32_sdwa v64, v64, v67 dst_sel:DWORD dst_unused:UNUSED_PAD src0_sel:DWORD src1_sel:WORD_1
	global_store_dwordx2 v[92:93], v[64:65], off offset:96
	v_add_u32_e32 v64, 16, v88
	v_ashrrev_i32_e32 v65, 31, v64
	v_lshlrev_b64 v[76:77], 11, v[64:65]
	v_lshl_add_u64 v[66:67], v[90:91], 0, v[76:77]
	global_load_dwordx2 v[70:71], v[66:67], off
	global_load_dwordx2 v[68:69], v[66:67], off offset:32
	v_lshl_add_u64 v[76:77], s[8:9], 0, v[76:77]
	v_lshl_add_u64 v[76:77], v[76:77], 0, v[96:97]
	s_waitcnt vmcnt(1)
	v_lshlrev_b32_e32 v118, 16, v70
	s_waitcnt vmcnt(0)
	v_lshlrev_b32_e32 v107, 16, v68
	v_and_b32_e32 v103, 0xffff0000, v68
	v_alignbit_b32 v65, v69, v68, 16
	v_and_b32_e32 v105, 0xffff0000, v69
	global_load_dwordx2 v[68:69], v[66:67], off offset:64
	v_and_b32_e32 v109, 0xffff0000, v65
	v_and_b32_e32 v113, 0xffff0000, v71
	v_and_b32_e32 v116, 0xffff0000, v70
	v_mov_b32_e32 v112, v118
	v_mov_b32_e32 v117, v118
	v_mul_f32_e32 v110, v118, v118
	v_mul_f32_e32 v106, v107, v107
	v_mul_f32_e32 v102, v103, v103
	v_mul_f32_e32 v108, v109, v109
	v_mul_f32_e32 v104, v105, v105
	s_waitcnt vmcnt(0)
	v_lshlrev_b32_e32 v95, 16, v68
	v_and_b32_e32 v79, 0xffff0000, v68
	v_alignbit_b32 v65, v69, v68, 16
	v_and_b32_e32 v93, 0xffff0000, v69
	global_load_dwordx2 v[68:69], v[66:67], off offset:96
	v_and_b32_e32 v101, 0xffff0000, v65
	v_mul_f32_e32 v94, v95, v95
	v_mul_f32_e32 v78, v79, v79
	v_mul_f32_e32 v100, v101, v101
	v_mul_f32_e32 v92, v93, v93
	s_waitcnt vmcnt(0)
	v_alignbit_b32 v65, v69, v68, 16
	v_and_b32_e32 v75, 0xffff0000, v65
	v_alignbit_b32 v65, v71, v70, 16
	v_and_b32_e32 v71, 0xffff0000, v65
	v_and_b32_e32 v70, 16, v70
	v_mov_b32_e32 v65, v118
	v_pk_add_f32 v[114:115], v[70:71], v[112:113]
	v_pk_add_f32 v[120:121], v[116:117], v[64:65] op_sel_hi:[0,1]
	v_mov_b32_e32 v111, v115
	v_pk_mul_f32 v[114:115], v[116:117], v[116:117]
	v_mov_b32_e32 v112, v71
	v_mov_b32_e32 v115, v121
	global_load_dwordx4 v[120:123], v89, s[0:1]
	global_load_dwordx4 v[124:127], v89, s[4:5]
	v_mul_f32_e32 v70, v113, v113
	v_mov_b32_e32 v119, v71
	v_pk_fma_f32 v[70:71], v[112:113], v[112:113], v[70:71] op_sel_hi:[1,1,0]
	v_pk_add_f32 v[110:111], v[110:111], v[114:115]
	v_mov_b32_e32 v71, v97
	v_pk_add_f32 v[70:71], v[110:111], v[70:71]
	v_pk_add_f32 v[110:111], v[106:107], v[102:103]
	v_pk_add_f32 v[114:115], v[108:109], v[104:105]
	v_lshlrev_b32_e32 v73, 16, v68
	v_pk_add_f32 v[110:111], v[110:111], v[114:115]
	v_and_b32_e32 v67, 0xffff0000, v68
	v_and_b32_e32 v69, 0xffff0000, v69
	v_pk_add_f32 v[70:71], v[70:71], v[110:111]
	v_pk_add_f32 v[110:111], v[94:95], v[78:79]
	v_pk_add_f32 v[114:115], v[100:101], v[92:93]
	v_mul_f32_e32 v72, v73, v73
	v_mul_f32_e32 v66, v67, v67
	v_mul_f32_e32 v74, v75, v75
	v_mul_f32_e32 v68, v69, v69
	v_pk_add_f32 v[110:111], v[110:111], v[114:115]
	v_pk_add_f32 v[114:115], v[74:75], v[68:69]
	v_pk_add_f32 v[70:71], v[70:71], v[110:111]
	v_pk_add_f32 v[110:111], v[72:73], v[66:67]
	v_mul_f32_e32 v68, 0xbfb8aa3b, v60
	v_pk_add_f32 v[110:111], v[110:111], v[114:115]
	v_exp_f32_e32 v114, v68
	v_pk_add_f32 v[70:71], v[70:71], v[110:111]
	s_nop 0
	ds_bpermute_b32 v111, v184, v71
	ds_bpermute_b32 v110, v184, v70
	v_mul_f32_e32 v68, 0xbfb8aa3b, v61
	v_mov_b32_e32 v117, v113
	v_mov_b32_e32 v108, v107
	v_mov_b32_e32 v104, v103
	s_waitcnt lgkmcnt(0)
	v_pk_add_f32 v[70:71], v[70:71], v[110:111]
	s_nop 0
	ds_bpermute_b32 v111, v185, v71
	ds_bpermute_b32 v110, v185, v70
	v_mov_b32_e32 v100, v95
	s_waitcnt lgkmcnt(0)
	v_pk_add_f32 v[70:71], v[70:71], v[110:111]
	s_nop 0
	v_pk_mul_f32 v[70:71], v[70:71], s[38:39] op_sel_hi:[1,0]
	v_exp_f32_e32 v110, v68
	v_fma_f32 v65, -v71, v71, v70
	v_max_f32_e32 v65, 0, v65
	v_add_f32_e32 v65, 0x3a27c5ac, v65
	v_cmp_gt_f32_e32 vcc, s12, v65
	v_mul_f32_e32 v66, 0x4b800000, v65
	v_pk_add_f32 v[118:119], v[118:119], v[70:71] op_sel:[0,1] neg_lo:[0,1] neg_hi:[0,1]
	v_cndmask_b32_e32 v65, v65, v66, vcc
	v_rsq_f32_e32 v65, v65
	v_mul_f32_e32 v68, 0xbfb8aa3b, v62
	v_exp_f32_e32 v115, v68
	v_mul_f32_e32 v68, 0xbfb8aa3b, v63
	v_mul_f32_e32 v66, 0x45800000, v65
	v_cndmask_b32_e32 v66, v65, v66, vcc
	v_pk_mul_f32 v[118:119], v[118:119], v[66:67] op_sel_hi:[1,0]
	v_pk_add_f32 v[114:115], v[114:115], 1.0 op_sel_hi:[1,0]
	v_exp_f32_e32 v111, v68
	s_nop 0
	v_pk_add_f32 v[110:111], v[110:111], 1.0 op_sel_hi:[1,0]
	v_pk_add_f32 v[112:113], v[116:117], v[70:71] op_sel:[0,1] neg_lo:[0,1] neg_hi:[0,1]
	v_mad_i64_i32 v[64:65], s[10:11], v64, s13, v[86:87]
	v_rcp_f32_e32 v68, v115
	s_nop 0
	v_mul_f32_e32 v115, v62, v68
	s_waitcnt vmcnt(1)
	v_mov_b32_e32 v128, v120
	v_mov_b32_e32 v129, v122
	s_waitcnt vmcnt(0)
	v_mov_b32_e32 v130, v124
	v_mov_b32_e32 v131, v126
	v_pk_fma_f32 v[118:119], v[128:129], v[118:119], v[130:131]
	global_load_dwordx2 v[128:129], v[76:77], off
	v_pk_mul_f32 v[112:113], v[112:113], v[66:67] op_sel_hi:[1,0]
	v_mov_b32_e32 v122, v121
	v_mov_b32_e32 v126, v125
	v_rcp_f32_e32 v62, v114
	s_nop 0
	v_mul_f32_e32 v114, v60, v62
	v_pk_fma_f32 v[112:113], v[122:123], v[112:113], v[126:127]
	v_pk_add_f32 v[106:107], v[108:109], v[70:71] op_sel:[0,1] neg_lo:[0,1] neg_hi:[0,1]
	v_pk_add_f32 v[102:103], v[104:105], v[70:71] op_sel:[0,1] neg_lo:[0,1] neg_hi:[0,1]
	v_rcp_f32_e32 v60, v111
	s_nop 0
	v_mul_f32_e32 v63, v63, v60
	v_pk_mul_f32 v[106:107], v[106:107], v[66:67] op_sel_hi:[1,0]
	v_pk_mul_f32 v[102:103], v[102:103], v[66:67] op_sel_hi:[1,0]
	v_pk_add_f32 v[94:95], v[100:101], v[70:71] op_sel:[0,1] neg_lo:[0,1] neg_hi:[0,1]
	v_rcp_f32_e32 v60, v110
	s_nop 0
	v_mul_f32_e32 v62, v61, v60
	v_pk_mul_f32 v[94:95], v[94:95], v[66:67] op_sel_hi:[1,0]
	s_waitcnt vmcnt(0)
	v_and_b32_e32 v117, 0xffff0000, v129
	v_and_b32_e32 v116, 0xffff0000, v128
	v_lshlrev_b32_e32 v131, 16, v129
	v_lshlrev_b32_e32 v130, 16, v128
	v_pk_add_f32 v[112:113], v[112:113], v[116:117]
	v_pk_add_f32 v[118:119], v[118:119], v[130:131]
	v_pk_mul_f32 v[60:61], v[62:63], v[112:113]
	v_pk_mul_f32 v[114:115], v[114:115], v[118:119]
	v_and_b32_sdwa v68, v61, v154 dst_sel:DWORD dst_unused:UNUSED_PAD src0_sel:WORD_1 src1_sel:DWORD
	v_and_b32_sdwa v72, v60, v154 dst_sel:DWORD dst_unused:UNUSED_PAD src0_sel:WORD_1 src1_sel:DWORD
	v_and_b32_sdwa v62, v115, v154 dst_sel:DWORD dst_unused:UNUSED_PAD src0_sel:WORD_1 src1_sel:DWORD
	v_and_b32_sdwa v63, v114, v154 dst_sel:DWORD dst_unused:UNUSED_PAD src0_sel:WORD_1 src1_sel:DWORD
	v_add3_u32 v61, v61, v68, s33
	v_add3_u32 v60, v60, v72, s33
	v_add3_u32 v63, v114, v63, s33
	v_add3_u32 v62, v115, v62, s33
	v_and_b32_e32 v61, 0xffff0000, v61
	v_and_b32_e32 v60, 0xffff0000, v60
	v_or_b32_sdwa v61, v61, v62 dst_sel:DWORD dst_unused:UNUSED_PAD src0_sel:DWORD src1_sel:WORD_1
	v_or_b32_sdwa v60, v60, v63 dst_sel:DWORD dst_unused:UNUSED_PAD src0_sel:DWORD src1_sel:WORD_1
	global_store_dwordx2 v[64:65], v[60:61], off
	global_load_dwordx4 v[110:113], v89, s[0:1] offset:64
	global_load_dwordx4 v[114:117], v89, s[4:5] offset:64
	v_mul_f32_e32 v60, 0xbfb8aa3b, v56
	v_mul_f32_e32 v61, 0xbfb8aa3b, v58
	v_exp_f32_e32 v62, v60
	v_exp_f32_e32 v63, v61
	v_mul_f32_e32 v60, 0xbfb8aa3b, v57
	v_mul_f32_e32 v61, 0xbfb8aa3b, v59
	v_exp_f32_e32 v60, v60
	v_pk_add_f32 v[62:63], v[62:63], 1.0 op_sel_hi:[1,0]
	v_exp_f32_e32 v61, v61
	s_nop 0
	v_pk_add_f32 v[60:61], v[60:61], 1.0 op_sel_hi:[1,0]
	v_rcp_f32_e32 v68, v63
	s_nop 0
	v_mul_f32_e32 v63, v58, v68
	v_mov_b32_e32 v92, v79
	v_rcp_f32_e32 v58, v62
	s_nop 0
	v_mul_f32_e32 v62, v56, v58
	v_pk_add_f32 v[78:79], v[92:93], v[70:71] op_sel:[0,1] neg_lo:[0,1] neg_hi:[0,1]
	v_rcp_f32_e32 v56, v61
	s_nop 0
	v_mul_f32_e32 v59, v59, v56
	v_pk_mul_f32 v[78:79], v[78:79], v[66:67] op_sel_hi:[1,0]
	v_rcp_f32_e32 v56, v60
	s_nop 0
	v_mul_f32_e32 v58, v57, v56
	s_waitcnt vmcnt(1)
	v_mov_b32_e32 v108, v110
	v_mov_b32_e32 v109, v112
	s_waitcnt vmcnt(0)
	v_mov_b32_e32 v118, v114
	v_mov_b32_e32 v119, v116
	v_pk_fma_f32 v[106:107], v[106:107], v[108:109], v[118:119]
	global_load_dwordx2 v[108:109], v[76:77], off offset:32
	v_mov_b32_e32 v112, v111
	v_mov_b32_e32 v116, v115
	v_pk_fma_f32 v[102:103], v[102:103], v[112:113], v[116:117]
	s_waitcnt vmcnt(0)
	v_and_b32_e32 v105, 0xffff0000, v109
	v_and_b32_e32 v104, 0xffff0000, v108
	v_lshlrev_b32_e32 v119, 16, v109
	v_lshlrev_b32_e32 v118, 16, v108
	v_pk_add_f32 v[102:103], v[102:103], v[104:105]
	v_pk_add_f32 v[106:107], v[106:107], v[118:119]
	v_pk_mul_f32 v[56:57], v[58:59], v[102:103]
	v_pk_mul_f32 v[62:63], v[62:63], v[106:107]
	v_and_b32_sdwa v60, v57, v154 dst_sel:DWORD dst_unused:UNUSED_PAD src0_sel:WORD_1 src1_sel:DWORD
	v_and_b32_sdwa v61, v56, v154 dst_sel:DWORD dst_unused:UNUSED_PAD src0_sel:WORD_1 src1_sel:DWORD
	v_and_b32_sdwa v58, v63, v154 dst_sel:DWORD dst_unused:UNUSED_PAD src0_sel:WORD_1 src1_sel:DWORD
	v_and_b32_sdwa v59, v62, v154 dst_sel:DWORD dst_unused:UNUSED_PAD src0_sel:WORD_1 src1_sel:DWORD
	v_add3_u32 v57, v57, v60, s33
	v_add3_u32 v56, v56, v61, s33
	v_add3_u32 v59, v62, v59, s33
	v_add3_u32 v58, v63, v58, s33
	v_and_b32_e32 v57, 0xffff0000, v57
	v_and_b32_e32 v56, 0xffff0000, v56
	v_or_b32_sdwa v57, v57, v58 dst_sel:DWORD dst_unused:UNUSED_PAD src0_sel:DWORD src1_sel:WORD_1
	v_or_b32_sdwa v56, v56, v59 dst_sel:DWORD dst_unused:UNUSED_PAD src0_sel:DWORD src1_sel:WORD_1
	global_store_dwordx2 v[64:65], v[56:57], off offset:32
	global_load_dwordx4 v[58:61], v89, s[0:1] offset:128
	global_load_dwordx4 v[102:105], v89, s[4:5] offset:128
	v_mul_f32_e32 v56, 0xbfb8aa3b, v52
	v_mul_f32_e32 v57, 0xbfb8aa3b, v54
	v_exp_f32_e32 v62, v56
	v_exp_f32_e32 v63, v57
	v_mul_f32_e32 v56, 0xbfb8aa3b, v53
	v_mul_f32_e32 v57, 0xbfb8aa3b, v55
	v_exp_f32_e32 v56, v56
	v_exp_f32_e32 v57, v57
	s_waitcnt vmcnt(1)
	v_mov_b32_e32 v100, v58
	v_mov_b32_e32 v101, v60
	s_waitcnt vmcnt(0)
	v_mov_b32_e32 v106, v102
	v_mov_b32_e32 v107, v104
	v_pk_fma_f32 v[94:95], v[94:95], v[100:101], v[106:107]
	global_load_dwordx2 v[100:101], v[76:77], off offset:64
	v_mov_b32_e32 v60, v59
	v_mov_b32_e32 v104, v103
	v_pk_fma_f32 v[58:59], v[78:79], v[60:61], v[104:105]
	v_pk_add_f32 v[56:57], v[56:57], 1.0 op_sel_hi:[1,0]
	s_waitcnt vmcnt(0)
	v_and_b32_e32 v61, 0xffff0000, v101
	v_and_b32_e32 v60, 0xffff0000, v100
	v_pk_add_f32 v[58:59], v[58:59], v[60:61]
	v_pk_add_f32 v[60:61], v[62:63], 1.0 op_sel_hi:[1,0]
	v_lshlrev_b32_e32 v107, 16, v101
	v_lshlrev_b32_e32 v106, 16, v100
	v_pk_add_f32 v[94:95], v[94:95], v[106:107]
	v_rcp_f32_e32 v62, v61
	s_nop 0
	v_mul_f32_e32 v61, v54, v62
	v_mov_b32_e32 v74, v73
	v_rcp_f32_e32 v54, v60
	s_nop 0
	v_mul_f32_e32 v60, v52, v54
	v_pk_mul_f32 v[60:61], v[60:61], v[94:95]
	v_pk_add_f32 v[72:73], v[74:75], v[70:71] op_sel:[0,1] neg_lo:[0,1] neg_hi:[0,1]
	v_rcp_f32_e32 v52, v57
	s_nop 0
	v_mul_f32_e32 v55, v55, v52
	v_pk_mul_f32 v[72:73], v[72:73], v[66:67] op_sel_hi:[1,0]
	v_mov_b32_e32 v68, v67
	v_pk_add_f32 v[68:69], v[68:69], v[70:71] op_sel:[0,1] neg_lo:[0,1] neg_hi:[0,1]
	v_rcp_f32_e32 v52, v56
	s_nop 0
	v_mul_f32_e32 v54, v53, v52
	v_pk_mul_f32 v[52:53], v[54:55], v[58:59]
	v_and_b32_sdwa v54, v61, v154 dst_sel:DWORD dst_unused:UNUSED_PAD src0_sel:WORD_1 src1_sel:DWORD
	v_and_b32_sdwa v56, v53, v154 dst_sel:DWORD dst_unused:UNUSED_PAD src0_sel:WORD_1 src1_sel:DWORD
	v_and_b32_sdwa v57, v52, v154 dst_sel:DWORD dst_unused:UNUSED_PAD src0_sel:WORD_1 src1_sel:DWORD
	v_and_b32_sdwa v55, v60, v154 dst_sel:DWORD dst_unused:UNUSED_PAD src0_sel:WORD_1 src1_sel:DWORD
	v_add3_u32 v53, v53, v56, s33
	v_add3_u32 v52, v52, v57, s33
	v_add3_u32 v55, v60, v55, s33
	v_add3_u32 v54, v61, v54, s33
	v_and_b32_e32 v53, 0xffff0000, v53
	v_and_b32_e32 v52, 0xffff0000, v52
	v_or_b32_sdwa v53, v53, v54 dst_sel:DWORD dst_unused:UNUSED_PAD src0_sel:DWORD src1_sel:WORD_1
	v_or_b32_sdwa v52, v52, v55 dst_sel:DWORD dst_unused:UNUSED_PAD src0_sel:DWORD src1_sel:WORD_1
	global_store_dwordx2 v[64:65], v[52:53], off offset:64
	global_load_dwordx4 v[54:57], v89, s[0:1] offset:192
	global_load_dwordx4 v[58:61], v89, s[4:5] offset:192
	v_mul_f32_e32 v52, 0xbfb8aa3b, v48
	v_mul_f32_e32 v53, 0xbfb8aa3b, v50
	v_exp_f32_e32 v62, v52
	v_exp_f32_e32 v63, v53
	v_pk_mul_f32 v[66:67], v[68:69], v[66:67] op_sel_hi:[1,0]
	v_mul_f32_e32 v52, 0xbfb8aa3b, v49
	v_mul_f32_e32 v53, 0xbfb8aa3b, v51
	v_exp_f32_e32 v52, v52
	v_exp_f32_e32 v53, v53
	s_waitcnt vmcnt(1)
	v_mov_b32_e32 v74, v54
	v_mov_b32_e32 v75, v56
	s_waitcnt vmcnt(0)
	v_mov_b32_e32 v78, v58
	v_mov_b32_e32 v79, v60
	v_pk_fma_f32 v[72:73], v[72:73], v[74:75], v[78:79]
	global_load_dwordx2 v[74:75], v[76:77], off offset:96
	v_mov_b32_e32 v56, v55
	v_mov_b32_e32 v60, v59
	v_pk_fma_f32 v[54:55], v[66:67], v[56:57], v[60:61]
	v_pk_add_f32 v[52:53], v[52:53], 1.0 op_sel_hi:[1,0]
	s_waitcnt vmcnt(0)
	v_and_b32_e32 v57, 0xffff0000, v75
	v_and_b32_e32 v56, 0xffff0000, v74
	v_pk_add_f32 v[54:55], v[54:55], v[56:57]
	v_pk_add_f32 v[56:57], v[62:63], 1.0 op_sel_hi:[1,0]
	v_lshlrev_b32_e32 v77, 16, v75
	v_lshlrev_b32_e32 v76, 16, v74
	v_pk_add_f32 v[72:73], v[72:73], v[76:77]
	v_rcp_f32_e32 v58, v57
	s_nop 0
	v_mul_f32_e32 v57, v50, v58
	s_nop 0
	v_rcp_f32_e32 v50, v56
	s_nop 0
	v_mul_f32_e32 v56, v48, v50
	v_pk_mul_f32 v[56:57], v[56:57], v[72:73]
	v_rcp_f32_e32 v48, v53
	s_nop 0
	v_mul_f32_e32 v51, v51, v48
	s_nop 0
	v_rcp_f32_e32 v48, v52
	s_nop 0
	v_mul_f32_e32 v50, v49, v48
	v_pk_mul_f32 v[48:49], v[50:51], v[54:55]
	v_and_b32_sdwa v50, v57, v154 dst_sel:DWORD dst_unused:UNUSED_PAD src0_sel:WORD_1 src1_sel:DWORD
	v_and_b32_sdwa v52, v49, v154 dst_sel:DWORD dst_unused:UNUSED_PAD src0_sel:WORD_1 src1_sel:DWORD
	v_and_b32_sdwa v53, v48, v154 dst_sel:DWORD dst_unused:UNUSED_PAD src0_sel:WORD_1 src1_sel:DWORD
	v_and_b32_sdwa v51, v56, v154 dst_sel:DWORD dst_unused:UNUSED_PAD src0_sel:WORD_1 src1_sel:DWORD
	v_add3_u32 v49, v49, v52, s33
	v_add3_u32 v48, v48, v53, s33
	v_add3_u32 v51, v56, v51, s33
	v_add3_u32 v50, v57, v50, s33
	v_and_b32_e32 v49, 0xffff0000, v49
	v_and_b32_e32 v48, 0xffff0000, v48
	v_or_b32_sdwa v49, v49, v50 dst_sel:DWORD dst_unused:UNUSED_PAD src0_sel:DWORD src1_sel:WORD_1
	v_or_b32_sdwa v48, v48, v51 dst_sel:DWORD dst_unused:UNUSED_PAD src0_sel:DWORD src1_sel:WORD_1
	global_store_dwordx2 v[64:65], v[48:49], off offset:96
	v_add_u32_e32 v48, 32, v88
	v_ashrrev_i32_e32 v49, 31, v48
	v_lshlrev_b64 v[60:61], 11, v[48:49]
	v_lshl_add_u64 v[50:51], v[90:91], 0, v[60:61]
	global_load_dwordx2 v[54:55], v[50:51], off
	global_load_dwordx2 v[52:53], v[50:51], off offset:32
	v_lshl_add_u64 v[60:61], s[8:9], 0, v[60:61]
	v_lshl_add_u64 v[60:61], v[60:61], 0, v[96:97]
	s_waitcnt vmcnt(1)
	v_lshlrev_b32_e32 v102, 16, v54
	s_waitcnt vmcnt(0)
	v_lshlrev_b32_e32 v75, 16, v52
	v_and_b32_e32 v71, 0xffff0000, v52
	v_alignbit_b32 v49, v53, v52, 16
	v_and_b32_e32 v73, 0xffff0000, v53
	global_load_dwordx2 v[52:53], v[50:51], off offset:64
	v_and_b32_e32 v77, 0xffff0000, v49
	v_and_b32_e32 v93, 0xffff0000, v55
	v_and_b32_e32 v100, 0xffff0000, v54
	v_mov_b32_e32 v92, v102
	v_mov_b32_e32 v101, v102
	v_mul_f32_e32 v78, v102, v102
	v_mul_f32_e32 v74, v75, v75
	v_mul_f32_e32 v70, v71, v71
	v_mul_f32_e32 v76, v77, v77
	v_mul_f32_e32 v72, v73, v73
	s_waitcnt vmcnt(0)
	v_lshlrev_b32_e32 v67, 16, v52
	v_and_b32_e32 v63, 0xffff0000, v52
	v_alignbit_b32 v49, v53, v52, 16
	v_and_b32_e32 v65, 0xffff0000, v53
	global_load_dwordx2 v[52:53], v[50:51], off offset:96
	v_and_b32_e32 v69, 0xffff0000, v49
	v_mul_f32_e32 v66, v67, v67
	v_mul_f32_e32 v62, v63, v63
	v_mul_f32_e32 v68, v69, v69
	v_mul_f32_e32 v64, v65, v65
	s_waitcnt vmcnt(0)
	v_alignbit_b32 v49, v53, v52, 16
	v_and_b32_e32 v59, 0xffff0000, v49
	v_alignbit_b32 v49, v55, v54, 16
	v_and_b32_e32 v55, 0xffff0000, v49
	v_and_b32_e32 v54, 16, v54
	v_mov_b32_e32 v49, v102
	v_pk_add_f32 v[94:95], v[54:55], v[92:93]
	v_pk_add_f32 v[104:105], v[100:101], v[48:49] op_sel_hi:[0,1]
	v_mov_b32_e32 v79, v95
	v_pk_mul_f32 v[94:95], v[100:101], v[100:101]
	v_mov_b32_e32 v92, v55
	v_mov_b32_e32 v95, v105
	global_load_dwordx4 v[104:107], v89, s[0:1]
	global_load_dwordx4 v[108:111], v89, s[4:5]
	v_mul_f32_e32 v54, v93, v93
	v_mov_b32_e32 v103, v55
	v_pk_fma_f32 v[54:55], v[92:93], v[92:93], v[54:55] op_sel_hi:[1,1,0]
	v_pk_add_f32 v[78:79], v[78:79], v[94:95]
	v_mov_b32_e32 v55, v97
	v_pk_add_f32 v[54:55], v[78:79], v[54:55]
	v_pk_add_f32 v[78:79], v[74:75], v[70:71]
	v_pk_add_f32 v[94:95], v[76:77], v[72:73]
	v_lshlrev_b32_e32 v57, 16, v52
	v_pk_add_f32 v[78:79], v[78:79], v[94:95]
	v_and_b32_e32 v51, 0xffff0000, v52
	v_and_b32_e32 v53, 0xffff0000, v53
	v_pk_add_f32 v[54:55], v[54:55], v[78:79]
	v_pk_add_f32 v[78:79], v[66:67], v[62:63]
	v_pk_add_f32 v[94:95], v[68:69], v[64:65]
	v_mul_f32_e32 v56, v57, v57
	v_mul_f32_e32 v50, v51, v51
	v_mul_f32_e32 v58, v59, v59
	v_mul_f32_e32 v52, v53, v53
	v_pk_add_f32 v[78:79], v[78:79], v[94:95]
	v_pk_add_f32 v[94:95], v[58:59], v[52:53]
	v_pk_add_f32 v[54:55], v[54:55], v[78:79]
	v_pk_add_f32 v[78:79], v[56:57], v[50:51]
	v_mul_f32_e32 v52, 0xbfb8aa3b, v44
	v_pk_add_f32 v[78:79], v[78:79], v[94:95]
	v_exp_f32_e32 v94, v52
	v_pk_add_f32 v[54:55], v[54:55], v[78:79]
	s_nop 0
	ds_bpermute_b32 v79, v184, v55
	ds_bpermute_b32 v78, v184, v54
	v_mul_f32_e32 v52, 0xbfb8aa3b, v45
	v_mov_b32_e32 v101, v93
	v_mov_b32_e32 v76, v75
	v_mov_b32_e32 v72, v71
	s_waitcnt lgkmcnt(0)
	v_pk_add_f32 v[54:55], v[54:55], v[78:79]
	s_nop 0
	ds_bpermute_b32 v79, v185, v55
	ds_bpermute_b32 v78, v185, v54
	v_mov_b32_e32 v68, v67
	s_waitcnt lgkmcnt(0)
	v_pk_add_f32 v[54:55], v[54:55], v[78:79]
	s_nop 0
	v_pk_mul_f32 v[54:55], v[54:55], s[38:39] op_sel_hi:[1,0]
	v_exp_f32_e32 v78, v52
	v_fma_f32 v49, -v55, v55, v54
	v_max_f32_e32 v49, 0, v49
	v_add_f32_e32 v49, 0x3a27c5ac, v49
	v_cmp_gt_f32_e32 vcc, s12, v49
	v_mul_f32_e32 v50, 0x4b800000, v49
	v_pk_add_f32 v[102:103], v[102:103], v[54:55] op_sel:[0,1] neg_lo:[0,1] neg_hi:[0,1]
	v_cndmask_b32_e32 v49, v49, v50, vcc
	v_rsq_f32_e32 v49, v49
	v_mul_f32_e32 v52, 0xbfb8aa3b, v46
	v_exp_f32_e32 v95, v52
	v_mul_f32_e32 v52, 0xbfb8aa3b, v47
	v_mul_f32_e32 v50, 0x45800000, v49
	v_cndmask_b32_e32 v50, v49, v50, vcc
	v_pk_mul_f32 v[102:103], v[102:103], v[50:51] op_sel_hi:[1,0]
	v_pk_add_f32 v[94:95], v[94:95], 1.0 op_sel_hi:[1,0]
	v_exp_f32_e32 v79, v52
	s_nop 0
	v_pk_add_f32 v[78:79], v[78:79], 1.0 op_sel_hi:[1,0]
	v_pk_add_f32 v[92:93], v[100:101], v[54:55] op_sel:[0,1] neg_lo:[0,1] neg_hi:[0,1]
	v_mad_i64_i32 v[48:49], s[10:11], v48, s13, v[86:87]
	v_rcp_f32_e32 v52, v95
	s_nop 0
	v_mul_f32_e32 v95, v46, v52
	s_waitcnt vmcnt(1)
	v_mov_b32_e32 v112, v104
	v_mov_b32_e32 v113, v106
	s_waitcnt vmcnt(0)
	v_mov_b32_e32 v114, v108
	v_mov_b32_e32 v115, v110
	v_pk_fma_f32 v[102:103], v[112:113], v[102:103], v[114:115]
	global_load_dwordx2 v[112:113], v[60:61], off
	v_pk_mul_f32 v[92:93], v[92:93], v[50:51] op_sel_hi:[1,0]
	v_mov_b32_e32 v106, v105
	v_mov_b32_e32 v110, v109
	v_rcp_f32_e32 v46, v94
	s_nop 0
	v_mul_f32_e32 v94, v44, v46
	v_pk_fma_f32 v[92:93], v[106:107], v[92:93], v[110:111]
	v_pk_add_f32 v[74:75], v[76:77], v[54:55] op_sel:[0,1] neg_lo:[0,1] neg_hi:[0,1]
	v_pk_add_f32 v[70:71], v[72:73], v[54:55] op_sel:[0,1] neg_lo:[0,1] neg_hi:[0,1]
	v_rcp_f32_e32 v44, v79
	s_nop 0
	v_mul_f32_e32 v47, v47, v44
	v_pk_mul_f32 v[74:75], v[74:75], v[50:51] op_sel_hi:[1,0]
	v_pk_mul_f32 v[70:71], v[70:71], v[50:51] op_sel_hi:[1,0]
	v_pk_add_f32 v[66:67], v[68:69], v[54:55] op_sel:[0,1] neg_lo:[0,1] neg_hi:[0,1]
	v_rcp_f32_e32 v44, v78
	s_nop 0
	v_mul_f32_e32 v46, v45, v44
	v_pk_mul_f32 v[66:67], v[66:67], v[50:51] op_sel_hi:[1,0]
	s_waitcnt vmcnt(0)
	v_and_b32_e32 v101, 0xffff0000, v113
	v_and_b32_e32 v100, 0xffff0000, v112
	v_lshlrev_b32_e32 v115, 16, v113
	v_lshlrev_b32_e32 v114, 16, v112
	v_pk_add_f32 v[92:93], v[92:93], v[100:101]
	v_pk_add_f32 v[102:103], v[102:103], v[114:115]
	v_pk_mul_f32 v[44:45], v[46:47], v[92:93]
	v_pk_mul_f32 v[94:95], v[94:95], v[102:103]
	v_and_b32_sdwa v52, v45, v154 dst_sel:DWORD dst_unused:UNUSED_PAD src0_sel:WORD_1 src1_sel:DWORD
	v_and_b32_sdwa v56, v44, v154 dst_sel:DWORD dst_unused:UNUSED_PAD src0_sel:WORD_1 src1_sel:DWORD
	v_and_b32_sdwa v46, v95, v154 dst_sel:DWORD dst_unused:UNUSED_PAD src0_sel:WORD_1 src1_sel:DWORD
	v_and_b32_sdwa v47, v94, v154 dst_sel:DWORD dst_unused:UNUSED_PAD src0_sel:WORD_1 src1_sel:DWORD
	v_add3_u32 v45, v45, v52, s33
	v_add3_u32 v44, v44, v56, s33
	v_add3_u32 v47, v94, v47, s33
	v_add3_u32 v46, v95, v46, s33
	v_and_b32_e32 v45, 0xffff0000, v45
	v_and_b32_e32 v44, 0xffff0000, v44
	v_or_b32_sdwa v45, v45, v46 dst_sel:DWORD dst_unused:UNUSED_PAD src0_sel:DWORD src1_sel:WORD_1
	v_or_b32_sdwa v44, v44, v47 dst_sel:DWORD dst_unused:UNUSED_PAD src0_sel:DWORD src1_sel:WORD_1
	global_store_dwordx2 v[48:49], v[44:45], off
	global_load_dwordx4 v[92:95], v89, s[0:1] offset:64
	global_load_dwordx4 v[100:103], v89, s[4:5] offset:64
	v_mul_f32_e32 v44, 0xbfb8aa3b, v40
	v_mul_f32_e32 v45, 0xbfb8aa3b, v42
	v_exp_f32_e32 v46, v44
	v_exp_f32_e32 v47, v45
	v_mul_f32_e32 v44, 0xbfb8aa3b, v41
	v_mul_f32_e32 v45, 0xbfb8aa3b, v43
	v_exp_f32_e32 v44, v44
	v_pk_add_f32 v[46:47], v[46:47], 1.0 op_sel_hi:[1,0]
	v_exp_f32_e32 v45, v45
	s_nop 0
	v_pk_add_f32 v[44:45], v[44:45], 1.0 op_sel_hi:[1,0]
	v_rcp_f32_e32 v52, v47
	s_nop 0
	v_mul_f32_e32 v47, v42, v52
	v_mov_b32_e32 v64, v63
	v_rcp_f32_e32 v42, v46
	s_nop 0
	v_mul_f32_e32 v46, v40, v42
	v_pk_add_f32 v[62:63], v[64:65], v[54:55] op_sel:[0,1] neg_lo:[0,1] neg_hi:[0,1]
	v_rcp_f32_e32 v40, v45
	s_nop 0
	v_mul_f32_e32 v43, v43, v40
	v_pk_mul_f32 v[62:63], v[62:63], v[50:51] op_sel_hi:[1,0]
	v_rcp_f32_e32 v40, v44
	s_nop 0
	v_mul_f32_e32 v42, v41, v40
	s_waitcnt vmcnt(1)
	v_mov_b32_e32 v76, v92
	v_mov_b32_e32 v77, v94
	s_waitcnt vmcnt(0)
	v_mov_b32_e32 v78, v100
	v_mov_b32_e32 v79, v102
	v_pk_fma_f32 v[74:75], v[74:75], v[76:77], v[78:79]
	global_load_dwordx2 v[76:77], v[60:61], off offset:32
	v_mov_b32_e32 v94, v93
	v_mov_b32_e32 v102, v101
	v_pk_fma_f32 v[70:71], v[70:71], v[94:95], v[102:103]
	s_waitcnt vmcnt(0)
	v_and_b32_e32 v73, 0xffff0000, v77
	v_and_b32_e32 v72, 0xffff0000, v76
	v_lshlrev_b32_e32 v79, 16, v77
	v_lshlrev_b32_e32 v78, 16, v76
	v_pk_add_f32 v[70:71], v[70:71], v[72:73]
	v_pk_add_f32 v[74:75], v[74:75], v[78:79]
	v_pk_mul_f32 v[40:41], v[42:43], v[70:71]
	v_pk_mul_f32 v[46:47], v[46:47], v[74:75]
	v_and_b32_sdwa v44, v41, v154 dst_sel:DWORD dst_unused:UNUSED_PAD src0_sel:WORD_1 src1_sel:DWORD
	v_and_b32_sdwa v45, v40, v154 dst_sel:DWORD dst_unused:UNUSED_PAD src0_sel:WORD_1 src1_sel:DWORD
	v_and_b32_sdwa v42, v47, v154 dst_sel:DWORD dst_unused:UNUSED_PAD src0_sel:WORD_1 src1_sel:DWORD
	v_and_b32_sdwa v43, v46, v154 dst_sel:DWORD dst_unused:UNUSED_PAD src0_sel:WORD_1 src1_sel:DWORD
	v_add3_u32 v41, v41, v44, s33
	v_add3_u32 v40, v40, v45, s33
	v_add3_u32 v43, v46, v43, s33
	v_add3_u32 v42, v47, v42, s33
	v_and_b32_e32 v41, 0xffff0000, v41
	v_and_b32_e32 v40, 0xffff0000, v40
	v_or_b32_sdwa v41, v41, v42 dst_sel:DWORD dst_unused:UNUSED_PAD src0_sel:DWORD src1_sel:WORD_1
	v_or_b32_sdwa v40, v40, v43 dst_sel:DWORD dst_unused:UNUSED_PAD src0_sel:DWORD src1_sel:WORD_1
	global_store_dwordx2 v[48:49], v[40:41], off offset:32
	global_load_dwordx4 v[42:45], v89, s[0:1] offset:128
	global_load_dwordx4 v[70:73], v89, s[4:5] offset:128
	v_mul_f32_e32 v40, 0xbfb8aa3b, v36
	v_mul_f32_e32 v41, 0xbfb8aa3b, v38
	v_exp_f32_e32 v46, v40
	v_exp_f32_e32 v47, v41
	v_mul_f32_e32 v40, 0xbfb8aa3b, v37
	v_mul_f32_e32 v41, 0xbfb8aa3b, v39
	v_exp_f32_e32 v40, v40
	v_exp_f32_e32 v41, v41
	s_waitcnt vmcnt(1)
	v_mov_b32_e32 v68, v42
	v_mov_b32_e32 v69, v44
	s_waitcnt vmcnt(0)
	v_mov_b32_e32 v74, v70
	v_mov_b32_e32 v75, v72
	v_pk_fma_f32 v[66:67], v[66:67], v[68:69], v[74:75]
	global_load_dwordx2 v[68:69], v[60:61], off offset:64
	v_mov_b32_e32 v44, v43
	v_mov_b32_e32 v72, v71
	v_pk_fma_f32 v[42:43], v[62:63], v[44:45], v[72:73]
	v_pk_add_f32 v[40:41], v[40:41], 1.0 op_sel_hi:[1,0]
	s_waitcnt vmcnt(0)
	v_and_b32_e32 v45, 0xffff0000, v69
	v_and_b32_e32 v44, 0xffff0000, v68
	v_pk_add_f32 v[42:43], v[42:43], v[44:45]
	v_pk_add_f32 v[44:45], v[46:47], 1.0 op_sel_hi:[1,0]
	v_lshlrev_b32_e32 v75, 16, v69
	v_lshlrev_b32_e32 v74, 16, v68
	v_pk_add_f32 v[66:67], v[66:67], v[74:75]
	v_rcp_f32_e32 v46, v45
	s_nop 0
	v_mul_f32_e32 v45, v38, v46
	v_mov_b32_e32 v58, v57
	v_rcp_f32_e32 v38, v44
	s_nop 0
	v_mul_f32_e32 v44, v36, v38
	v_pk_mul_f32 v[44:45], v[44:45], v[66:67]
	v_pk_add_f32 v[56:57], v[58:59], v[54:55] op_sel:[0,1] neg_lo:[0,1] neg_hi:[0,1]
	v_rcp_f32_e32 v36, v41
	s_nop 0
	v_mul_f32_e32 v39, v39, v36
	v_pk_mul_f32 v[56:57], v[56:57], v[50:51] op_sel_hi:[1,0]
	v_mov_b32_e32 v52, v51
	v_pk_add_f32 v[52:53], v[52:53], v[54:55] op_sel:[0,1] neg_lo:[0,1] neg_hi:[0,1]
	v_rcp_f32_e32 v36, v40
	s_nop 0
	v_mul_f32_e32 v38, v37, v36
	v_pk_mul_f32 v[36:37], v[38:39], v[42:43]
	v_and_b32_sdwa v38, v45, v154 dst_sel:DWORD dst_unused:UNUSED_PAD src0_sel:WORD_1 src1_sel:DWORD
	v_and_b32_sdwa v40, v37, v154 dst_sel:DWORD dst_unused:UNUSED_PAD src0_sel:WORD_1 src1_sel:DWORD
	v_and_b32_sdwa v41, v36, v154 dst_sel:DWORD dst_unused:UNUSED_PAD src0_sel:WORD_1 src1_sel:DWORD
	v_and_b32_sdwa v39, v44, v154 dst_sel:DWORD dst_unused:UNUSED_PAD src0_sel:WORD_1 src1_sel:DWORD
	v_add3_u32 v37, v37, v40, s33
	v_add3_u32 v36, v36, v41, s33
	v_add3_u32 v39, v44, v39, s33
	v_add3_u32 v38, v45, v38, s33
	v_and_b32_e32 v37, 0xffff0000, v37
	v_and_b32_e32 v36, 0xffff0000, v36
	v_or_b32_sdwa v37, v37, v38 dst_sel:DWORD dst_unused:UNUSED_PAD src0_sel:DWORD src1_sel:WORD_1
	v_or_b32_sdwa v36, v36, v39 dst_sel:DWORD dst_unused:UNUSED_PAD src0_sel:DWORD src1_sel:WORD_1
	global_store_dwordx2 v[48:49], v[36:37], off offset:64
	global_load_dwordx4 v[38:41], v89, s[0:1] offset:192
	global_load_dwordx4 v[42:45], v89, s[4:5] offset:192
	v_mul_f32_e32 v36, 0xbfb8aa3b, v32
	v_mul_f32_e32 v37, 0xbfb8aa3b, v34
	v_exp_f32_e32 v46, v36
	v_exp_f32_e32 v47, v37
	v_pk_mul_f32 v[50:51], v[52:53], v[50:51] op_sel_hi:[1,0]
	v_mul_f32_e32 v36, 0xbfb8aa3b, v33
	v_mul_f32_e32 v37, 0xbfb8aa3b, v35
	v_exp_f32_e32 v36, v36
	v_exp_f32_e32 v37, v37
	s_waitcnt vmcnt(1)
	v_mov_b32_e32 v58, v38
	v_mov_b32_e32 v59, v40
	s_waitcnt vmcnt(0)
	v_mov_b32_e32 v62, v42
	v_mov_b32_e32 v63, v44
	v_pk_fma_f32 v[56:57], v[56:57], v[58:59], v[62:63]
	global_load_dwordx2 v[58:59], v[60:61], off offset:96
	v_mov_b32_e32 v40, v39
	v_mov_b32_e32 v44, v43
	v_pk_fma_f32 v[38:39], v[50:51], v[40:41], v[44:45]
	v_pk_add_f32 v[36:37], v[36:37], 1.0 op_sel_hi:[1,0]
	s_waitcnt vmcnt(0)
	v_and_b32_e32 v41, 0xffff0000, v59
	v_and_b32_e32 v40, 0xffff0000, v58
	v_pk_add_f32 v[38:39], v[38:39], v[40:41]
	v_pk_add_f32 v[40:41], v[46:47], 1.0 op_sel_hi:[1,0]
	v_lshlrev_b32_e32 v61, 16, v59
	v_lshlrev_b32_e32 v60, 16, v58
	v_pk_add_f32 v[56:57], v[56:57], v[60:61]
	v_rcp_f32_e32 v42, v41
	s_nop 0
	v_mul_f32_e32 v41, v34, v42
	s_nop 0
	v_rcp_f32_e32 v34, v40
	s_nop 0
	v_mul_f32_e32 v40, v32, v34
	v_pk_mul_f32 v[40:41], v[40:41], v[56:57]
	v_rcp_f32_e32 v32, v37
	s_nop 0
	v_mul_f32_e32 v35, v35, v32
	s_nop 0
	v_rcp_f32_e32 v32, v36
	s_nop 0
	v_mul_f32_e32 v34, v33, v32
	v_pk_mul_f32 v[32:33], v[34:35], v[38:39]
	v_and_b32_sdwa v34, v41, v154 dst_sel:DWORD dst_unused:UNUSED_PAD src0_sel:WORD_1 src1_sel:DWORD
	v_and_b32_sdwa v36, v33, v154 dst_sel:DWORD dst_unused:UNUSED_PAD src0_sel:WORD_1 src1_sel:DWORD
	v_and_b32_sdwa v37, v32, v154 dst_sel:DWORD dst_unused:UNUSED_PAD src0_sel:WORD_1 src1_sel:DWORD
	v_and_b32_sdwa v35, v40, v154 dst_sel:DWORD dst_unused:UNUSED_PAD src0_sel:WORD_1 src1_sel:DWORD
	v_add3_u32 v33, v33, v36, s33
	v_add3_u32 v32, v32, v37, s33
	v_add3_u32 v35, v40, v35, s33
	v_add3_u32 v34, v41, v34, s33
	v_and_b32_e32 v33, 0xffff0000, v33
	v_and_b32_e32 v32, 0xffff0000, v32
	v_or_b32_sdwa v33, v33, v34 dst_sel:DWORD dst_unused:UNUSED_PAD src0_sel:DWORD src1_sel:WORD_1
	v_or_b32_sdwa v32, v32, v35 dst_sel:DWORD dst_unused:UNUSED_PAD src0_sel:DWORD src1_sel:WORD_1
	global_store_dwordx2 v[48:49], v[32:33], off offset:96
	v_add_u32_e32 v32, 48, v88
	v_ashrrev_i32_e32 v33, 31, v32
	v_lshlrev_b64 v[44:45], 11, v[32:33]
	v_lshl_add_u64 v[34:35], v[90:91], 0, v[44:45]
	global_load_dwordx2 v[38:39], v[34:35], off
	global_load_dwordx2 v[36:37], v[34:35], off offset:32
	v_lshl_add_u64 v[44:45], s[8:9], 0, v[44:45]
	v_lshl_add_u64 v[44:45], v[44:45], 0, v[96:97]
	s_waitcnt vmcnt(1)
	v_lshlrev_b32_e32 v70, 16, v38
	s_waitcnt vmcnt(0)
	v_lshlrev_b32_e32 v59, 16, v36
	v_and_b32_e32 v55, 0xffff0000, v36
	v_alignbit_b32 v33, v37, v36, 16
	v_and_b32_e32 v57, 0xffff0000, v37
	global_load_dwordx2 v[36:37], v[34:35], off offset:64
	v_and_b32_e32 v61, 0xffff0000, v33
	v_and_b32_e32 v65, 0xffff0000, v39
	v_and_b32_e32 v68, 0xffff0000, v38
	v_mov_b32_e32 v64, v70
	v_mov_b32_e32 v69, v70
	v_mul_f32_e32 v62, v70, v70
	v_mul_f32_e32 v58, v59, v59
	v_mul_f32_e32 v54, v55, v55
	v_mul_f32_e32 v60, v61, v61
	v_mul_f32_e32 v56, v57, v57
	s_waitcnt vmcnt(0)
	v_lshlrev_b32_e32 v51, 16, v36
	v_and_b32_e32 v47, 0xffff0000, v36
	v_alignbit_b32 v33, v37, v36, 16
	v_and_b32_e32 v49, 0xffff0000, v37
	global_load_dwordx2 v[36:37], v[34:35], off offset:96
	v_and_b32_e32 v53, 0xffff0000, v33
	v_mul_f32_e32 v50, v51, v51
	v_mul_f32_e32 v46, v47, v47
	v_mul_f32_e32 v52, v53, v53
	v_mul_f32_e32 v48, v49, v49
	s_waitcnt vmcnt(0)
	v_alignbit_b32 v33, v37, v36, 16
	v_and_b32_e32 v43, 0xffff0000, v33
	v_alignbit_b32 v33, v39, v38, 16
	v_and_b32_e32 v39, 0xffff0000, v33
	v_and_b32_e32 v38, 16, v38
	v_mov_b32_e32 v33, v70
	v_pk_add_f32 v[66:67], v[38:39], v[64:65]
	v_pk_add_f32 v[72:73], v[68:69], v[32:33] op_sel_hi:[0,1]
	v_mov_b32_e32 v63, v67
	v_pk_mul_f32 v[66:67], v[68:69], v[68:69]
	v_mov_b32_e32 v64, v39
	v_mov_b32_e32 v67, v73
	global_load_dwordx4 v[72:75], v89, s[0:1]
	global_load_dwordx4 v[76:79], v89, s[4:5]
	v_mul_f32_e32 v38, v65, v65
	v_mov_b32_e32 v71, v39
	v_pk_fma_f32 v[38:39], v[64:65], v[64:65], v[38:39] op_sel_hi:[1,1,0]
	v_pk_add_f32 v[62:63], v[62:63], v[66:67]
	v_mov_b32_e32 v39, v97
	v_pk_add_f32 v[38:39], v[62:63], v[38:39]
	v_pk_add_f32 v[62:63], v[58:59], v[54:55]
	v_pk_add_f32 v[66:67], v[60:61], v[56:57]
	v_lshlrev_b32_e32 v41, 16, v36
	v_pk_add_f32 v[62:63], v[62:63], v[66:67]
	v_and_b32_e32 v35, 0xffff0000, v36
	v_and_b32_e32 v37, 0xffff0000, v37
	v_pk_add_f32 v[38:39], v[38:39], v[62:63]
	v_pk_add_f32 v[62:63], v[50:51], v[46:47]
	v_pk_add_f32 v[66:67], v[52:53], v[48:49]
	v_mul_f32_e32 v40, v41, v41
	v_mul_f32_e32 v34, v35, v35
	v_mul_f32_e32 v42, v43, v43
	v_mul_f32_e32 v36, v37, v37
	v_pk_add_f32 v[62:63], v[62:63], v[66:67]
	v_pk_add_f32 v[66:67], v[42:43], v[36:37]
	v_pk_add_f32 v[38:39], v[38:39], v[62:63]
	v_pk_add_f32 v[62:63], v[40:41], v[34:35]
	v_mul_f32_e32 v36, 0xbfb8aa3b, v28
	v_pk_add_f32 v[62:63], v[62:63], v[66:67]
	v_exp_f32_e32 v66, v36
	v_pk_add_f32 v[38:39], v[38:39], v[62:63]
	s_nop 0
	ds_bpermute_b32 v63, v184, v39
	ds_bpermute_b32 v62, v184, v38
	v_mul_f32_e32 v36, 0xbfb8aa3b, v29
	v_mov_b32_e32 v69, v65
	v_mov_b32_e32 v60, v59
	v_mov_b32_e32 v56, v55
	s_waitcnt lgkmcnt(0)
	v_pk_add_f32 v[38:39], v[38:39], v[62:63]
	s_nop 0
	ds_bpermute_b32 v63, v185, v39
	ds_bpermute_b32 v62, v185, v38
	v_mov_b32_e32 v52, v51
	s_waitcnt lgkmcnt(0)
	v_pk_add_f32 v[38:39], v[38:39], v[62:63]
	s_nop 0
	v_pk_mul_f32 v[38:39], v[38:39], s[38:39] op_sel_hi:[1,0]
	v_exp_f32_e32 v62, v36
	v_fma_f32 v33, -v39, v39, v38
	v_max_f32_e32 v33, 0, v33
	v_add_f32_e32 v33, 0x3a27c5ac, v33
	v_cmp_gt_f32_e32 vcc, s12, v33
	v_mul_f32_e32 v34, 0x4b800000, v33
	v_pk_add_f32 v[70:71], v[70:71], v[38:39] op_sel:[0,1] neg_lo:[0,1] neg_hi:[0,1]
	v_cndmask_b32_e32 v33, v33, v34, vcc
	v_rsq_f32_e32 v33, v33
	v_mul_f32_e32 v36, 0xbfb8aa3b, v30
	v_exp_f32_e32 v67, v36
	v_mul_f32_e32 v36, 0xbfb8aa3b, v31
	v_mul_f32_e32 v34, 0x45800000, v33
	v_cndmask_b32_e32 v34, v33, v34, vcc
	v_pk_mul_f32 v[70:71], v[70:71], v[34:35] op_sel_hi:[1,0]
	v_pk_add_f32 v[66:67], v[66:67], 1.0 op_sel_hi:[1,0]
	v_exp_f32_e32 v63, v36
	s_nop 0
	v_pk_add_f32 v[62:63], v[62:63], 1.0 op_sel_hi:[1,0]
	v_pk_add_f32 v[64:65], v[68:69], v[38:39] op_sel:[0,1] neg_lo:[0,1] neg_hi:[0,1]
	v_mad_i64_i32 v[32:33], s[10:11], v32, s13, v[86:87]
	v_rcp_f32_e32 v36, v67
	s_nop 0
	v_mul_f32_e32 v67, v30, v36
	s_waitcnt vmcnt(1)
	v_mov_b32_e32 v92, v72
	v_mov_b32_e32 v93, v74
	s_waitcnt vmcnt(0)
	v_mov_b32_e32 v94, v76
	v_mov_b32_e32 v95, v78
	v_pk_fma_f32 v[70:71], v[92:93], v[70:71], v[94:95]
	global_load_dwordx2 v[92:93], v[44:45], off
	v_pk_mul_f32 v[64:65], v[64:65], v[34:35] op_sel_hi:[1,0]
	v_mov_b32_e32 v74, v73
	v_mov_b32_e32 v78, v77
	v_rcp_f32_e32 v30, v66
	s_nop 0
	v_mul_f32_e32 v66, v28, v30
	v_pk_fma_f32 v[64:65], v[74:75], v[64:65], v[78:79]
	v_pk_add_f32 v[58:59], v[60:61], v[38:39] op_sel:[0,1] neg_lo:[0,1] neg_hi:[0,1]
	v_pk_add_f32 v[54:55], v[56:57], v[38:39] op_sel:[0,1] neg_lo:[0,1] neg_hi:[0,1]
	v_rcp_f32_e32 v28, v63
	s_nop 0
	v_mul_f32_e32 v31, v31, v28
	v_pk_mul_f32 v[58:59], v[58:59], v[34:35] op_sel_hi:[1,0]
	v_pk_mul_f32 v[54:55], v[54:55], v[34:35] op_sel_hi:[1,0]
	v_pk_add_f32 v[50:51], v[52:53], v[38:39] op_sel:[0,1] neg_lo:[0,1] neg_hi:[0,1]
	v_rcp_f32_e32 v28, v62
	s_nop 0
	v_mul_f32_e32 v30, v29, v28
	v_pk_mul_f32 v[50:51], v[50:51], v[34:35] op_sel_hi:[1,0]
	s_waitcnt vmcnt(0)
	v_and_b32_e32 v69, 0xffff0000, v93
	v_and_b32_e32 v68, 0xffff0000, v92
	v_lshlrev_b32_e32 v95, 16, v93
	v_lshlrev_b32_e32 v94, 16, v92
	v_pk_add_f32 v[64:65], v[64:65], v[68:69]
	v_pk_add_f32 v[70:71], v[70:71], v[94:95]
	v_pk_mul_f32 v[28:29], v[30:31], v[64:65]
	v_pk_mul_f32 v[66:67], v[66:67], v[70:71]
	v_and_b32_sdwa v36, v29, v154 dst_sel:DWORD dst_unused:UNUSED_PAD src0_sel:WORD_1 src1_sel:DWORD
	v_and_b32_sdwa v40, v28, v154 dst_sel:DWORD dst_unused:UNUSED_PAD src0_sel:WORD_1 src1_sel:DWORD
	v_and_b32_sdwa v30, v67, v154 dst_sel:DWORD dst_unused:UNUSED_PAD src0_sel:WORD_1 src1_sel:DWORD
	v_and_b32_sdwa v31, v66, v154 dst_sel:DWORD dst_unused:UNUSED_PAD src0_sel:WORD_1 src1_sel:DWORD
	v_add3_u32 v29, v29, v36, s33
	v_add3_u32 v28, v28, v40, s33
	v_add3_u32 v31, v66, v31, s33
	v_add3_u32 v30, v67, v30, s33
	v_and_b32_e32 v29, 0xffff0000, v29
	v_and_b32_e32 v28, 0xffff0000, v28
	v_or_b32_sdwa v29, v29, v30 dst_sel:DWORD dst_unused:UNUSED_PAD src0_sel:DWORD src1_sel:WORD_1
	v_or_b32_sdwa v28, v28, v31 dst_sel:DWORD dst_unused:UNUSED_PAD src0_sel:DWORD src1_sel:WORD_1
	global_store_dwordx2 v[32:33], v[28:29], off
	global_load_dwordx4 v[62:65], v89, s[0:1] offset:64
	global_load_dwordx4 v[66:69], v89, s[4:5] offset:64
	v_mul_f32_e32 v28, 0xbfb8aa3b, v24
	v_mul_f32_e32 v29, 0xbfb8aa3b, v26
	v_exp_f32_e32 v30, v28
	v_exp_f32_e32 v31, v29
	v_mul_f32_e32 v28, 0xbfb8aa3b, v25
	v_mul_f32_e32 v29, 0xbfb8aa3b, v27
	v_exp_f32_e32 v28, v28
	v_pk_add_f32 v[30:31], v[30:31], 1.0 op_sel_hi:[1,0]
	v_exp_f32_e32 v29, v29
	s_nop 0
	v_pk_add_f32 v[28:29], v[28:29], 1.0 op_sel_hi:[1,0]
	v_rcp_f32_e32 v36, v31
	s_nop 0
	v_mul_f32_e32 v31, v26, v36
	v_mov_b32_e32 v48, v47
	v_rcp_f32_e32 v26, v30
	s_nop 0
	v_mul_f32_e32 v30, v24, v26
	v_pk_add_f32 v[46:47], v[48:49], v[38:39] op_sel:[0,1] neg_lo:[0,1] neg_hi:[0,1]
	v_rcp_f32_e32 v24, v29
	s_nop 0
	v_mul_f32_e32 v27, v27, v24
	v_pk_mul_f32 v[46:47], v[46:47], v[34:35] op_sel_hi:[1,0]
	v_rcp_f32_e32 v24, v28
	s_nop 0
	v_mul_f32_e32 v26, v25, v24
	s_waitcnt vmcnt(1)
	v_mov_b32_e32 v60, v62
	v_mov_b32_e32 v61, v64
	s_waitcnt vmcnt(0)
	v_mov_b32_e32 v70, v66
	v_mov_b32_e32 v71, v68
	v_pk_fma_f32 v[58:59], v[58:59], v[60:61], v[70:71]
	global_load_dwordx2 v[60:61], v[44:45], off offset:32
	v_mov_b32_e32 v64, v63
	v_mov_b32_e32 v68, v67
	v_pk_fma_f32 v[54:55], v[54:55], v[64:65], v[68:69]
	s_waitcnt vmcnt(0)
	v_and_b32_e32 v57, 0xffff0000, v61
	v_and_b32_e32 v56, 0xffff0000, v60
	v_lshlrev_b32_e32 v71, 16, v61
	v_lshlrev_b32_e32 v70, 16, v60
	v_pk_add_f32 v[54:55], v[54:55], v[56:57]
	v_pk_add_f32 v[58:59], v[58:59], v[70:71]
	v_pk_mul_f32 v[24:25], v[26:27], v[54:55]
	v_pk_mul_f32 v[30:31], v[30:31], v[58:59]
	v_and_b32_sdwa v28, v25, v154 dst_sel:DWORD dst_unused:UNUSED_PAD src0_sel:WORD_1 src1_sel:DWORD
	v_and_b32_sdwa v29, v24, v154 dst_sel:DWORD dst_unused:UNUSED_PAD src0_sel:WORD_1 src1_sel:DWORD
	v_and_b32_sdwa v26, v31, v154 dst_sel:DWORD dst_unused:UNUSED_PAD src0_sel:WORD_1 src1_sel:DWORD
	v_and_b32_sdwa v27, v30, v154 dst_sel:DWORD dst_unused:UNUSED_PAD src0_sel:WORD_1 src1_sel:DWORD
	v_add3_u32 v25, v25, v28, s33
	v_add3_u32 v24, v24, v29, s33
	v_add3_u32 v27, v30, v27, s33
	v_add3_u32 v26, v31, v26, s33
	v_and_b32_e32 v25, 0xffff0000, v25
	v_and_b32_e32 v24, 0xffff0000, v24
	v_or_b32_sdwa v25, v25, v26 dst_sel:DWORD dst_unused:UNUSED_PAD src0_sel:DWORD src1_sel:WORD_1
	v_or_b32_sdwa v24, v24, v27 dst_sel:DWORD dst_unused:UNUSED_PAD src0_sel:DWORD src1_sel:WORD_1
	global_store_dwordx2 v[32:33], v[24:25], off offset:32
	global_load_dwordx4 v[26:29], v89, s[0:1] offset:128
	global_load_dwordx4 v[54:57], v89, s[4:5] offset:128
	v_mul_f32_e32 v24, 0xbfb8aa3b, v20
	v_mul_f32_e32 v25, 0xbfb8aa3b, v22
	v_exp_f32_e32 v30, v24
	v_exp_f32_e32 v31, v25
	v_mul_f32_e32 v24, 0xbfb8aa3b, v21
	v_mul_f32_e32 v25, 0xbfb8aa3b, v23
	v_exp_f32_e32 v24, v24
	v_exp_f32_e32 v25, v25
	s_waitcnt vmcnt(1)
	v_mov_b32_e32 v52, v26
	v_mov_b32_e32 v53, v28
	s_waitcnt vmcnt(0)
	v_mov_b32_e32 v58, v54
	v_mov_b32_e32 v59, v56
	v_pk_fma_f32 v[50:51], v[50:51], v[52:53], v[58:59]
	global_load_dwordx2 v[52:53], v[44:45], off offset:64
	v_mov_b32_e32 v28, v27
	v_mov_b32_e32 v56, v55
	v_pk_fma_f32 v[26:27], v[46:47], v[28:29], v[56:57]
	v_pk_add_f32 v[24:25], v[24:25], 1.0 op_sel_hi:[1,0]
	s_waitcnt vmcnt(0)
	v_and_b32_e32 v29, 0xffff0000, v53
	v_and_b32_e32 v28, 0xffff0000, v52
	v_pk_add_f32 v[26:27], v[26:27], v[28:29]
	v_pk_add_f32 v[28:29], v[30:31], 1.0 op_sel_hi:[1,0]
	v_lshlrev_b32_e32 v59, 16, v53
	v_lshlrev_b32_e32 v58, 16, v52
	v_pk_add_f32 v[50:51], v[50:51], v[58:59]
	v_rcp_f32_e32 v30, v29
	s_nop 0
	v_mul_f32_e32 v29, v22, v30
	v_mov_b32_e32 v42, v41
	v_rcp_f32_e32 v22, v28
	s_nop 0
	v_mul_f32_e32 v28, v20, v22
	v_pk_mul_f32 v[28:29], v[28:29], v[50:51]
	v_pk_add_f32 v[40:41], v[42:43], v[38:39] op_sel:[0,1] neg_lo:[0,1] neg_hi:[0,1]
	v_rcp_f32_e32 v20, v25
	s_nop 0
	v_mul_f32_e32 v23, v23, v20
	v_pk_mul_f32 v[40:41], v[40:41], v[34:35] op_sel_hi:[1,0]
	v_mov_b32_e32 v36, v35
	v_pk_add_f32 v[36:37], v[36:37], v[38:39] op_sel:[0,1] neg_lo:[0,1] neg_hi:[0,1]
	v_rcp_f32_e32 v20, v24
	s_nop 0
	v_mul_f32_e32 v22, v21, v20
	v_pk_mul_f32 v[20:21], v[22:23], v[26:27]
	v_and_b32_sdwa v22, v29, v154 dst_sel:DWORD dst_unused:UNUSED_PAD src0_sel:WORD_1 src1_sel:DWORD
	v_and_b32_sdwa v24, v21, v154 dst_sel:DWORD dst_unused:UNUSED_PAD src0_sel:WORD_1 src1_sel:DWORD
	v_and_b32_sdwa v25, v20, v154 dst_sel:DWORD dst_unused:UNUSED_PAD src0_sel:WORD_1 src1_sel:DWORD
	v_and_b32_sdwa v23, v28, v154 dst_sel:DWORD dst_unused:UNUSED_PAD src0_sel:WORD_1 src1_sel:DWORD
	v_add3_u32 v21, v21, v24, s33
	v_add3_u32 v20, v20, v25, s33
	v_add3_u32 v23, v28, v23, s33
	v_add3_u32 v22, v29, v22, s33
	v_and_b32_e32 v21, 0xffff0000, v21
	v_and_b32_e32 v20, 0xffff0000, v20
	v_or_b32_sdwa v21, v21, v22 dst_sel:DWORD dst_unused:UNUSED_PAD src0_sel:DWORD src1_sel:WORD_1
	v_or_b32_sdwa v20, v20, v23 dst_sel:DWORD dst_unused:UNUSED_PAD src0_sel:DWORD src1_sel:WORD_1
	global_store_dwordx2 v[32:33], v[20:21], off offset:64
	global_load_dwordx4 v[22:25], v89, s[0:1] offset:192
	global_load_dwordx4 v[26:29], v89, s[4:5] offset:192
	v_mul_f32_e32 v20, 0xbfb8aa3b, v16
	v_mul_f32_e32 v21, 0xbfb8aa3b, v18
	v_exp_f32_e32 v30, v20
	v_exp_f32_e32 v31, v21
	v_pk_mul_f32 v[34:35], v[36:37], v[34:35] op_sel_hi:[1,0]
	v_mul_f32_e32 v20, 0xbfb8aa3b, v17
	v_mul_f32_e32 v21, 0xbfb8aa3b, v19
	v_exp_f32_e32 v20, v20
	v_exp_f32_e32 v21, v21
	s_waitcnt vmcnt(1)
	v_mov_b32_e32 v42, v22
	v_mov_b32_e32 v43, v24
	s_waitcnt vmcnt(0)
	v_mov_b32_e32 v46, v26
	v_mov_b32_e32 v47, v28
	v_pk_fma_f32 v[40:41], v[40:41], v[42:43], v[46:47]
	global_load_dwordx2 v[42:43], v[44:45], off offset:96
	v_mov_b32_e32 v24, v23
	v_mov_b32_e32 v28, v27
	v_pk_fma_f32 v[22:23], v[34:35], v[24:25], v[28:29]
	v_pk_add_f32 v[20:21], v[20:21], 1.0 op_sel_hi:[1,0]
	s_waitcnt vmcnt(0)
	v_and_b32_e32 v25, 0xffff0000, v43
	v_and_b32_e32 v24, 0xffff0000, v42
	v_pk_add_f32 v[22:23], v[22:23], v[24:25]
	v_pk_add_f32 v[24:25], v[30:31], 1.0 op_sel_hi:[1,0]
	v_lshlrev_b32_e32 v45, 16, v43
	v_lshlrev_b32_e32 v44, 16, v42
	v_pk_add_f32 v[40:41], v[40:41], v[44:45]
	v_rcp_f32_e32 v26, v25
	s_nop 0
	v_mul_f32_e32 v25, v18, v26
	s_nop 0
	v_rcp_f32_e32 v18, v24
	s_nop 0
	v_mul_f32_e32 v24, v16, v18
	v_pk_mul_f32 v[24:25], v[24:25], v[40:41]
	v_rcp_f32_e32 v16, v21
	s_nop 0
	v_mul_f32_e32 v19, v19, v16
	s_nop 0
	v_rcp_f32_e32 v16, v20
	s_nop 0
	v_mul_f32_e32 v18, v17, v16
	v_pk_mul_f32 v[16:17], v[18:19], v[22:23]
	v_and_b32_sdwa v18, v25, v154 dst_sel:DWORD dst_unused:UNUSED_PAD src0_sel:WORD_1 src1_sel:DWORD
	v_and_b32_sdwa v20, v17, v154 dst_sel:DWORD dst_unused:UNUSED_PAD src0_sel:WORD_1 src1_sel:DWORD
	v_and_b32_sdwa v21, v16, v154 dst_sel:DWORD dst_unused:UNUSED_PAD src0_sel:WORD_1 src1_sel:DWORD
	v_and_b32_sdwa v19, v24, v154 dst_sel:DWORD dst_unused:UNUSED_PAD src0_sel:WORD_1 src1_sel:DWORD
	v_add3_u32 v17, v17, v20, s33
	v_add3_u32 v16, v16, v21, s33
	v_add3_u32 v19, v24, v19, s33
	v_add3_u32 v18, v25, v18, s33
	v_and_b32_e32 v17, 0xffff0000, v17
	v_and_b32_e32 v16, 0xffff0000, v16
	v_or_b32_sdwa v17, v17, v18 dst_sel:DWORD dst_unused:UNUSED_PAD src0_sel:DWORD src1_sel:WORD_1
	v_or_b32_sdwa v16, v16, v19 dst_sel:DWORD dst_unused:UNUSED_PAD src0_sel:DWORD src1_sel:WORD_1
	global_store_dwordx2 v[32:33], v[16:17], off offset:96
	v_add_u32_e32 v16, 64, v88
	v_ashrrev_i32_e32 v17, 31, v16
	v_lshlrev_b64 v[28:29], 11, v[16:17]
	v_lshl_add_u64 v[18:19], v[90:91], 0, v[28:29]
	global_load_dwordx2 v[22:23], v[18:19], off
	global_load_dwordx2 v[20:21], v[18:19], off offset:32
	v_lshl_add_u64 v[28:29], s[8:9], 0, v[28:29]
	v_lshl_add_u64 v[28:29], v[28:29], 0, v[96:97]
	s_waitcnt vmcnt(1)
	v_lshlrev_b32_e32 v54, 16, v22
	s_waitcnt vmcnt(0)
	v_lshlrev_b32_e32 v43, 16, v20
	v_and_b32_e32 v39, 0xffff0000, v20
	v_alignbit_b32 v17, v21, v20, 16
	v_and_b32_e32 v41, 0xffff0000, v21
	global_load_dwordx2 v[20:21], v[18:19], off offset:64
	v_and_b32_e32 v45, 0xffff0000, v17
	v_and_b32_e32 v49, 0xffff0000, v23
	v_and_b32_e32 v52, 0xffff0000, v22
	v_mov_b32_e32 v48, v54
	v_mov_b32_e32 v53, v54
	v_mul_f32_e32 v46, v54, v54
	v_mul_f32_e32 v42, v43, v43
	v_mul_f32_e32 v38, v39, v39
	v_mul_f32_e32 v44, v45, v45
	v_mul_f32_e32 v40, v41, v41
	s_waitcnt vmcnt(0)
	v_lshlrev_b32_e32 v35, 16, v20
	v_and_b32_e32 v31, 0xffff0000, v20
	v_alignbit_b32 v17, v21, v20, 16
	v_and_b32_e32 v33, 0xffff0000, v21
	global_load_dwordx2 v[20:21], v[18:19], off offset:96
	v_and_b32_e32 v37, 0xffff0000, v17
	v_mul_f32_e32 v34, v35, v35
	v_mul_f32_e32 v30, v31, v31
	v_mul_f32_e32 v36, v37, v37
	v_mul_f32_e32 v32, v33, v33
	s_waitcnt vmcnt(0)
	v_alignbit_b32 v17, v21, v20, 16
	v_and_b32_e32 v27, 0xffff0000, v17
	v_alignbit_b32 v17, v23, v22, 16
	v_and_b32_e32 v23, 0xffff0000, v17
	v_and_b32_e32 v22, 16, v22
	v_mov_b32_e32 v17, v54
	v_pk_add_f32 v[50:51], v[22:23], v[48:49]
	v_pk_add_f32 v[56:57], v[52:53], v[16:17] op_sel_hi:[0,1]
	v_mov_b32_e32 v47, v51
	v_pk_mul_f32 v[50:51], v[52:53], v[52:53]
	v_mov_b32_e32 v48, v23
	v_mov_b32_e32 v51, v57
	global_load_dwordx4 v[56:59], v89, s[0:1]
	global_load_dwordx4 v[60:63], v89, s[4:5]
	v_mul_f32_e32 v22, v49, v49
	v_mov_b32_e32 v55, v23
	v_pk_fma_f32 v[22:23], v[48:49], v[48:49], v[22:23] op_sel_hi:[1,1,0]
	v_pk_add_f32 v[46:47], v[46:47], v[50:51]
	v_mov_b32_e32 v23, v97
	v_pk_add_f32 v[22:23], v[46:47], v[22:23]
	v_pk_add_f32 v[46:47], v[42:43], v[38:39]
	v_pk_add_f32 v[50:51], v[44:45], v[40:41]
	v_lshlrev_b32_e32 v25, 16, v20
	v_pk_add_f32 v[46:47], v[46:47], v[50:51]
	v_and_b32_e32 v19, 0xffff0000, v20
	v_and_b32_e32 v21, 0xffff0000, v21
	v_pk_add_f32 v[22:23], v[22:23], v[46:47]
	v_pk_add_f32 v[46:47], v[34:35], v[30:31]
	v_pk_add_f32 v[50:51], v[36:37], v[32:33]
	v_mul_f32_e32 v24, v25, v25
	v_mul_f32_e32 v18, v19, v19
	v_mul_f32_e32 v26, v27, v27
	v_mul_f32_e32 v20, v21, v21
	v_pk_add_f32 v[46:47], v[46:47], v[50:51]
	v_pk_add_f32 v[50:51], v[26:27], v[20:21]
	v_pk_add_f32 v[22:23], v[22:23], v[46:47]
	v_pk_add_f32 v[46:47], v[24:25], v[18:19]
	v_mul_f32_e32 v20, 0xbfb8aa3b, v12
	v_pk_add_f32 v[46:47], v[46:47], v[50:51]
	v_exp_f32_e32 v50, v20
	v_pk_add_f32 v[22:23], v[22:23], v[46:47]
	s_nop 0
	ds_bpermute_b32 v47, v184, v23
	ds_bpermute_b32 v46, v184, v22
	v_mul_f32_e32 v20, 0xbfb8aa3b, v13
	v_mov_b32_e32 v53, v49
	v_mov_b32_e32 v44, v43
	v_mov_b32_e32 v40, v39
	s_waitcnt lgkmcnt(0)
	v_pk_add_f32 v[22:23], v[22:23], v[46:47]
	s_nop 0
	ds_bpermute_b32 v47, v185, v23
	ds_bpermute_b32 v46, v185, v22
	v_mov_b32_e32 v36, v35
	s_waitcnt lgkmcnt(0)
	v_pk_add_f32 v[22:23], v[22:23], v[46:47]
	s_nop 0
	v_pk_mul_f32 v[22:23], v[22:23], s[38:39] op_sel_hi:[1,0]
	v_exp_f32_e32 v46, v20
	v_fma_f32 v17, -v23, v23, v22
	v_max_f32_e32 v17, 0, v17
	v_add_f32_e32 v17, 0x3a27c5ac, v17
	v_cmp_gt_f32_e32 vcc, s12, v17
	v_mul_f32_e32 v18, 0x4b800000, v17
	v_pk_add_f32 v[54:55], v[54:55], v[22:23] op_sel:[0,1] neg_lo:[0,1] neg_hi:[0,1]
	v_cndmask_b32_e32 v17, v17, v18, vcc
	v_rsq_f32_e32 v17, v17
	v_mul_f32_e32 v20, 0xbfb8aa3b, v14
	v_exp_f32_e32 v51, v20
	v_mul_f32_e32 v20, 0xbfb8aa3b, v15
	v_mul_f32_e32 v18, 0x45800000, v17
	v_cndmask_b32_e32 v18, v17, v18, vcc
	v_pk_mul_f32 v[54:55], v[54:55], v[18:19] op_sel_hi:[1,0]
	v_pk_add_f32 v[50:51], v[50:51], 1.0 op_sel_hi:[1,0]
	v_exp_f32_e32 v47, v20
	s_nop 0
	v_pk_add_f32 v[46:47], v[46:47], 1.0 op_sel_hi:[1,0]
	v_pk_add_f32 v[48:49], v[52:53], v[22:23] op_sel:[0,1] neg_lo:[0,1] neg_hi:[0,1]
	v_mad_i64_i32 v[16:17], s[10:11], v16, s13, v[86:87]
	v_rcp_f32_e32 v20, v51
	s_nop 0
	v_mul_f32_e32 v51, v14, v20
	s_waitcnt vmcnt(1)
	v_mov_b32_e32 v64, v56
	v_mov_b32_e32 v65, v58
	s_waitcnt vmcnt(0)
	v_mov_b32_e32 v66, v60
	v_mov_b32_e32 v67, v62
	v_pk_fma_f32 v[54:55], v[64:65], v[54:55], v[66:67]
	global_load_dwordx2 v[64:65], v[28:29], off
	v_pk_mul_f32 v[48:49], v[48:49], v[18:19] op_sel_hi:[1,0]
	v_mov_b32_e32 v58, v57
	v_mov_b32_e32 v62, v61
	v_rcp_f32_e32 v14, v50
	s_nop 0
	v_mul_f32_e32 v50, v12, v14
	v_pk_fma_f32 v[48:49], v[58:59], v[48:49], v[62:63]
	v_pk_add_f32 v[42:43], v[44:45], v[22:23] op_sel:[0,1] neg_lo:[0,1] neg_hi:[0,1]
	v_pk_add_f32 v[38:39], v[40:41], v[22:23] op_sel:[0,1] neg_lo:[0,1] neg_hi:[0,1]
	v_rcp_f32_e32 v12, v47
	s_nop 0
	v_mul_f32_e32 v15, v15, v12
	v_pk_mul_f32 v[42:43], v[42:43], v[18:19] op_sel_hi:[1,0]
	v_pk_mul_f32 v[38:39], v[38:39], v[18:19] op_sel_hi:[1,0]
	v_pk_add_f32 v[34:35], v[36:37], v[22:23] op_sel:[0,1] neg_lo:[0,1] neg_hi:[0,1]
	v_rcp_f32_e32 v12, v46
	s_nop 0
	v_mul_f32_e32 v14, v13, v12
	v_pk_mul_f32 v[34:35], v[34:35], v[18:19] op_sel_hi:[1,0]
	s_waitcnt vmcnt(0)
	v_and_b32_e32 v53, 0xffff0000, v65
	v_and_b32_e32 v52, 0xffff0000, v64
	v_lshlrev_b32_e32 v67, 16, v65
	v_lshlrev_b32_e32 v66, 16, v64
	v_pk_add_f32 v[48:49], v[48:49], v[52:53]
	v_pk_add_f32 v[54:55], v[54:55], v[66:67]
	v_pk_mul_f32 v[12:13], v[14:15], v[48:49]
	v_pk_mul_f32 v[50:51], v[50:51], v[54:55]
	v_and_b32_sdwa v20, v13, v154 dst_sel:DWORD dst_unused:UNUSED_PAD src0_sel:WORD_1 src1_sel:DWORD
	v_and_b32_sdwa v24, v12, v154 dst_sel:DWORD dst_unused:UNUSED_PAD src0_sel:WORD_1 src1_sel:DWORD
	v_and_b32_sdwa v14, v51, v154 dst_sel:DWORD dst_unused:UNUSED_PAD src0_sel:WORD_1 src1_sel:DWORD
	v_and_b32_sdwa v15, v50, v154 dst_sel:DWORD dst_unused:UNUSED_PAD src0_sel:WORD_1 src1_sel:DWORD
	v_add3_u32 v13, v13, v20, s33
	v_add3_u32 v12, v12, v24, s33
	v_add3_u32 v15, v50, v15, s33
	v_add3_u32 v14, v51, v14, s33
	v_and_b32_e32 v13, 0xffff0000, v13
	v_and_b32_e32 v12, 0xffff0000, v12
	v_or_b32_sdwa v13, v13, v14 dst_sel:DWORD dst_unused:UNUSED_PAD src0_sel:DWORD src1_sel:WORD_1
	v_or_b32_sdwa v12, v12, v15 dst_sel:DWORD dst_unused:UNUSED_PAD src0_sel:DWORD src1_sel:WORD_1
	global_store_dwordx2 v[16:17], v[12:13], off
	global_load_dwordx4 v[46:49], v89, s[0:1] offset:64
	global_load_dwordx4 v[50:53], v89, s[4:5] offset:64
	v_mul_f32_e32 v12, 0xbfb8aa3b, v8
	v_mul_f32_e32 v13, 0xbfb8aa3b, v10
	v_exp_f32_e32 v14, v12
	v_exp_f32_e32 v15, v13
	v_mul_f32_e32 v12, 0xbfb8aa3b, v9
	v_mul_f32_e32 v13, 0xbfb8aa3b, v11
	v_exp_f32_e32 v12, v12
	v_pk_add_f32 v[14:15], v[14:15], 1.0 op_sel_hi:[1,0]
	v_exp_f32_e32 v13, v13
	s_nop 0
	v_pk_add_f32 v[12:13], v[12:13], 1.0 op_sel_hi:[1,0]
	v_rcp_f32_e32 v20, v15
	s_nop 0
	v_mul_f32_e32 v15, v10, v20
	v_mov_b32_e32 v32, v31
	v_rcp_f32_e32 v10, v14
	s_nop 0
	v_mul_f32_e32 v14, v8, v10
	v_pk_add_f32 v[30:31], v[32:33], v[22:23] op_sel:[0,1] neg_lo:[0,1] neg_hi:[0,1]
	v_rcp_f32_e32 v8, v13
	s_nop 0
	v_mul_f32_e32 v11, v11, v8
	v_pk_mul_f32 v[30:31], v[30:31], v[18:19] op_sel_hi:[1,0]
	v_rcp_f32_e32 v8, v12
	s_nop 0
	v_mul_f32_e32 v10, v9, v8
	s_waitcnt vmcnt(1)
	v_mov_b32_e32 v44, v46
	v_mov_b32_e32 v45, v48
	s_waitcnt vmcnt(0)
	v_mov_b32_e32 v54, v50
	v_mov_b32_e32 v55, v52
	v_pk_fma_f32 v[42:43], v[42:43], v[44:45], v[54:55]
	global_load_dwordx2 v[44:45], v[28:29], off offset:32
	v_mov_b32_e32 v48, v47
	v_mov_b32_e32 v52, v51
	v_pk_fma_f32 v[38:39], v[38:39], v[48:49], v[52:53]
	s_waitcnt vmcnt(0)
	v_and_b32_e32 v41, 0xffff0000, v45
	v_and_b32_e32 v40, 0xffff0000, v44
	v_lshlrev_b32_e32 v55, 16, v45
	v_lshlrev_b32_e32 v54, 16, v44
	v_pk_add_f32 v[38:39], v[38:39], v[40:41]
	v_pk_add_f32 v[42:43], v[42:43], v[54:55]
	v_pk_mul_f32 v[8:9], v[10:11], v[38:39]
	v_pk_mul_f32 v[14:15], v[14:15], v[42:43]
	v_and_b32_sdwa v12, v9, v154 dst_sel:DWORD dst_unused:UNUSED_PAD src0_sel:WORD_1 src1_sel:DWORD
	v_and_b32_sdwa v13, v8, v154 dst_sel:DWORD dst_unused:UNUSED_PAD src0_sel:WORD_1 src1_sel:DWORD
	v_and_b32_sdwa v10, v15, v154 dst_sel:DWORD dst_unused:UNUSED_PAD src0_sel:WORD_1 src1_sel:DWORD
	v_and_b32_sdwa v11, v14, v154 dst_sel:DWORD dst_unused:UNUSED_PAD src0_sel:WORD_1 src1_sel:DWORD
	v_add3_u32 v9, v9, v12, s33
	v_add3_u32 v8, v8, v13, s33
	v_add3_u32 v11, v14, v11, s33
	v_add3_u32 v10, v15, v10, s33
	v_and_b32_e32 v9, 0xffff0000, v9
	v_and_b32_e32 v8, 0xffff0000, v8
	v_or_b32_sdwa v9, v9, v10 dst_sel:DWORD dst_unused:UNUSED_PAD src0_sel:DWORD src1_sel:WORD_1
	v_or_b32_sdwa v8, v8, v11 dst_sel:DWORD dst_unused:UNUSED_PAD src0_sel:DWORD src1_sel:WORD_1
	global_store_dwordx2 v[16:17], v[8:9], off offset:32
	global_load_dwordx4 v[10:13], v89, s[0:1] offset:128
	global_load_dwordx4 v[38:41], v89, s[4:5] offset:128
	v_mul_f32_e32 v8, 0xbfb8aa3b, v4
	v_mul_f32_e32 v9, 0xbfb8aa3b, v6
	v_exp_f32_e32 v14, v8
	v_exp_f32_e32 v15, v9
	v_mul_f32_e32 v8, 0xbfb8aa3b, v5
	v_mul_f32_e32 v9, 0xbfb8aa3b, v7
	v_exp_f32_e32 v8, v8
	v_exp_f32_e32 v9, v9
	s_waitcnt vmcnt(1)
	v_mov_b32_e32 v36, v10
	v_mov_b32_e32 v37, v12
	s_waitcnt vmcnt(0)
	v_mov_b32_e32 v42, v38
	v_mov_b32_e32 v43, v40
	v_pk_fma_f32 v[34:35], v[34:35], v[36:37], v[42:43]
	global_load_dwordx2 v[36:37], v[28:29], off offset:64
	v_mov_b32_e32 v12, v11
	v_mov_b32_e32 v40, v39
	v_pk_fma_f32 v[10:11], v[30:31], v[12:13], v[40:41]
	v_pk_add_f32 v[8:9], v[8:9], 1.0 op_sel_hi:[1,0]
	s_waitcnt vmcnt(0)
	v_and_b32_e32 v13, 0xffff0000, v37
	v_and_b32_e32 v12, 0xffff0000, v36
	v_pk_add_f32 v[10:11], v[10:11], v[12:13]
	v_pk_add_f32 v[12:13], v[14:15], 1.0 op_sel_hi:[1,0]
	v_lshlrev_b32_e32 v43, 16, v37
	v_lshlrev_b32_e32 v42, 16, v36
	v_pk_add_f32 v[34:35], v[34:35], v[42:43]
	v_rcp_f32_e32 v14, v13
	s_nop 0
	v_mul_f32_e32 v13, v6, v14
	v_mov_b32_e32 v26, v25
	v_rcp_f32_e32 v6, v12
	s_nop 0
	v_mul_f32_e32 v12, v4, v6
	v_pk_mul_f32 v[12:13], v[12:13], v[34:35]
	v_pk_add_f32 v[24:25], v[26:27], v[22:23] op_sel:[0,1] neg_lo:[0,1] neg_hi:[0,1]
	v_rcp_f32_e32 v4, v9
	s_nop 0
	v_mul_f32_e32 v7, v7, v4
	v_pk_mul_f32 v[24:25], v[24:25], v[18:19] op_sel_hi:[1,0]
	v_mov_b32_e32 v20, v19
	v_pk_add_f32 v[20:21], v[20:21], v[22:23] op_sel:[0,1] neg_lo:[0,1] neg_hi:[0,1]
	v_rcp_f32_e32 v4, v8
	s_nop 0
	v_mul_f32_e32 v6, v5, v4
	v_pk_mul_f32 v[4:5], v[6:7], v[10:11]
	v_and_b32_sdwa v6, v13, v154 dst_sel:DWORD dst_unused:UNUSED_PAD src0_sel:WORD_1 src1_sel:DWORD
	v_and_b32_sdwa v8, v5, v154 dst_sel:DWORD dst_unused:UNUSED_PAD src0_sel:WORD_1 src1_sel:DWORD
	v_and_b32_sdwa v9, v4, v154 dst_sel:DWORD dst_unused:UNUSED_PAD src0_sel:WORD_1 src1_sel:DWORD
	v_and_b32_sdwa v7, v12, v154 dst_sel:DWORD dst_unused:UNUSED_PAD src0_sel:WORD_1 src1_sel:DWORD
	v_add3_u32 v5, v5, v8, s33
	v_add3_u32 v4, v4, v9, s33
	v_add3_u32 v7, v12, v7, s33
	v_add3_u32 v6, v13, v6, s33
	v_and_b32_e32 v5, 0xffff0000, v5
	v_and_b32_e32 v4, 0xffff0000, v4
	v_or_b32_sdwa v5, v5, v6 dst_sel:DWORD dst_unused:UNUSED_PAD src0_sel:DWORD src1_sel:WORD_1
	v_or_b32_sdwa v4, v4, v7 dst_sel:DWORD dst_unused:UNUSED_PAD src0_sel:DWORD src1_sel:WORD_1
	global_store_dwordx2 v[16:17], v[4:5], off offset:64
	global_load_dwordx4 v[6:9], v89, s[0:1] offset:192
	global_load_dwordx4 v[10:13], v89, s[4:5] offset:192
	v_mul_f32_e32 v4, 0xbfb8aa3b, v0
	v_mul_f32_e32 v5, 0xbfb8aa3b, v2
	v_exp_f32_e32 v14, v4
	v_exp_f32_e32 v15, v5
	v_pk_mul_f32 v[18:19], v[20:21], v[18:19] op_sel_hi:[1,0]
	v_mul_f32_e32 v4, 0xbfb8aa3b, v1
	v_mul_f32_e32 v5, 0xbfb8aa3b, v3
	v_exp_f32_e32 v4, v4
	v_exp_f32_e32 v5, v5
	s_waitcnt vmcnt(1)
	v_mov_b32_e32 v26, v6
	v_mov_b32_e32 v27, v8
	s_waitcnt vmcnt(0)
	v_mov_b32_e32 v30, v10
	v_mov_b32_e32 v31, v12
	v_pk_fma_f32 v[24:25], v[24:25], v[26:27], v[30:31]
	global_load_dwordx2 v[26:27], v[28:29], off offset:96
	v_mov_b32_e32 v8, v7
	v_mov_b32_e32 v12, v11
	v_pk_fma_f32 v[6:7], v[18:19], v[8:9], v[12:13]
	v_pk_add_f32 v[4:5], v[4:5], 1.0 op_sel_hi:[1,0]
	s_waitcnt vmcnt(0)
	v_and_b32_e32 v9, 0xffff0000, v27
	v_and_b32_e32 v8, 0xffff0000, v26
	v_pk_add_f32 v[6:7], v[6:7], v[8:9]
	v_pk_add_f32 v[8:9], v[14:15], 1.0 op_sel_hi:[1,0]
	v_lshlrev_b32_e32 v29, 16, v27
	v_lshlrev_b32_e32 v28, 16, v26
	v_pk_add_f32 v[24:25], v[24:25], v[28:29]
	v_rcp_f32_e32 v10, v9
	s_nop 0
	v_mul_f32_e32 v9, v2, v10
	s_nop 0
	v_rcp_f32_e32 v2, v8
	s_nop 0
	v_mul_f32_e32 v8, v0, v2
	v_pk_mul_f32 v[8:9], v[8:9], v[24:25]
	v_rcp_f32_e32 v0, v5
	s_nop 0
	v_mul_f32_e32 v3, v3, v0
	s_nop 0
	v_rcp_f32_e32 v0, v4
	s_nop 0
	v_mul_f32_e32 v2, v1, v0
	v_pk_mul_f32 v[0:1], v[2:3], v[6:7]
	v_and_b32_sdwa v2, v9, v154 dst_sel:DWORD dst_unused:UNUSED_PAD src0_sel:WORD_1 src1_sel:DWORD
	v_and_b32_sdwa v4, v1, v154 dst_sel:DWORD dst_unused:UNUSED_PAD src0_sel:WORD_1 src1_sel:DWORD
	v_and_b32_sdwa v5, v0, v154 dst_sel:DWORD dst_unused:UNUSED_PAD src0_sel:WORD_1 src1_sel:DWORD
	v_and_b32_sdwa v3, v8, v154 dst_sel:DWORD dst_unused:UNUSED_PAD src0_sel:WORD_1 src1_sel:DWORD
	v_add3_u32 v1, v1, v4, s33
	v_add3_u32 v0, v0, v5, s33
	v_add3_u32 v3, v8, v3, s33
	v_add3_u32 v2, v9, v2, s33
	v_and_b32_e32 v1, 0xffff0000, v1
	v_and_b32_e32 v0, 0xffff0000, v0
	v_or_b32_sdwa v1, v1, v2 dst_sel:DWORD dst_unused:UNUSED_PAD src0_sel:DWORD src1_sel:WORD_1
	v_or_b32_sdwa v0, v0, v3 dst_sel:DWORD dst_unused:UNUSED_PAD src0_sel:DWORD src1_sel:WORD_1
	global_store_dwordx2 v[16:17], v[0:1], off offset:96

.LBB0_579:
	s_lshl_b32 s4, s12, 3
	s_mul_i32 s5, s4, s2
	s_cmpk_gt_i32 s5, 0x33f
	s_mov_b32 s8, 2
	s_cbranch_scc1 .LBB0_584
	s_or_b32 s4, s4, s10
	s_mul_i32 s4, s4, s2
	s_add_i32 s4, s4, s11
	s_cmpk_gt_i32 s4, 0x33f
	s_mov_b32 s8, 4
	s_cbranch_scc1 .LBB0_584
	s_mul_hi_i32 s5, s4, 0x4ec4ec4f
	s_lshr_b32 s6, s5, 31
	s_ashr_i32 s5, s5, 8
	s_add_i32 s5, s5, s6
	s_mul_i32 s6, s5, 0x340
	s_sub_i32 s4, s4, s6
	s_lshr_b32 s6, s4, 3
	s_lshl_b32 s5, s5, 3
	s_and_b32 s4, s4, 7
	s_or_b32 s4, s5, s4
	s_mulk_i32 s6, 0xa0
	s_ashr_i32 s7, s6, 31
	s_ashr_i32 s5, s4, 31
	s_lshl_b64 s[8:9], s[6:7], 11
	s_lshl_b64 s[14:15], s[4:5], 18
	v_readfirstlane_b32 s5, v92
	v_add_u32_e32 v4, 0x1000, v92
	v_lshl_add_u64 v[0:1], v[80:81], 0, s[8:9]
	s_mov_b32 m0, s5
	s_mov_b64 s[34:35], 0x10000
	v_readfirstlane_b32 s5, v4
	v_add_u32_e32 v4, 0x2000, v92
	global_load_lds_dwordx4 v[0:1], off
	v_lshl_add_u64 v[2:3], v[0:1], 0, s[34:35]
	s_mov_b32 m0, s5
	s_mov_b64 s[36:37], 0x20000
	v_readfirstlane_b32 s5, v4
	v_add_u32_e32 v4, 0x3000, v92
	global_load_lds_dwordx4 v[2:3], off
	v_lshl_add_u64 v[2:3], v[0:1], 0, s[36:37]
	s_mov_b32 m0, s5
	s_mov_b64 s[38:39], 0x30000
	v_readfirstlane_b32 s5, v4
	global_load_lds_dwordx4 v[2:3], off
	v_lshl_add_u64 v[2:3], v[0:1], 0, s[38:39]
	s_mov_b32 m0, s5
	s_mov_b64 s[40:41], 0x40000
	global_load_lds_dwordx4 v[2:3], off
	v_add_u32_e32 v2, 0x4000, v92
	v_lshl_add_u64 v[0:1], v[0:1], 0, s[40:41]
	v_readfirstlane_b32 s5, v2
	v_add_u32_e32 v2, 0x5000, v92
	s_mov_b32 m0, s5
	v_readfirstlane_b32 s5, v2
	v_add_u32_e32 v4, 0x6000, v92
	global_load_lds_dwordx4 v[0:1], off
	v_lshl_add_u64 v[0:1], v[82:83], 0, s[14:15]
	s_mov_b32 m0, s5
	v_readfirstlane_b32 s5, v4
	v_add_u32_e32 v4, 0x7000, v92
	global_load_lds_dwordx4 v[0:1], off
	v_lshl_add_u64 v[2:3], v[0:1], 0, s[34:35]
	s_mov_b32 m0, s5
	v_readfirstlane_b32 s5, v4
	global_load_lds_dwordx4 v[2:3], off
	v_lshl_add_u64 v[2:3], v[0:1], 0, s[36:37]
	s_mov_b32 m0, s5
	v_lshl_add_u64 v[0:1], v[0:1], 0, s[38:39]
	global_load_lds_dwordx4 v[2:3], off
	v_add_u32_e32 v2, 0x8000, v92
	v_lshl_add_u64 v[88:89], v[84:85], 0, s[8:9]
	v_readfirstlane_b32 s5, v2
	s_mov_b32 m0, s5
	v_lshl_add_u64 v[90:91], v[86:87], 0, s[14:15]
	global_load_lds_dwordx4 v[0:1], off
	s_nop 0
	v_mov_b32_e32 v0, 0
	s_mov_b32 s5, 0
	s_mov_b64 s[8:9], 0
	v_mov_b32_e32 v1, v0
	v_mov_b32_e32 v2, v0
	v_mov_b32_e32 v3, v0
	v_mov_b32_e32 v4, v0
	v_mov_b32_e32 v5, v0
	v_mov_b32_e32 v6, v0
	v_mov_b32_e32 v7, v0
	v_mov_b32_e32 v8, v0
	v_mov_b32_e32 v9, v0
	v_mov_b32_e32 v10, v0
	v_mov_b32_e32 v11, v0
	v_mov_b32_e32 v12, v0
	v_mov_b32_e32 v13, v0
	v_mov_b32_e32 v14, v0
	v_mov_b32_e32 v15, v0
	v_mov_b32_e32 v16, v0
	v_mov_b32_e32 v17, v0
	v_mov_b32_e32 v18, v0
	v_mov_b32_e32 v19, v0
	v_mov_b32_e32 v20, v0
	v_mov_b32_e32 v21, v0
	v_mov_b32_e32 v22, v0
	v_mov_b32_e32 v23, v0
	v_mov_b32_e32 v24, v0
	v_mov_b32_e32 v25, v0
	v_mov_b32_e32 v26, v0
	v_mov_b32_e32 v27, v0
	v_mov_b32_e32 v28, v0
	v_mov_b32_e32 v29, v0
	v_mov_b32_e32 v30, v0
	v_mov_b32_e32 v31, v0
	v_mov_b32_e32 v32, v0
	v_mov_b32_e32 v33, v0
	v_mov_b32_e32 v34, v0
	v_mov_b32_e32 v35, v0
	v_mov_b32_e32 v36, v0
	v_mov_b32_e32 v37, v0
	v_mov_b32_e32 v38, v0
	v_mov_b32_e32 v39, v0
	v_mov_b32_e32 v40, v0
	v_mov_b32_e32 v41, v0
	v_mov_b32_e32 v42, v0
	v_mov_b32_e32 v43, v0
	v_mov_b32_e32 v44, v0
	v_mov_b32_e32 v45, v0
	v_mov_b32_e32 v46, v0
	v_mov_b32_e32 v47, v0
	v_mov_b32_e32 v48, v0
	v_mov_b32_e32 v49, v0
	v_mov_b32_e32 v50, v0
	v_mov_b32_e32 v51, v0
	v_mov_b32_e32 v52, v0
	v_mov_b32_e32 v53, v0
	v_mov_b32_e32 v54, v0
	v_mov_b32_e32 v55, v0
	v_mov_b32_e32 v56, v0
	v_mov_b32_e32 v57, v0
	v_mov_b32_e32 v58, v0
	v_mov_b32_e32 v59, v0
	v_mov_b32_e32 v60, v0
	v_mov_b32_e32 v61, v0
	v_mov_b32_e32 v62, v0
	v_mov_b32_e32 v63, v0
	v_mov_b32_e32 v64, v0
	v_mov_b32_e32 v65, v0
	v_mov_b32_e32 v66, v0
	v_mov_b32_e32 v67, v0
	v_mov_b32_e32 v68, v0
	v_mov_b32_e32 v69, v0
	v_mov_b32_e32 v70, v0
	v_mov_b32_e32 v71, v0
	v_mov_b32_e32 v72, v0
	v_mov_b32_e32 v73, v0
	v_mov_b32_e32 v74, v0
	v_mov_b32_e32 v75, v0
	v_mov_b32_e32 v76, v0
	v_mov_b32_e32 v77, v0
	v_mov_b32_e32 v78, v0
	v_mov_b32_e32 v79, v0
	s_nop 0
	s_nop 0
	s_mov_b32 s13, 0x9000
	v_add_u32_e32 v190, s13, v92
	v_lshl_add_u64 v[186:187], v[88:89], 0, s[8:9]
	s_mov_b64 s[14:15], 0x1c9b1080
	v_readfirstlane_b32 s13, v190
	v_add_u32_e32 v191, 0x1000, v190
	v_lshl_add_u64 v[188:189], v[186:187], 0, s[14:15]
	s_mov_b32 m0, s13
	s_mov_b64 s[14:15], 0x1c9c1080
	v_readfirstlane_b32 s13, v191
	v_add_u32_e32 v191, 0x2000, v190
	global_load_lds_dwordx4 v[188:189], off
	v_lshl_add_u64 v[188:189], v[186:187], 0, s[14:15]
	s_mov_b32 m0, s13
	s_mov_b64 s[14:15], 0x1c9d1080
	v_readfirstlane_b32 s13, v191
	v_add_u32_e32 v191, 0x3000, v190
	global_load_lds_dwordx4 v[188:189], off
	v_lshl_add_u64 v[188:189], v[186:187], 0, s[14:15]
	s_mov_b32 m0, s13
	s_mov_b64 s[14:15], 0x1c9e1080
	v_readfirstlane_b32 s13, v191
	global_load_lds_dwordx4 v[188:189], off
	v_lshl_add_u64 v[188:189], v[186:187], 0, s[14:15]
	s_mov_b32 m0, s13
	s_mov_b64 s[14:15], 0x1c9f1080
	global_load_lds_dwordx4 v[188:189], off
	v_add_u32_e32 v188, 0x4000, v190
	v_lshl_add_u64 v[186:187], v[186:187], 0, s[14:15]
	v_readfirstlane_b32 s13, v188
	s_mov_b32 m0, s13
	v_add_u32_e32 v191, 0x5000, v190
	global_load_lds_dwordx4 v[186:187], off
	v_lshl_add_u64 v[186:187], v[90:91], 0, s[8:9]
	s_mov_b64 s[14:15], 0x14b31080
	v_readfirstlane_b32 s13, v191
	v_add_u32_e32 v191, 0x6000, v190
	v_lshl_add_u64 v[188:189], v[186:187], 0, s[14:15]
	s_mov_b32 m0, s13
	s_mov_b64 s[14:15], 0x14b41080
	v_readfirstlane_b32 s13, v191
	v_add_u32_e32 v191, 0x7000, v190
	global_load_lds_dwordx4 v[188:189], off
	v_lshl_add_u64 v[188:189], v[186:187], 0, s[14:15]
	s_mov_b32 m0, s13
	s_mov_b64 s[14:15], 0x14b51080
	v_readfirstlane_b32 s13, v191
	global_load_lds_dwordx4 v[188:189], off
	v_lshl_add_u64 v[188:189], v[186:187], 0, s[14:15]
	s_mov_b32 m0, s13
	s_mov_b64 s[14:15], 0x14b61080
	global_load_lds_dwordx4 v[188:189], off
	v_add_u32_e32 v188, 0x8000, v190
	v_lshl_add_u64 v[186:187], v[186:187], 0, s[14:15]
	v_readfirstlane_b32 s13, v188
	s_mov_b32 m0, s13
	s_nop 0
	global_load_lds_dwordx4 v[186:187], off
	s_waitcnt vmcnt(9) lgkmcnt(0)
	s_barrier
.LBB0_582:
	s_add_i32 s7, s5, 1
	s_bitcmp1_b32 s5, 0
	s_cselect_b32 s5, 0x9000, 0
	s_add_i32 s5, s5, 0
	v_add_u32_e32 v118, s5, v93
	v_add_u32_e32 v119, v118, v94
	v_add_u32_e32 v156, v118, v95
	ds_read_b128 v[102:105], v119
	ds_read_b128 v[106:109], v119 offset:2048
	ds_read_b128 v[110:113], v119 offset:4096
	ds_read_b128 v[114:117], v119 offset:6144
	ds_read_b128 v[118:121], v119 offset:8192
	ds_read_b128 v[122:125], v156 offset:20480
	ds_read_b128 v[126:129], v156 offset:22528
	ds_read_b128 v[130:133], v156 offset:24576
	ds_read_b128 v[156:159], v156 offset:26624
	v_add_u32_e32 v206, s5, v96
	v_add_u32_e32 v207, v206, v94
	v_add_u32_e32 v208, v206, v95
	ds_read_b128 v[210:213], v207
	ds_read_b128 v[214:217], v207 offset:2048
	ds_read_b128 v[218:221], v207 offset:4096
	ds_read_b128 v[222:225], v207 offset:6144
	ds_read_b128 v[226:229], v207 offset:8192
	ds_read_b128 v[230:233], v208 offset:20480
	ds_read_b128 v[234:237], v208 offset:22528
	ds_read_b128 v[238:241], v208 offset:24576
	ds_read_b128 v[242:245], v208 offset:26624
	s_setprio 1
	s_waitcnt lgkmcnt(9)
	v_mfma_f32_16x16x32_bf16 v[76:79], v[122:125], v[102:105], v[76:79]
	v_mfma_f32_16x16x32_bf16 v[72:75], v[126:129], v[102:105], v[72:75]
	v_mfma_f32_16x16x32_bf16 v[68:71], v[130:133], v[102:105], v[68:71]
	v_mfma_f32_16x16x32_bf16 v[64:67], v[156:159], v[102:105], v[64:67]
	v_mfma_f32_16x16x32_bf16 v[60:63], v[122:125], v[106:109], v[60:63]
	v_mfma_f32_16x16x32_bf16 v[56:59], v[126:129], v[106:109], v[56:59]
	v_mfma_f32_16x16x32_bf16 v[52:55], v[130:133], v[106:109], v[52:55]
	v_mfma_f32_16x16x32_bf16 v[48:51], v[156:159], v[106:109], v[48:51]
	v_mfma_f32_16x16x32_bf16 v[44:47], v[122:125], v[110:113], v[44:47]
	v_mfma_f32_16x16x32_bf16 v[40:43], v[126:129], v[110:113], v[40:43]
	v_mfma_f32_16x16x32_bf16 v[36:39], v[130:133], v[110:113], v[36:39]
	v_mfma_f32_16x16x32_bf16 v[32:35], v[156:159], v[110:113], v[32:35]
	v_mfma_f32_16x16x32_bf16 v[28:31], v[122:125], v[114:117], v[28:31]
	v_mfma_f32_16x16x32_bf16 v[24:27], v[126:129], v[114:117], v[24:27]
	v_mfma_f32_16x16x32_bf16 v[20:23], v[130:133], v[114:117], v[20:23]
	v_mfma_f32_16x16x32_bf16 v[16:19], v[156:159], v[114:117], v[16:19]
	v_mfma_f32_16x16x32_bf16 v[12:15], v[122:125], v[118:121], v[12:15]
	v_mfma_f32_16x16x32_bf16 v[8:11], v[126:129], v[118:121], v[8:11]
	v_mfma_f32_16x16x32_bf16 v[4:7], v[130:133], v[118:121], v[4:7]
	v_mfma_f32_16x16x32_bf16 v[0:3], v[156:159], v[118:121], v[0:3]
	s_setprio 0
	s_setprio 1
	s_waitcnt lgkmcnt(0)
	s_setprio 0
	s_barrier
	s_add_u32 s8, s8, 0x80
	s_addc_u32 s9, s9, 0
	s_mov_b32 s13, s5
	v_add_u32_e32 v190, s13, v92
	v_lshl_add_u64 v[186:187], v[88:89], 0, s[8:9]
	s_mov_b64 s[14:15], 0x1c9b1080
	v_readfirstlane_b32 s13, v190
	v_add_u32_e32 v191, 0x1000, v190
	v_lshl_add_u64 v[188:189], v[186:187], 0, s[14:15]
	s_mov_b32 m0, s13
	s_mov_b64 s[14:15], 0x1c9c1080
	v_readfirstlane_b32 s13, v191
	v_add_u32_e32 v191, 0x2000, v190
	global_load_lds_dwordx4 v[188:189], off
	v_lshl_add_u64 v[188:189], v[186:187], 0, s[14:15]
	s_mov_b32 m0, s13
	s_mov_b64 s[14:15], 0x1c9d1080
	v_readfirstlane_b32 s13, v191
	v_add_u32_e32 v191, 0x3000, v190
	global_load_lds_dwordx4 v[188:189], off
	v_lshl_add_u64 v[188:189], v[186:187], 0, s[14:15]
	s_mov_b32 m0, s13
	s_mov_b64 s[14:15], 0x1c9e1080
	v_readfirstlane_b32 s13, v191
	global_load_lds_dwordx4 v[188:189], off
	v_lshl_add_u64 v[188:189], v[186:187], 0, s[14:15]
	s_mov_b32 m0, s13
	s_mov_b64 s[14:15], 0x1c9f1080
	global_load_lds_dwordx4 v[188:189], off
	v_add_u32_e32 v188, 0x4000, v190
	v_lshl_add_u64 v[186:187], v[186:187], 0, s[14:15]
	v_readfirstlane_b32 s13, v188
	s_mov_b32 m0, s13
	v_add_u32_e32 v191, 0x5000, v190
	global_load_lds_dwordx4 v[186:187], off
	v_lshl_add_u64 v[186:187], v[90:91], 0, s[8:9]
	s_mov_b64 s[14:15], 0x14b31080
	v_readfirstlane_b32 s13, v191
	v_add_u32_e32 v191, 0x6000, v190
	v_lshl_add_u64 v[188:189], v[186:187], 0, s[14:15]
	s_mov_b32 m0, s13
	s_mov_b64 s[14:15], 0x14b41080
	v_readfirstlane_b32 s13, v191
	v_add_u32_e32 v191, 0x7000, v190
	global_load_lds_dwordx4 v[188:189], off
	v_lshl_add_u64 v[188:189], v[186:187], 0, s[14:15]
	s_mov_b32 m0, s13
	s_mov_b64 s[14:15], 0x14b51080
	v_readfirstlane_b32 s13, v191
	global_load_lds_dwordx4 v[188:189], off
	v_lshl_add_u64 v[188:189], v[186:187], 0, s[14:15]
	s_mov_b32 m0, s13
	s_mov_b64 s[14:15], 0x14b61080
	global_load_lds_dwordx4 v[188:189], off
	v_add_u32_e32 v188, 0x8000, v190
	v_lshl_add_u64 v[186:187], v[186:187], 0, s[14:15]
	v_readfirstlane_b32 s13, v188
	s_mov_b32 m0, s13
	s_nop 0
	global_load_lds_dwordx4 v[186:187], off
	s_setprio 1
	v_mfma_f32_16x16x32_bf16 v[76:79], v[230:233], v[210:213], v[76:79]
	v_mfma_f32_16x16x32_bf16 v[72:75], v[234:237], v[210:213], v[72:75]
	v_mfma_f32_16x16x32_bf16 v[68:71], v[238:241], v[210:213], v[68:71]
	v_mfma_f32_16x16x32_bf16 v[64:67], v[242:245], v[210:213], v[64:67]
	v_mfma_f32_16x16x32_bf16 v[60:63], v[230:233], v[214:217], v[60:63]
	v_mfma_f32_16x16x32_bf16 v[56:59], v[234:237], v[214:217], v[56:59]
	v_mfma_f32_16x16x32_bf16 v[52:55], v[238:241], v[214:217], v[52:55]
	v_mfma_f32_16x16x32_bf16 v[48:51], v[242:245], v[214:217], v[48:51]
	v_mfma_f32_16x16x32_bf16 v[44:47], v[230:233], v[218:221], v[44:47]
	v_mfma_f32_16x16x32_bf16 v[40:43], v[234:237], v[218:221], v[40:43]
	v_mfma_f32_16x16x32_bf16 v[36:39], v[238:241], v[218:221], v[36:39]
	v_mfma_f32_16x16x32_bf16 v[32:35], v[242:245], v[218:221], v[32:35]
	v_mfma_f32_16x16x32_bf16 v[28:31], v[230:233], v[222:225], v[28:31]
	v_mfma_f32_16x16x32_bf16 v[24:27], v[234:237], v[222:225], v[24:27]
	v_mfma_f32_16x16x32_bf16 v[20:23], v[238:241], v[222:225], v[20:23]
	v_mfma_f32_16x16x32_bf16 v[16:19], v[242:245], v[222:225], v[16:19]
	v_mfma_f32_16x16x32_bf16 v[12:15], v[230:233], v[226:229], v[12:15]
	v_mfma_f32_16x16x32_bf16 v[8:11], v[234:237], v[226:229], v[8:11]
	v_mfma_f32_16x16x32_bf16 v[4:7], v[238:241], v[226:229], v[4:7]
	v_mfma_f32_16x16x32_bf16 v[0:3], v[242:245], v[226:229], v[0:3]
	s_setprio 0
	s_cmpk_lg_i32 s8, 0x700
	s_mov_b32 s5, s7
	s_waitcnt vmcnt(9)
	s_barrier
	s_cbranch_scc1 .LBB0_582
	s_add_i32 s7, s5, 1
	s_bitcmp1_b32 s5, 0
	s_cselect_b32 s5, 0x9000, 0
	s_add_i32 s5, s5, 0
	v_add_u32_e32 v118, s5, v93
	v_add_u32_e32 v119, v118, v94
	v_add_u32_e32 v156, v118, v95
	ds_read_b128 v[102:105], v119
	ds_read_b128 v[106:109], v119 offset:2048
	ds_read_b128 v[110:113], v119 offset:4096
	ds_read_b128 v[114:117], v119 offset:6144
	ds_read_b128 v[118:121], v119 offset:8192
	ds_read_b128 v[122:125], v156 offset:20480
	ds_read_b128 v[126:129], v156 offset:22528
	ds_read_b128 v[130:133], v156 offset:24576
	ds_read_b128 v[156:159], v156 offset:26624
	v_add_u32_e32 v206, s5, v96
	v_add_u32_e32 v207, v206, v94
	v_add_u32_e32 v208, v206, v95
	ds_read_b128 v[210:213], v207
	ds_read_b128 v[214:217], v207 offset:2048
	ds_read_b128 v[218:221], v207 offset:4096
	ds_read_b128 v[222:225], v207 offset:6144
	ds_read_b128 v[226:229], v207 offset:8192
	ds_read_b128 v[230:233], v208 offset:20480
	ds_read_b128 v[234:237], v208 offset:22528
	ds_read_b128 v[238:241], v208 offset:24576
	ds_read_b128 v[242:245], v208 offset:26624
	s_setprio 1
	s_waitcnt lgkmcnt(9)
	v_mfma_f32_16x16x32_bf16 v[76:79], v[122:125], v[102:105], v[76:79]
	v_mfma_f32_16x16x32_bf16 v[72:75], v[126:129], v[102:105], v[72:75]
	v_mfma_f32_16x16x32_bf16 v[68:71], v[130:133], v[102:105], v[68:71]
	v_mfma_f32_16x16x32_bf16 v[64:67], v[156:159], v[102:105], v[64:67]
	v_mfma_f32_16x16x32_bf16 v[60:63], v[122:125], v[106:109], v[60:63]
	v_mfma_f32_16x16x32_bf16 v[56:59], v[126:129], v[106:109], v[56:59]
	v_mfma_f32_16x16x32_bf16 v[52:55], v[130:133], v[106:109], v[52:55]
	v_mfma_f32_16x16x32_bf16 v[48:51], v[156:159], v[106:109], v[48:51]
	v_mfma_f32_16x16x32_bf16 v[44:47], v[122:125], v[110:113], v[44:47]
	v_mfma_f32_16x16x32_bf16 v[40:43], v[126:129], v[110:113], v[40:43]
	v_mfma_f32_16x16x32_bf16 v[36:39], v[130:133], v[110:113], v[36:39]
	v_mfma_f32_16x16x32_bf16 v[32:35], v[156:159], v[110:113], v[32:35]
	v_mfma_f32_16x16x32_bf16 v[28:31], v[122:125], v[114:117], v[28:31]
	v_mfma_f32_16x16x32_bf16 v[24:27], v[126:129], v[114:117], v[24:27]
	v_mfma_f32_16x16x32_bf16 v[20:23], v[130:133], v[114:117], v[20:23]
	v_mfma_f32_16x16x32_bf16 v[16:19], v[156:159], v[114:117], v[16:19]
	v_mfma_f32_16x16x32_bf16 v[12:15], v[122:125], v[118:121], v[12:15]
	v_mfma_f32_16x16x32_bf16 v[8:11], v[126:129], v[118:121], v[8:11]
	v_mfma_f32_16x16x32_bf16 v[4:7], v[130:133], v[118:121], v[4:7]
	v_mfma_f32_16x16x32_bf16 v[0:3], v[156:159], v[118:121], v[0:3]
	s_setprio 0
	s_setprio 1
	s_waitcnt lgkmcnt(0)
	v_mfma_f32_16x16x32_bf16 v[76:79], v[230:233], v[210:213], v[76:79]
	v_mfma_f32_16x16x32_bf16 v[72:75], v[234:237], v[210:213], v[72:75]
	v_mfma_f32_16x16x32_bf16 v[68:71], v[238:241], v[210:213], v[68:71]
	v_mfma_f32_16x16x32_bf16 v[64:67], v[242:245], v[210:213], v[64:67]
	v_mfma_f32_16x16x32_bf16 v[60:63], v[230:233], v[214:217], v[60:63]
	v_mfma_f32_16x16x32_bf16 v[56:59], v[234:237], v[214:217], v[56:59]
	v_mfma_f32_16x16x32_bf16 v[52:55], v[238:241], v[214:217], v[52:55]
	v_mfma_f32_16x16x32_bf16 v[48:51], v[242:245], v[214:217], v[48:51]
	v_mfma_f32_16x16x32_bf16 v[44:47], v[230:233], v[218:221], v[44:47]
	v_mfma_f32_16x16x32_bf16 v[40:43], v[234:237], v[218:221], v[40:43]
	v_mfma_f32_16x16x32_bf16 v[36:39], v[238:241], v[218:221], v[36:39]
	v_mfma_f32_16x16x32_bf16 v[32:35], v[242:245], v[218:221], v[32:35]
	v_mfma_f32_16x16x32_bf16 v[28:31], v[230:233], v[222:225], v[28:31]
	v_mfma_f32_16x16x32_bf16 v[24:27], v[234:237], v[222:225], v[24:27]
	v_mfma_f32_16x16x32_bf16 v[20:23], v[238:241], v[222:225], v[20:23]
	v_mfma_f32_16x16x32_bf16 v[16:19], v[242:245], v[222:225], v[16:19]
	v_mfma_f32_16x16x32_bf16 v[12:15], v[230:233], v[226:229], v[12:15]
	v_mfma_f32_16x16x32_bf16 v[8:11], v[234:237], v[226:229], v[8:11]
	v_mfma_f32_16x16x32_bf16 v[4:7], v[238:241], v[226:229], v[4:7]
	v_mfma_f32_16x16x32_bf16 v[0:3], v[242:245], v[226:229], v[0:3]
	s_setprio 0
	s_add_u32 s8, s8, 0x80
	s_addc_u32 s9, s9, 0
	s_mov_b32 s5, s7
	s_waitcnt vmcnt(0)
	s_barrier
	v_add_u32_e32 v110, v100, v95
	v_add_u32_e32 v130, v100, v94
	ds_read_b128 v[88:91], v110 offset:63488
	ds_read_b128 v[102:105], v110 offset:61440
	ds_read_b128 v[106:109], v110 offset:59392
	ds_read_b128 v[110:113], v110 offset:57344
	ds_read_b128 v[114:117], v130 offset:45056
	ds_read_b128 v[118:121], v130 offset:43008
	ds_read_b128 v[122:125], v130 offset:40960
	ds_read_b128 v[126:129], v130 offset:38912
	ds_read_b128 v[130:133], v130 offset:36864
	s_setprio 1
	s_waitcnt lgkmcnt(0)
	v_mfma_f32_16x16x32_bf16 v[76:79], v[110:113], v[130:133], v[76:79]
	v_mfma_f32_16x16x32_bf16 v[72:75], v[106:109], v[130:133], v[72:75]
	v_mfma_f32_16x16x32_bf16 v[68:71], v[102:105], v[130:133], v[68:71]
	v_mfma_f32_16x16x32_bf16 v[64:67], v[88:91], v[130:133], v[64:67]
	v_mfma_f32_16x16x32_bf16 v[60:63], v[110:113], v[126:129], v[60:63]
	v_mfma_f32_16x16x32_bf16 v[56:59], v[106:109], v[126:129], v[56:59]
	v_mfma_f32_16x16x32_bf16 v[52:55], v[102:105], v[126:129], v[52:55]
	v_mfma_f32_16x16x32_bf16 v[48:51], v[88:91], v[126:129], v[48:51]
	v_mfma_f32_16x16x32_bf16 v[44:47], v[110:113], v[122:125], v[44:47]
	v_mfma_f32_16x16x32_bf16 v[40:43], v[106:109], v[122:125], v[40:43]
	v_mfma_f32_16x16x32_bf16 v[36:39], v[102:105], v[122:125], v[36:39]
	v_mfma_f32_16x16x32_bf16 v[32:35], v[88:91], v[122:125], v[32:35]
	v_mfma_f32_16x16x32_bf16 v[28:31], v[110:113], v[118:121], v[28:31]
	v_mfma_f32_16x16x32_bf16 v[24:27], v[106:109], v[118:121], v[24:27]
	v_mfma_f32_16x16x32_bf16 v[20:23], v[102:105], v[118:121], v[20:23]
	v_mfma_f32_16x16x32_bf16 v[16:19], v[88:91], v[118:121], v[16:19]
	v_mfma_f32_16x16x32_bf16 v[12:15], v[110:113], v[114:117], v[12:15]
	v_mfma_f32_16x16x32_bf16 v[8:11], v[106:109], v[114:117], v[8:11]
	v_mfma_f32_16x16x32_bf16 v[4:7], v[102:105], v[114:117], v[4:7]
	v_mfma_f32_16x16x32_bf16 v[0:3], v[88:91], v[114:117], v[0:3]
	s_setprio 0
	v_add_u32_e32 v114, v101, v94
	v_add_u32_e32 v130, v101, v95
	ds_read_b128 v[88:91], v114 offset:36864
	ds_read_b128 v[102:105], v114 offset:38912
	ds_read_b128 v[106:109], v114 offset:40960
	ds_read_b128 v[110:113], v114 offset:43008
	ds_read_b128 v[114:117], v114 offset:45056
	ds_read_b128 v[118:121], v130 offset:57344
	ds_read_b128 v[122:125], v130 offset:59392
	ds_read_b128 v[126:129], v130 offset:61440
	ds_read_b128 v[130:133], v130 offset:63488
	s_setprio 1
	s_waitcnt lgkmcnt(3)
	v_mfma_f32_16x16x32_bf16 v[76:79], v[118:121], v[88:91], v[76:79]
	s_waitcnt lgkmcnt(2)
	v_mfma_f32_16x16x32_bf16 v[72:75], v[122:125], v[88:91], v[72:75]
	s_waitcnt lgkmcnt(1)
	v_mfma_f32_16x16x32_bf16 v[68:71], v[126:129], v[88:91], v[68:71]
	s_waitcnt lgkmcnt(0)
	v_mfma_f32_16x16x32_bf16 v[64:67], v[130:133], v[88:91], v[64:67]
	v_mfma_f32_16x16x32_bf16 v[60:63], v[118:121], v[102:105], v[60:63]
	v_mfma_f32_16x16x32_bf16 v[56:59], v[122:125], v[102:105], v[56:59]
	v_mfma_f32_16x16x32_bf16 v[88:91], v[126:129], v[102:105], v[52:55]
	v_mfma_f32_16x16x32_bf16 v[48:51], v[130:133], v[102:105], v[48:51]
	v_mfma_f32_16x16x32_bf16 v[44:47], v[118:121], v[106:109], v[44:47]
	v_mfma_f32_16x16x32_bf16 v[40:43], v[122:125], v[106:109], v[40:43]
	v_mfma_f32_16x16x32_bf16 v[36:39], v[126:129], v[106:109], v[36:39]
	v_mfma_f32_16x16x32_bf16 v[32:35], v[130:133], v[106:109], v[32:35]
	v_mfma_f32_16x16x32_bf16 v[28:31], v[118:121], v[110:113], v[28:31]
	v_mfma_f32_16x16x32_bf16 v[24:27], v[122:125], v[110:113], v[24:27]
	v_mfma_f32_16x16x32_bf16 v[20:23], v[126:129], v[110:113], v[20:23]
	v_mfma_f32_16x16x32_bf16 v[16:19], v[130:133], v[110:113], v[16:19]
	v_mfma_f32_16x16x32_bf16 v[12:15], v[118:121], v[114:117], v[12:15]
	v_mfma_f32_16x16x32_bf16 v[8:11], v[122:125], v[114:117], v[8:11]
	v_mfma_f32_16x16x32_bf16 v[4:7], v[126:129], v[114:117], v[4:7]
	v_mfma_f32_16x16x32_bf16 v[0:3], v[130:133], v[114:117], v[0:3]
	s_setprio 0
	v_mov_b32_e32 v52, v97
	s_waitcnt vmcnt(0)
	s_barrier
	s_mov_b32 s8, 0
	v_add_u32_e32 v52, v52, v176
	v_lshrrev_b32_e32 v55, 2, v52
	v_ashrrev_i32_e32 v53, 7, v52
	v_and_b32_e32 v54, 64, v52
	v_and_b32_e32 v55, 12, v55
	v_and_or_b32 v52, v52, 15, s6
	s_movk_i32 s5, 0x50
	s_lshl_b32 s4, s4, 7
	v_mad_u64_u32 v[52:53], s[6:7], v53, s5, v[52:53]
	v_or3_b32 v54, v54, v55, s4
	v_ashrrev_i32_e32 v53, 31, v52
	v_lshlrev_b64 v[52:53], 12, v[52:53]
	v_lshl_add_u64 v[52:53], s[0:1], 0, v[52:53]
	v_ashrrev_i32_e32 v55, 31, v54
	v_lshl_add_u64 v[52:53], v[54:55], 2, v[52:53]
	global_load_dwordx4 v[102:105], v[52:53], off
	s_waitcnt vmcnt(0)
	v_pk_add_f32 v[76:77], v[76:77], v[102:103]
	v_pk_add_f32 v[78:79], v[78:79], v[104:105]
	s_nop 0
	global_store_dwordx4 v[52:53], v[76:79], off
	global_load_dwordx4 v[76:79], v[52:53], off offset:64
	s_waitcnt vmcnt(0)
	v_pk_add_f32 v[72:73], v[72:73], v[76:77]
	v_pk_add_f32 v[74:75], v[74:75], v[78:79]
	s_nop 0
	global_store_dwordx4 v[52:53], v[72:75], off offset:64
	global_load_dwordx4 v[72:75], v[52:53], off offset:128
	s_waitcnt vmcnt(0)
	v_pk_add_f32 v[68:69], v[68:69], v[72:73]
	v_pk_add_f32 v[70:71], v[70:71], v[74:75]
	s_nop 0
	global_store_dwordx4 v[52:53], v[68:71], off offset:128
	global_load_dwordx4 v[68:71], v[52:53], off offset:192
	s_waitcnt vmcnt(0)
	v_pk_add_f32 v[64:65], v[64:65], v[68:69]
	v_pk_add_f32 v[66:67], v[66:67], v[70:71]
	s_nop 0
	global_store_dwordx4 v[52:53], v[64:67], off offset:192
	s_mov_b32 s4, 0x10000
	v_add_co_u32_e32 v54, vcc, s4, v52
	v_lshl_add_u64 v[68:69], v[52:53], 0, s[34:35]
	s_nop 0
	v_addc_co_u32_e32 v55, vcc, 0, v53, vcc
	global_load_dwordx4 v[64:67], v[54:55], off
	s_waitcnt vmcnt(0)
	v_pk_add_f32 v[60:61], v[60:61], v[64:65]
	v_pk_add_f32 v[62:63], v[62:63], v[66:67]
	s_nop 0
	global_store_dwordx4 v[54:55], v[60:63], off
	global_load_dwordx4 v[60:63], v[68:69], off offset:64
	s_waitcnt vmcnt(0)
	v_pk_add_f32 v[54:55], v[56:57], v[60:61]
	v_pk_add_f32 v[56:57], v[58:59], v[62:63]
	s_nop 0
	global_store_dwordx4 v[68:69], v[54:57], off offset:64
	global_load_dwordx4 v[54:57], v[68:69], off offset:128
	s_waitcnt vmcnt(0)
	v_pk_add_f32 v[54:55], v[88:89], v[54:55]
	v_pk_add_f32 v[56:57], v[90:91], v[56:57]
	s_nop 0
	global_store_dwordx4 v[68:69], v[54:57], off offset:128
	global_load_dwordx4 v[54:57], v[68:69], off offset:192
	s_waitcnt vmcnt(0)
	v_pk_add_f32 v[48:49], v[48:49], v[54:55]
	v_pk_add_f32 v[50:51], v[50:51], v[56:57]
	s_nop 0
	global_store_dwordx4 v[68:69], v[48:51], off offset:192
	s_mov_b64 s[4:5], 0x20000
	v_lshl_add_u64 v[54:55], v[52:53], 0, s[4:5]
	s_mov_b32 s4, 0x20000
	v_add_co_u32_e32 v56, vcc, s4, v52
	s_nop 1
	v_addc_co_u32_e32 v57, vcc, 0, v53, vcc
	global_load_dwordx4 v[48:51], v[56:57], off
	s_waitcnt vmcnt(0)
	v_pk_add_f32 v[44:45], v[44:45], v[48:49]
	v_pk_add_f32 v[46:47], v[46:47], v[50:51]
	s_nop 0
	global_store_dwordx4 v[56:57], v[44:47], off
	global_load_dwordx4 v[44:47], v[54:55], off offset:64
	s_waitcnt vmcnt(0)
	v_pk_add_f32 v[40:41], v[40:41], v[44:45]
	v_pk_add_f32 v[42:43], v[42:43], v[46:47]
	s_nop 0
	global_store_dwordx4 v[54:55], v[40:43], off offset:64
	global_load_dwordx4 v[40:43], v[54:55], off offset:128
	s_waitcnt vmcnt(0)
	v_pk_add_f32 v[36:37], v[36:37], v[40:41]
	v_pk_add_f32 v[38:39], v[38:39], v[42:43]
	s_nop 0
	global_store_dwordx4 v[54:55], v[36:39], off offset:128
	global_load_dwordx4 v[36:39], v[54:55], off offset:192
	s_waitcnt vmcnt(0)
	v_pk_add_f32 v[32:33], v[32:33], v[36:37]
	v_pk_add_f32 v[34:35], v[34:35], v[38:39]
	s_nop 0
	global_store_dwordx4 v[54:55], v[32:35], off offset:192
	s_mov_b64 s[4:5], 0x30000
	v_lshl_add_u64 v[36:37], v[52:53], 0, s[4:5]
	s_mov_b32 s4, 0x30000
	v_add_co_u32_e32 v38, vcc, s4, v52
	s_nop 1
	v_addc_co_u32_e32 v39, vcc, 0, v53, vcc
	global_load_dwordx4 v[32:35], v[38:39], off
	s_waitcnt vmcnt(0)
	v_pk_add_f32 v[28:29], v[28:29], v[32:33]
	v_pk_add_f32 v[30:31], v[30:31], v[34:35]
	s_nop 0
	global_store_dwordx4 v[38:39], v[28:31], off
	global_load_dwordx4 v[28:31], v[36:37], off offset:64
	s_waitcnt vmcnt(0)
	v_pk_add_f32 v[24:25], v[24:25], v[28:29]
	v_pk_add_f32 v[26:27], v[26:27], v[30:31]
	s_nop 0
	global_store_dwordx4 v[36:37], v[24:27], off offset:64
	global_load_dwordx4 v[24:27], v[36:37], off offset:128
	s_waitcnt vmcnt(0)
	v_pk_add_f32 v[20:21], v[20:21], v[24:25]
	v_pk_add_f32 v[22:23], v[22:23], v[26:27]
	s_nop 0
	global_store_dwordx4 v[36:37], v[20:23], off offset:128
	global_load_dwordx4 v[20:23], v[36:37], off offset:192
	s_waitcnt vmcnt(0)
	v_pk_add_f32 v[16:17], v[16:17], v[20:21]
	v_pk_add_f32 v[18:19], v[18:19], v[22:23]
	s_nop 0
	global_store_dwordx4 v[36:37], v[16:19], off offset:192
	s_mov_b64 s[4:5], 0x40000
	v_lshl_add_u64 v[20:21], v[52:53], 0, s[4:5]
	s_mov_b32 s4, 0x40000
	v_add_co_u32_e32 v22, vcc, s4, v52
	s_nop 1
	v_addc_co_u32_e32 v23, vcc, 0, v53, vcc
	global_load_dwordx4 v[16:19], v[22:23], off
	s_waitcnt vmcnt(0)
	v_pk_add_f32 v[12:13], v[12:13], v[16:17]
	v_pk_add_f32 v[14:15], v[14:15], v[18:19]
	s_nop 0
	global_store_dwordx4 v[22:23], v[12:15], off
	global_load_dwordx4 v[12:15], v[20:21], off offset:64
	s_waitcnt vmcnt(0)
	v_pk_add_f32 v[8:9], v[8:9], v[12:13]
	v_pk_add_f32 v[10:11], v[10:11], v[14:15]
	s_nop 0
	global_store_dwordx4 v[20:21], v[8:11], off offset:64
	global_load_dwordx4 v[8:11], v[20:21], off offset:128
	s_waitcnt vmcnt(0)
	v_pk_add_f32 v[4:5], v[4:5], v[8:9]
	v_pk_add_f32 v[6:7], v[6:7], v[10:11]
	s_nop 0
	global_store_dwordx4 v[20:21], v[4:7], off offset:128
	global_load_dwordx4 v[4:7], v[20:21], off offset:192
	s_waitcnt vmcnt(0)
	v_pk_add_f32 v[0:1], v[0:1], v[4:5]
	v_pk_add_f32 v[2:3], v[2:3], v[6:7]
	s_nop 0
	global_store_dwordx4 v[20:21], v[0:3], off offset:192
